# GEMM k-loops: the k-step's global loads are issued at top wave priority (2), then back to the existing 0/1 pattern
# speedup vs baseline: 1.0338x; 1.0107x over previous
; #define G_LOAD(kt_) do { \
;     if constexpr (AF32) { _Pragma("unroll") for (int i = 0; i < 4; ++i) ld16_sc1(ra[i], Af + (size_t)i * 32 * lda + (kt_) * 32); } \
;     else { _Pragma("unroll") for (int i = 0; i < 2; ++i) ld16_sc1(rab[i], Ab + (size_t)i * 64 * lda + (kt_) * 32); } \
;     _Pragma("unroll") for (int i = 0; i < 4; ++i) ld16_sc1(rb[i], Bp + (size_t)(kt_) * bstep + i * 2048); } while (0)
; template <bool AF32, class Epi>
; __device__ __forceinline__ void gemm_tile(unsigned char* smem, const void* Ap, int lda, const bf16_t* WT, int N, int K, const Epi& epi, int m0, int n0,
;                                           GPre& pr, bool preloaded, const void* nAp, int nn0, bool has_next) {
;     ...
;   if (!preloaded) G_LOAD(0);
;   G_STORE(0);
;   if (nk > 1) G_LOAD(1);
;   __syncthreads();
;   for (int kt = 0; kt < nk; ++kt) {
;     const int cur = kt & 1;
;     if (kt + 1 < nk) G_STORE(cur ^ 1);
;     if (kt + 2 < nk) G_LOAD(kt + 2);
;     const bf16_t* a_s = sbase + cur * G_STAGE + (wr * 64 + l15) * GLD + quad * 8;
;     const bf16_t* b_s = sbase + cur * G_STAGE + 128 * GLD + (wc * 128 + l15) * GLD + quad * 8;
;     __builtin_amdgcn_s_setprio(1);
;     bf16x8 af[4];
; #pragma unroll
;     for (int m = 0; m < 4; ++m) af[m] = *(const bf16x8*)(a_s + m * 16 * GLD);
; #pragma unroll
;     for (int nh = 0; nh < 4; ++nh) {
;       bf16x8 bfr[2];
; #pragma unroll
;       for (int n2 = 0; n2 < 2; ++n2) bfr[n2] = *(const bf16x8*)(b_s + (nh * 2 + n2) * 16 * GLD);
; #pragma unroll
;       for (int m = 0; m < 4; ++m)
; #pragma unroll
;         for (int n2 = 0; n2 < 2; ++n2) acc[m][nh * 2 + n2] = __builtin_amdgcn_mfma_f32_16x16x32_bf16(bfr[n2], af[m], acc[m][nh * 2 + n2], 0, 0, 0);
;     }
;     __builtin_amdgcn_s_setprio(0);
;     __syncthreads();
;   }
.LBB0_126:
	s_and_b32 s3, s12, 1
	s_waitcnt vmcnt(0)
	s_xor_b32 s4, s3, 1
	s_mulk_i32 s4, 0x7800
	v_cvt_pk_bf16_f32 v198, v16, v17
	v_mov_b32_e32 v201, v16
	v_mov_b32_e32 v16, v9
	v_lshl_add_u32 v185, v181, 1, s4
	v_cvt_pk_bf16_f32 v199, v18, v19
	v_mov_b32_e32 v200, v8
	v_mov_b32_e32 v202, v10
	v_mov_b32_e32 v203, v18
	v_mov_b32_e32 v18, v11
	v_cvt_pk_bf16_f32 v8, v8, v9
	v_cvt_pk_bf16_f32 v9, v10, v11
	v_cvt_pk_bf16_f32 v10, v4, v5
	v_cvt_pk_bf16_f32 v11, v6, v7
	v_mov_b32_e32 v204, v0
	v_mov_b32_e32 v205, v4
	v_mov_b32_e32 v4, v1
	v_mov_b32_e32 v206, v2
	v_mov_b32_e32 v207, v6
	v_mov_b32_e32 v6, v3
	v_cvt_pk_bf16_f32 v0, v0, v1
	v_cvt_pk_bf16_f32 v1, v2, v3
	v_pk_mul_f32 v[2:3], v[16:17], v[16:17]
	v_lshl_add_u32 v208, v170, 1, s4
	ds_write2st64_b64 v185, v[198:199], v[8:9] offset1:5
	ds_write2st64_b64 v185, v[10:11], v[0:1] offset0:10 offset1:15
	ds_write_b128 v208, v[32:35] offset:10240
	ds_write_b128 v208, v[36:39] offset:15360
	ds_write_b128 v208, v[40:43] offset:20480
	ds_write_b128 v208, v[48:51] offset:25600
	v_pk_fma_f32 v[0:1], v[200:201], v[200:201], v[2:3]
	v_pk_mul_f32 v[4:5], v[4:5], v[4:5]
	v_pk_fma_f32 v[0:1], v[202:203], v[202:203], v[0:1]
	v_pk_fma_f32 v[2:3], v[204:205], v[204:205], v[4:5]
	v_pk_fma_f32 v[198:199], v[18:19], v[18:19], v[0:1]
	s_setprio 2
	global_load_dwordx4 v[16:19], v[174:175], off sc1
	v_lshl_add_u64 v[186:187], v[174:175], 0, s[26:27]
	v_pk_fma_f32 v[2:3], v[206:207], v[206:207], v[2:3]
	global_load_dwordx4 v[8:11], v[186:187], off sc1
	v_lshl_add_u64 v[188:189], v[174:175], 0, s[28:29]
	v_pk_fma_f32 v[200:201], v[6:7], v[6:7], v[2:3]
	global_load_dwordx4 v[4:7], v[188:189], off sc1
	v_lshl_add_u64 v[190:191], v[174:175], 0, s[22:23]
	global_load_dwordx4 v[0:3], v[190:191], off sc1
	global_load_dwordx4 v[32:35], v[172:173], off sc1
	v_lshl_add_u64 v[192:193], v[172:173], 0, s[30:31]
	global_load_dwordx4 v[36:39], v[192:193], off sc1
	v_lshl_add_u64 v[194:195], v[172:173], 0, s[34:35]
	global_load_dwordx4 v[40:43], v[194:195], off sc1
	v_lshl_add_u64 v[196:197], v[172:173], 0, s[36:37]
	global_load_dwordx4 v[48:51], v[196:197], off sc1
	s_setprio 0
	s_add_i32 s12, s12, 1
	s_mulk_i32 s3, 0x7800
	v_pk_add_f32 v[168:169], v[168:169], v[198:199]
	v_pk_add_f32 v[164:165], v[164:165], v[200:201]
	v_add3_u32 v185, s3, v166, v184
	s_setprio 1
	v_add3_u32 v212, s3, v183, v184
	ds_read_b128 v[186:189], v212 offset:10240
	ds_read_b128 v[190:193], v212 offset:11520
	ds_read_b128 v[194:197], v185
	ds_read_b128 v[198:201], v185 offset:1280
	ds_read_b128 v[202:205], v185 offset:2560
	ds_read_b128 v[206:209], v185 offset:3840
	s_waitcnt lgkmcnt(3)
	v_mfma_f32_16x16x32_bf16 v[156:159], v[186:189], v[194:197], v[156:159]
	v_mfma_f32_16x16x32_bf16 v[152:155], v[190:193], v[194:197], v[152:155]
	s_waitcnt lgkmcnt(2)
	v_mfma_f32_16x16x32_bf16 v[140:143], v[186:189], v[198:201], v[140:143]
	v_mfma_f32_16x16x32_bf16 v[136:139], v[190:193], v[198:201], v[136:139]
	s_waitcnt lgkmcnt(1)
	v_mfma_f32_16x16x32_bf16 v[108:111], v[186:189], v[202:205], v[108:111]
	v_mfma_f32_16x16x32_bf16 v[100:103], v[190:193], v[202:205], v[100:103]
	s_waitcnt lgkmcnt(0)
	v_mfma_f32_16x16x32_bf16 v[76:79], v[186:189], v[206:209], v[76:79]
	ds_read_b128 v[186:189], v212 offset:12800
	v_mfma_f32_16x16x32_bf16 v[68:71], v[190:193], v[206:209], v[68:71]
	ds_read_b128 v[190:193], v212 offset:14080
	s_waitcnt lgkmcnt(1)
	v_mfma_f32_16x16x32_bf16 v[148:151], v[186:189], v[194:197], v[148:151]
	s_waitcnt lgkmcnt(0)
	v_mfma_f32_16x16x32_bf16 v[144:147], v[190:193], v[194:197], v[144:147]
	v_mfma_f32_16x16x32_bf16 v[124:127], v[186:189], v[198:201], v[124:127]
	v_mfma_f32_16x16x32_bf16 v[116:119], v[190:193], v[198:201], v[116:119]
	v_mfma_f32_16x16x32_bf16 v[92:95], v[186:189], v[202:205], v[92:95]
	v_mfma_f32_16x16x32_bf16 v[84:87], v[190:193], v[202:205], v[84:87]
	v_mfma_f32_16x16x32_bf16 v[60:63], v[186:189], v[206:209], v[60:63]
	ds_read_b128 v[186:189], v212 offset:15360
	v_mfma_f32_16x16x32_bf16 v[52:55], v[190:193], v[206:209], v[52:55]
	ds_read_b128 v[190:193], v212 offset:16640
	s_waitcnt lgkmcnt(1)
	v_mfma_f32_16x16x32_bf16 v[132:135], v[186:189], v[194:197], v[132:135]
	s_waitcnt lgkmcnt(0)
	v_mfma_f32_16x16x32_bf16 v[128:131], v[190:193], v[194:197], v[128:131]
	v_mfma_f32_16x16x32_bf16 v[104:107], v[186:189], v[198:201], v[104:107]
	v_mfma_f32_16x16x32_bf16 v[96:99], v[190:193], v[198:201], v[96:99]
	v_mfma_f32_16x16x32_bf16 v[72:75], v[186:189], v[202:205], v[72:75]
	v_mfma_f32_16x16x32_bf16 v[64:67], v[190:193], v[202:205], v[64:67]
	v_mfma_f32_16x16x32_bf16 v[28:31], v[186:189], v[206:209], v[28:31]
	ds_read_b128 v[186:189], v212 offset:17920
	v_mfma_f32_16x16x32_bf16 v[24:27], v[190:193], v[206:209], v[24:27]
	ds_read_b128 v[190:193], v212 offset:19200
	s_waitcnt lgkmcnt(1)
	v_mfma_f32_16x16x32_bf16 v[120:123], v[186:189], v[194:197], v[120:123]
	s_waitcnt lgkmcnt(0)
	v_mfma_f32_16x16x32_bf16 v[112:115], v[190:193], v[194:197], v[112:115]
	v_mfma_f32_16x16x32_bf16 v[88:91], v[186:189], v[198:201], v[88:91]
	v_mfma_f32_16x16x32_bf16 v[80:83], v[190:193], v[198:201], v[80:83]
	v_mfma_f32_16x16x32_bf16 v[56:59], v[186:189], v[202:205], v[56:59]
	v_mfma_f32_16x16x32_bf16 v[44:47], v[190:193], v[202:205], v[44:47]
	v_mfma_f32_16x16x32_bf16 v[20:23], v[186:189], v[206:209], v[20:23]
	v_mfma_f32_16x16x32_bf16 v[12:15], v[190:193], v[206:209], v[12:15]
	s_setprio 0
	v_lshl_add_u64 v[172:173], v[172:173], 0, s[26:27]
	s_cmp_eq_u32 s12, 30
	v_lshl_add_u64 v[174:175], v[174:175], 0, s[38:39]
	s_barrier
	s_cbranch_scc0 .LBB0_126
; #define G_LOAD(kt_) do { \
;     if constexpr (AF32) { _Pragma("unroll") for (int i = 0; i < 4; ++i) ld16_sc1(ra[i], Af + (size_t)i * 32 * lda + (kt_) * 32); } \
;     else { _Pragma("unroll") for (int i = 0; i < 2; ++i) ld16_sc1(rab[i], Ab + (size_t)i * 64 * lda + (kt_) * 32); } \
;     _Pragma("unroll") for (int i = 0; i < 4; ++i) ld16_sc1(rb[i], Bp + (size_t)(kt_) * bstep + i * 2048); } while (0)
; template <bool AF32, class Epi>
; __device__ __forceinline__ void gemm_tile(unsigned char* smem, const void* Ap, int lda, const bf16_t* WT, int N, int K, const Epi& epi, int m0, int n0,
;                                           GPre& pr, bool preloaded, const void* nAp, int nn0, bool has_next) {
;     ...
;     if (kt + 1 < nk) G_STORE(cur ^ 1);
;     if (kt + 2 < nk) G_LOAD(kt + 2);
;     const bf16_t* a_s = sbase + cur * G_STAGE + (wr * 64 + l15) * GLD + quad * 8;
;     const bf16_t* b_s = sbase + cur * G_STAGE + 128 * GLD + (wc * 128 + l15) * GLD + quad * 8;
;     __builtin_amdgcn_s_setprio(1);
;     bf16x8 af[4];
; #pragma unroll
;     for (int m = 0; m < 4; ++m) af[m] = *(const bf16x8*)(a_s + m * 16 * GLD);
; #pragma unroll
;     for (int nh = 0; nh < 4; ++nh) {
;       bf16x8 bfr[2];
; #pragma unroll
;       for (int n2 = 0; n2 < 2; ++n2) bfr[n2] = *(const bf16x8*)(b_s + (nh * 2 + n2) * 16 * GLD);
; #pragma unroll
;       for (int m = 0; m < 4; ++m)
; #pragma unroll
;         for (int n2 = 0; n2 < 2; ++n2) acc[m][nh * 2 + n2] = __builtin_amdgcn_mfma_f32_16x16x32_bf16(bfr[n2], af[m], acc[m][nh * 2 + n2], 0, 0, 0);
	s_waitcnt vmcnt(0)
	s_nop 0
	v_cvt_pk_bf16_f32 v172, v16, v17
	v_mul_f32_e32 v17, v17, v17
	v_fmac_f32_e32 v17, v16, v16
	v_cvt_pk_bf16_f32 v173, v18, v19
	v_cvt_pk_bf16_f32 v174, v8, v9
	v_cvt_pk_bf16_f32 v175, v10, v11
	v_fmac_f32_e32 v17, v18, v18
	ds_write2st64_b64 v171, v[172:173], v[174:175] offset0:60 offset1:65
	v_cvt_pk_bf16_f32 v172, v4, v5
	v_cvt_pk_bf16_f32 v173, v6, v7
	v_cvt_pk_bf16_f32 v174, v0, v1
	v_cvt_pk_bf16_f32 v175, v2, v3
	v_fmac_f32_e32 v17, v19, v19
	ds_write2st64_b64 v171, v[172:173], v[174:175] offset0:70 offset1:75
	ds_write_b128 v182, v[32:35] offset:40960
	ds_write_b128 v182, v[36:39] offset:46080
	ds_write_b128 v182, v[40:43] offset:51200
	ds_write_b128 v182, v[48:51] offset:56320
	v_add_f32_e32 v169, v169, v17
	v_add_u32_e32 v174, v166, v184
	s_setprio 1
	v_add_u32_e32 v175, v183, v184
	ds_read_b128 v[16:19], v175 offset:10240
	ds_read_b128 v[32:35], v175 offset:11520
	ds_read_b128 v[36:39], v174
	ds_read_b128 v[40:43], v174 offset:1280
	s_waitcnt lgkmcnt(1)
	v_mfma_f32_16x16x32_bf16 v[48:51], v[16:19], v[36:39], v[156:159]
	s_waitcnt lgkmcnt(0)
	v_mfma_f32_16x16x32_bf16 v[156:159], v[32:35], v[40:43], v[136:139]
	s_nop 2
	ds_read_b128 v[136:139], v174 offset:2560
	ds_read_b128 v[170:173], v174 offset:3840
	v_mfma_f32_16x16x32_bf16 v[152:155], v[32:35], v[36:39], v[152:155]
	v_mfma_f32_16x16x32_bf16 v[140:143], v[16:19], v[40:43], v[140:143]
	s_waitcnt lgkmcnt(1)
	v_mfma_f32_16x16x32_bf16 v[108:111], v[16:19], v[136:139], v[108:111]
	v_mfma_f32_16x16x32_bf16 v[100:103], v[32:35], v[136:139], v[100:103]
	s_waitcnt lgkmcnt(0)
	v_mfma_f32_16x16x32_bf16 v[16:19], v[16:19], v[170:173], v[76:79]
	s_nop 2
	ds_read_b128 v[76:79], v175 offset:12800
	v_mfma_f32_16x16x32_bf16 v[32:35], v[32:35], v[170:173], v[68:71]
	s_nop 2
	ds_read_b128 v[68:71], v175 offset:14080
	s_waitcnt lgkmcnt(1)
	v_mfma_f32_16x16x32_bf16 v[148:151], v[76:79], v[36:39], v[148:151]
	s_waitcnt lgkmcnt(0)
	v_mfma_f32_16x16x32_bf16 v[144:147], v[68:71], v[36:39], v[144:147]
	v_mfma_f32_16x16x32_bf16 v[124:127], v[76:79], v[40:43], v[124:127]
	v_mfma_f32_16x16x32_bf16 v[116:119], v[68:71], v[40:43], v[116:119]
	v_mfma_f32_16x16x32_bf16 v[92:95], v[76:79], v[136:139], v[92:95]
	v_mfma_f32_16x16x32_bf16 v[84:87], v[68:71], v[136:139], v[84:87]
	v_mfma_f32_16x16x32_bf16 v[60:63], v[76:79], v[170:173], v[60:63]
	ds_read_b128 v[76:79], v175 offset:15360
	v_mfma_f32_16x16x32_bf16 v[52:55], v[68:71], v[170:173], v[52:55]
	ds_read_b128 v[68:71], v175 offset:16640
	s_waitcnt lgkmcnt(1)
	v_mfma_f32_16x16x32_bf16 v[182:185], v[76:79], v[36:39], v[132:135]
	v_mfma_f32_16x16x32_bf16 v[190:193], v[76:79], v[40:43], v[104:107]
	v_mfma_f32_16x16x32_bf16 v[198:201], v[76:79], v[136:139], v[72:75]
	v_mfma_f32_16x16x32_bf16 v[76:79], v[76:79], v[170:173], v[28:31]
	s_nop 2
	ds_read_b128 v[28:31], v175 offset:17920
	s_waitcnt lgkmcnt(1)
	v_mfma_f32_16x16x32_bf16 v[206:209], v[68:71], v[170:173], v[24:27]
	s_nop 2
	ds_read_b128 v[24:27], v175 offset:19200
	s_waitcnt lgkmcnt(0)
	v_mfma_f32_16x16x32_bf16 v[44:47], v[24:27], v[136:139], v[44:47]
	v_mfma_f32_16x16x32_bf16 v[12:15], v[24:27], v[170:173], v[12:15]
	v_mfma_f32_16x16x32_bf16 v[186:189], v[68:71], v[36:39], v[128:131]
	v_mfma_f32_16x16x32_bf16 v[194:197], v[68:71], v[40:43], v[96:99]
	v_mfma_f32_16x16x32_bf16 v[202:205], v[68:71], v[136:139], v[64:67]
	v_mfma_f32_16x16x32_bf16 v[212:215], v[28:31], v[36:39], v[120:123]
	v_mfma_f32_16x16x32_bf16 v[216:219], v[24:27], v[36:39], v[112:115]
	v_mfma_f32_16x16x32_bf16 v[220:223], v[28:31], v[40:43], v[88:91]
	v_mfma_f32_16x16x32_bf16 v[224:227], v[24:27], v[40:43], v[80:83]
	v_mfma_f32_16x16x32_bf16 v[228:231], v[28:31], v[136:139], v[56:59]
	v_mfma_f32_16x16x32_bf16 v[232:235], v[28:31], v[170:173], v[20:23]
	s_setprio 0
	s_barrier
; #define G_LOAD(kt_) do { \
;     if constexpr (AF32) { _Pragma("unroll") for (int i = 0; i < 4; ++i) ld16_sc1(ra[i], Af + (size_t)i * 32 * lda + (kt_) * 32); } \
;     else { _Pragma("unroll") for (int i = 0; i < 2; ++i) ld16_sc1(rab[i], Ab + (size_t)i * 64 * lda + (kt_) * 32); } \
;     _Pragma("unroll") for (int i = 0; i < 4; ++i) ld16_sc1(rb[i], Bp + (size_t)(kt_) * bstep + i * 2048); } while (0)
; template <bool AF32, class Epi>
; __device__ __forceinline__ void gemm_tile(unsigned char* smem, const void* Ap, int lda, const bf16_t* WT, int N, int K, const Epi& epi, int m0, int n0,
;                                           GPre& pr, bool preloaded, const void* nAp, int nn0, bool has_next) {
;     ...
;     for (int m = 0; m < 4; ++m) af[m] = *(const bf16x8*)(a_s + m * 16 * GLD);
; #pragma unroll
;     for (int nh = 0; nh < 4; ++nh) {
;       bf16x8 bfr[2];
; #pragma unroll
;       for (int n2 = 0; n2 < 2; ++n2) bfr[n2] = *(const bf16x8*)(b_s + (nh * 2 + n2) * 16 * GLD);
; #pragma unroll
;       for (int m = 0; m < 4; ++m)
; #pragma unroll
;         for (int n2 = 0; n2 < 2; ++n2) acc[m][nh * 2 + n2] = __builtin_amdgcn_mfma_f32_16x16x32_bf16(bfr[n2], af[m], acc[m][nh * 2 + n2], 0, 0, 0);
;     }
;     __builtin_amdgcn_s_setprio(0);
;     __syncthreads();
;   }
;   if (has_next) {
;     const float* Af = (const float*)nAp + (size_t)(tid >> 3) * lda + (tid & 7) * 4;
;     const bf16_t* Ab = (const bf16_t*)nAp + (size_t)(tid >> 2) * lda + (tid & 3) * 8;
;     const bf16_t* Bp = WT + (size_t)nn0 * 32 + tid * 8;
;     G_LOAD(0);
;   }
;     ...
;   if constexpr (AF32) {
;     const float invK = 1.0f / (float)K;
; #pragma unroll
;     for (int i = 0; i < 4; ++i) {
;       float s = ss[i];
;       s += __shfl_xor(s, 1); s += __shfl_xor(s, 2); s += __shfl_xor(s, 4);
;       if ((tid & 7) == 0) sR[(tid >> 3) + 32 * i] = rsqrtf(s * invK + EPS);
;     }
;     __syncthreads();
	s_setprio 1
	ds_read_b128 v[20:23], v175 offset:40960
	ds_read_b128 v[24:27], v175 offset:42240
	ds_read_b128 v[170:173], v174 offset:30720
	ds_read_b128 v[236:239], v174 offset:32000
	s_waitcnt lgkmcnt(1)
	v_mfma_f32_16x16x32_bf16 v[128:131], v[24:27], v[170:173], v[152:155]
	s_waitcnt lgkmcnt(0)
	v_mfma_f32_16x16x32_bf16 v[104:107], v[20:23], v[236:239], v[140:143]
	s_nop 2
	ds_read_b128 v[140:143], v174 offset:33280
	ds_read_b128 v[152:155], v174 offset:34560
	s_waitcnt lgkmcnt(0)
	v_mfma_f32_16x16x32_bf16 v[40:43], v[20:23], v[152:155], v[16:19]
	s_nop 2
	ds_read_b128 v[16:19], v175 offset:43520
	v_mfma_f32_16x16x32_bf16 v[136:139], v[20:23], v[170:173], v[48:51]
	v_mfma_f32_16x16x32_bf16 v[72:75], v[20:23], v[140:143], v[108:111]
	ds_read_b128 v[20:23], v175 offset:44800
	v_mfma_f32_16x16x32_bf16 v[64:67], v[24:27], v[140:143], v[100:103]
	v_mfma_f32_16x16x32_bf16 v[36:39], v[24:27], v[152:155], v[32:35]
	s_waitcnt lgkmcnt(1)
	v_mfma_f32_16x16x32_bf16 v[132:135], v[16:19], v[170:173], v[148:151]
	v_mfma_f32_16x16x32_bf16 v[100:103], v[16:19], v[236:239], v[124:127]
	v_mfma_f32_16x16x32_bf16 v[68:71], v[16:19], v[140:143], v[92:95]
	v_mfma_f32_16x16x32_bf16 v[32:35], v[16:19], v[152:155], v[60:63]
	ds_read_b128 v[16:19], v175 offset:46080
	v_mfma_f32_16x16x32_bf16 v[96:99], v[24:27], v[236:239], v[156:159]
	s_waitcnt lgkmcnt(1)
	v_mfma_f32_16x16x32_bf16 v[120:123], v[20:23], v[170:173], v[144:147]
	v_mfma_f32_16x16x32_bf16 v[88:91], v[20:23], v[236:239], v[116:119]
	s_nop 1
	ds_read_b128 v[144:147], v175 offset:49920
	v_mfma_f32_16x16x32_bf16 v[56:59], v[20:23], v[140:143], v[84:87]
	v_mfma_f32_16x16x32_bf16 v[28:31], v[20:23], v[152:155], v[52:55]
	ds_read_b128 v[20:23], v175 offset:47360
	s_waitcnt lgkmcnt(2)
	v_mfma_f32_16x16x32_bf16 v[124:127], v[16:19], v[170:173], v[182:185]
	v_mfma_f32_16x16x32_bf16 v[92:95], v[16:19], v[236:239], v[190:193]
	v_mfma_f32_16x16x32_bf16 v[60:63], v[16:19], v[140:143], v[198:201]
	v_mfma_f32_16x16x32_bf16 v[24:27], v[16:19], v[152:155], v[76:79]
	ds_read_b128 v[16:19], v175 offset:48640
	s_waitcnt lgkmcnt(1)
	v_mfma_f32_16x16x32_bf16 v[112:115], v[20:23], v[170:173], v[186:189]
	v_mfma_f32_16x16x32_bf16 v[80:83], v[20:23], v[236:239], v[194:197]
	v_mfma_f32_16x16x32_bf16 v[48:51], v[20:23], v[140:143], v[202:205]
	v_mfma_f32_16x16x32_bf16 v[20:23], v[20:23], v[152:155], v[206:209]
	s_waitcnt lgkmcnt(0)
	v_mfma_f32_16x16x32_bf16 v[116:119], v[16:19], v[170:173], v[212:215]
	v_mfma_f32_16x16x32_bf16 v[108:111], v[144:147], v[170:173], v[216:219]
	v_mfma_f32_16x16x32_bf16 v[84:87], v[16:19], v[236:239], v[220:223]
	v_mfma_f32_16x16x32_bf16 v[76:79], v[144:147], v[236:239], v[224:227]
	v_mfma_f32_16x16x32_bf16 v[52:55], v[16:19], v[140:143], v[228:231]
	v_mfma_f32_16x16x32_bf16 v[44:47], v[144:147], v[140:143], v[44:47]
	v_mfma_f32_16x16x32_bf16 v[16:19], v[16:19], v[152:155], v[232:235]
	v_mfma_f32_16x16x32_bf16 v[12:15], v[144:147], v[152:155], v[12:15]
	s_setprio 0
	v_and_b32_e32 v141, 64, v177
	v_xor_b32_e32 v140, 1, v177
	v_add_u32_e32 v141, 64, v141
	v_cmp_lt_i32_e32 vcc, v140, v141
	v_xor_b32_e32 v142, 2, v177
	s_nop 0
	v_cndmask_b32_e32 v140, v177, v140, vcc
	v_lshlrev_b32_e32 v140, 2, v140
	ds_bpermute_b32 v143, v140, v169
	v_cmp_lt_i32_e32 vcc, v142, v141
	s_barrier
	s_waitcnt lgkmcnt(0)
	v_cndmask_b32_e32 v142, v177, v142, vcc
	v_lshlrev_b32_e32 v142, 2, v142
	v_add_f32_e32 v144, v169, v143
	ds_bpermute_b32 v145, v142, v144
	v_xor_b32_e32 v143, 4, v177
	v_cmp_lt_i32_e32 vcc, v143, v141
	s_waitcnt lgkmcnt(0)
	v_add_f32_e32 v144, v144, v145
	v_cndmask_b32_e32 v141, v177, v143, vcc
	v_lshlrev_b32_e32 v143, 2, v141
	ds_bpermute_b32 v145, v143, v144
	v_cmp_eq_u32_e32 vcc, 0, v163
	v_lshlrev_b32_e32 v141, 2, v162
	s_and_saveexec_b64 s[6:7], vcc
	s_cbranch_execz .LBB0_129
	s_waitcnt lgkmcnt(0)
	v_add_f32_e32 v144, v144, v145
	v_fmamk_f32 v144, v144, 0x3a800000, v176
	v_mul_f32_e32 v145, 0x4b800000, v144
	v_cmp_gt_f32_e64 s[4:5], s73, v144
	s_nop 1
	v_cndmask_b32_e64 v144, v144, v145, s[4:5]
	v_rsq_f32_e32 v144, v144
	s_nop 0
	v_mul_f32_e32 v145, 0x45800000, v144
	v_cndmask_b32_e64 v144, v144, v145, s[4:5]
	ds_write_b32 v141, v144 offset:61440

; #define G_LOAD(kt_) do { \
;     if constexpr (AF32) { _Pragma("unroll") for (int i = 0; i < 4; ++i) ld16_sc1(ra[i], Af + (size_t)i * 32 * lda + (kt_) * 32); } \
;     else { _Pragma("unroll") for (int i = 0; i < 2; ++i) ld16_sc1(rab[i], Ab + (size_t)i * 64 * lda + (kt_) * 32); } \
;     _Pragma("unroll") for (int i = 0; i < 4; ++i) ld16_sc1(rb[i], Bp + (size_t)(kt_) * bstep + i * 2048); } while (0)
; template <bool AF32, class Epi>
; __device__ __forceinline__ void gemm_tile(unsigned char* smem, const void* Ap, int lda, const bf16_t* WT, int N, int K, const Epi& epi, int m0, int n0,
;                                           GPre& pr, bool preloaded, const void* nAp, int nn0, bool has_next) {
;     ...
;   if (!preloaded) G_LOAD(0);
;   G_STORE(0);
;   if (nk > 1) G_LOAD(1);
;   __syncthreads();
;   for (int kt = 0; kt < nk; ++kt) {
;     const int cur = kt & 1;
;     if (kt + 1 < nk) G_STORE(cur ^ 1);
;     if (kt + 2 < nk) G_LOAD(kt + 2);
;     const bf16_t* a_s = sbase + cur * G_STAGE + (wr * 64 + l15) * GLD + quad * 8;
;     const bf16_t* b_s = sbase + cur * G_STAGE + 128 * GLD + (wc * 128 + l15) * GLD + quad * 8;
;     __builtin_amdgcn_s_setprio(1);
;     bf16x8 af[4];
; #pragma unroll
;     for (int m = 0; m < 4; ++m) af[m] = *(const bf16x8*)(a_s + m * 16 * GLD);
; #pragma unroll
;     for (int nh = 0; nh < 4; ++nh) {
;       bf16x8 bfr[2];
; #pragma unroll
;       for (int n2 = 0; n2 < 2; ++n2) bfr[n2] = *(const bf16x8*)(b_s + (nh * 2 + n2) * 16 * GLD);
; #pragma unroll
;       for (int m = 0; m < 4; ++m)
; #pragma unroll
;         for (int n2 = 0; n2 < 2; ++n2) acc[m][nh * 2 + n2] = __builtin_amdgcn_mfma_f32_16x16x32_bf16(bfr[n2], af[m], acc[m][nh * 2 + n2], 0, 0, 0);
;     }
;     __builtin_amdgcn_s_setprio(0);
;     __syncthreads();
;   }
.LBB0_141:
	s_and_b32 s3, s4, 1
	s_waitcnt vmcnt(0)
	s_xor_b32 s5, s3, 1
	v_cvt_pk_bf16_f32 v198, v4, v5
	v_mov_b32_e32 v201, v4
	v_mov_b32_e32 v4, v137
	s_mulk_i32 s5, 0x7800
	v_mov_b32_e32 v200, v136
	v_pk_mul_f32 v[4:5], v[4:5], v[4:5]
	v_lshl_add_u32 v208, v184, 1, s5
	v_cvt_pk_bf16_f32 v199, v6, v7
	v_mov_b32_e32 v202, v138
	v_mov_b32_e32 v203, v6
	v_mov_b32_e32 v6, v139
	v_cvt_pk_bf16_f32 v136, v136, v137
	v_cvt_pk_bf16_f32 v137, v138, v139
	v_cvt_pk_bf16_f32 v138, v132, v133
	v_cvt_pk_bf16_f32 v139, v134, v135
	v_mov_b32_e32 v204, v128
	v_mov_b32_e32 v205, v132
	v_mov_b32_e32 v132, v129
	v_cvt_pk_bf16_f32 v128, v128, v129
	v_cvt_pk_bf16_f32 v129, v130, v131
	v_pk_fma_f32 v[4:5], v[200:201], v[200:201], v[4:5]
	v_lshl_add_u32 v209, v170, 1, s5
	v_mov_b32_e32 v206, v130
	v_mov_b32_e32 v207, v134
	v_mov_b32_e32 v134, v131
	ds_write2st64_b64 v208, v[198:199], v[136:137] offset1:5
	v_pk_mul_f32 v[130:131], v[132:133], v[132:133]
	ds_write2st64_b64 v208, v[138:139], v[128:129] offset0:10 offset1:15
	ds_write_b128 v209, v[20:23] offset:10240
	ds_write_b128 v209, v[24:27] offset:15360
	ds_write_b128 v209, v[28:31] offset:20480
	ds_write_b128 v209, v[36:39] offset:25600
	v_pk_fma_f32 v[4:5], v[202:203], v[202:203], v[4:5]
	v_pk_fma_f32 v[20:21], v[204:205], v[204:205], v[130:131]
	v_pk_fma_f32 v[198:199], v[6:7], v[6:7], v[4:5]
	s_setprio 2
	global_load_dwordx4 v[4:7], v[174:175], off sc1
	v_lshl_add_u64 v[186:187], v[174:175], 0, s[26:27]
	v_pk_fma_f32 v[20:21], v[206:207], v[206:207], v[20:21]
	global_load_dwordx4 v[136:139], v[186:187], off sc1
	v_lshl_add_u64 v[188:189], v[174:175], 0, s[28:29]
	v_pk_fma_f32 v[200:201], v[134:135], v[134:135], v[20:21]
	global_load_dwordx4 v[132:135], v[188:189], off sc1
	v_lshl_add_u64 v[190:191], v[174:175], 0, s[22:23]
	global_load_dwordx4 v[128:131], v[190:191], off sc1
	global_load_dwordx4 v[20:23], v[172:173], off sc1
	v_lshl_add_u64 v[192:193], v[172:173], 0, s[30:31]
	global_load_dwordx4 v[24:27], v[192:193], off sc1
	v_lshl_add_u64 v[194:195], v[172:173], 0, s[34:35]
	global_load_dwordx4 v[28:31], v[194:195], off sc1
	v_lshl_add_u64 v[196:197], v[172:173], 0, s[36:37]
	global_load_dwordx4 v[36:39], v[196:197], off sc1
	s_setprio 0
	s_add_i32 s4, s4, 1
	s_mulk_i32 s3, 0x7800
	v_pk_add_f32 v[168:169], v[168:169], v[198:199]
	v_pk_add_f32 v[166:167], v[166:167], v[200:201]
	v_add3_u32 v206, s3, v162, v160
	s_setprio 1
	v_add3_u32 v212, s3, v185, v160
	ds_read_b128 v[186:189], v212 offset:10240
	ds_read_b128 v[190:193], v212 offset:11520
	ds_read_b128 v[194:197], v206
	ds_read_b128 v[198:201], v206 offset:1280
	ds_read_b128 v[202:205], v206 offset:2560
	ds_read_b128 v[206:209], v206 offset:3840
	s_waitcnt lgkmcnt(3)
	v_mfma_f32_16x16x32_bf16 v[156:159], v[186:189], v[194:197], v[156:159]
	v_mfma_f32_16x16x32_bf16 v[152:155], v[190:193], v[194:197], v[152:155]
	s_waitcnt lgkmcnt(2)
	v_mfma_f32_16x16x32_bf16 v[140:143], v[186:189], v[198:201], v[140:143]
	v_mfma_f32_16x16x32_bf16 v[124:127], v[190:193], v[198:201], v[124:127]
	s_waitcnt lgkmcnt(1)
	v_mfma_f32_16x16x32_bf16 v[96:99], v[186:189], v[202:205], v[96:99]
	v_mfma_f32_16x16x32_bf16 v[88:91], v[190:193], v[202:205], v[88:91]
	s_waitcnt lgkmcnt(0)
	v_mfma_f32_16x16x32_bf16 v[64:67], v[186:189], v[206:209], v[64:67]
	ds_read_b128 v[186:189], v212 offset:12800
	v_mfma_f32_16x16x32_bf16 v[56:59], v[190:193], v[206:209], v[56:59]
	ds_read_b128 v[190:193], v212 offset:14080
	s_waitcnt lgkmcnt(1)
	v_mfma_f32_16x16x32_bf16 v[148:151], v[186:189], v[194:197], v[148:151]
	s_waitcnt lgkmcnt(0)
	v_mfma_f32_16x16x32_bf16 v[144:147], v[190:193], v[194:197], v[144:147]
	v_mfma_f32_16x16x32_bf16 v[112:115], v[186:189], v[198:201], v[112:115]
	v_mfma_f32_16x16x32_bf16 v[104:107], v[190:193], v[198:201], v[104:107]
	v_mfma_f32_16x16x32_bf16 v[80:83], v[186:189], v[202:205], v[80:83]
	v_mfma_f32_16x16x32_bf16 v[72:75], v[190:193], v[202:205], v[72:75]
	v_mfma_f32_16x16x32_bf16 v[48:51], v[186:189], v[206:209], v[48:51]
	ds_read_b128 v[186:189], v212 offset:15360
	v_mfma_f32_16x16x32_bf16 v[40:43], v[190:193], v[206:209], v[40:43]
	ds_read_b128 v[190:193], v212 offset:16640
	s_waitcnt lgkmcnt(1)
	v_mfma_f32_16x16x32_bf16 v[120:123], v[186:189], v[194:197], v[120:123]
	s_waitcnt lgkmcnt(0)
	v_mfma_f32_16x16x32_bf16 v[116:119], v[190:193], v[194:197], v[116:119]
	v_mfma_f32_16x16x32_bf16 v[92:95], v[186:189], v[198:201], v[92:95]
	v_mfma_f32_16x16x32_bf16 v[84:87], v[190:193], v[198:201], v[84:87]
	v_mfma_f32_16x16x32_bf16 v[60:63], v[186:189], v[202:205], v[60:63]
	v_mfma_f32_16x16x32_bf16 v[52:55], v[190:193], v[202:205], v[52:55]
	v_mfma_f32_16x16x32_bf16 v[16:19], v[186:189], v[206:209], v[16:19]
	ds_read_b128 v[186:189], v212 offset:17920
	v_mfma_f32_16x16x32_bf16 v[12:15], v[190:193], v[206:209], v[12:15]
	ds_read_b128 v[190:193], v212 offset:19200
	s_waitcnt lgkmcnt(1)
	v_mfma_f32_16x16x32_bf16 v[108:111], v[186:189], v[194:197], v[108:111]
	s_waitcnt lgkmcnt(0)
	v_mfma_f32_16x16x32_bf16 v[100:103], v[190:193], v[194:197], v[100:103]
	v_mfma_f32_16x16x32_bf16 v[76:79], v[186:189], v[198:201], v[76:79]
	v_mfma_f32_16x16x32_bf16 v[68:71], v[190:193], v[198:201], v[68:71]
	v_mfma_f32_16x16x32_bf16 v[44:47], v[186:189], v[202:205], v[44:47]
	v_mfma_f32_16x16x32_bf16 v[32:35], v[190:193], v[202:205], v[32:35]
	v_mfma_f32_16x16x32_bf16 v[8:11], v[186:189], v[206:209], v[8:11]
	v_mfma_f32_16x16x32_bf16 v[0:3], v[190:193], v[206:209], v[0:3]
	s_setprio 0
	v_lshl_add_u64 v[172:173], v[172:173], 0, s[56:57]
	s_cmp_eq_u32 s4, 30
	v_lshl_add_u64 v[174:175], v[174:175], 0, s[38:39]
	s_barrier
	s_cbranch_scc0 .LBB0_141
; #define G_LOAD(kt_) do { \
;     if constexpr (AF32) { _Pragma("unroll") for (int i = 0; i < 4; ++i) ld16_sc1(ra[i], Af + (size_t)i * 32 * lda + (kt_) * 32); } \
;     else { _Pragma("unroll") for (int i = 0; i < 2; ++i) ld16_sc1(rab[i], Ab + (size_t)i * 64 * lda + (kt_) * 32); } \
;     _Pragma("unroll") for (int i = 0; i < 4; ++i) ld16_sc1(rb[i], Bp + (size_t)(kt_) * bstep + i * 2048); } while (0)
; template <bool AF32, class Epi>
; __device__ __forceinline__ void gemm_tile(unsigned char* smem, const void* Ap, int lda, const bf16_t* WT, int N, int K, const Epi& epi, int m0, int n0,
;                                           GPre& pr, bool preloaded, const void* nAp, int nn0, bool has_next) {
;     ...
;     if (kt + 1 < nk) G_STORE(cur ^ 1);
;     if (kt + 2 < nk) G_LOAD(kt + 2);
;     const bf16_t* a_s = sbase + cur * G_STAGE + (wr * 64 + l15) * GLD + quad * 8;
;     const bf16_t* b_s = sbase + cur * G_STAGE + 128 * GLD + (wc * 128 + l15) * GLD + quad * 8;
;     __builtin_amdgcn_s_setprio(1);
;     bf16x8 af[4];
; #pragma unroll
;     for (int m = 0; m < 4; ++m) af[m] = *(const bf16x8*)(a_s + m * 16 * GLD);
; #pragma unroll
;     for (int nh = 0; nh < 4; ++nh) {
;       bf16x8 bfr[2];
; #pragma unroll
;       for (int n2 = 0; n2 < 2; ++n2) bfr[n2] = *(const bf16x8*)(b_s + (nh * 2 + n2) * 16 * GLD);
; #pragma unroll
;       for (int m = 0; m < 4; ++m)
; #pragma unroll
;         for (int n2 = 0; n2 < 2; ++n2) acc[m][nh * 2 + n2] = __builtin_amdgcn_mfma_f32_16x16x32_bf16(bfr[n2], af[m], acc[m][nh * 2 + n2], 0, 0, 0);
	s_waitcnt vmcnt(0)
	s_nop 0
	v_cvt_pk_bf16_f32 v172, v4, v5
	v_mul_f32_e32 v5, v5, v5
	v_fmac_f32_e32 v5, v4, v4
	v_cvt_pk_bf16_f32 v173, v6, v7
	v_cvt_pk_bf16_f32 v174, v136, v137
	v_cvt_pk_bf16_f32 v175, v138, v139
	v_fmac_f32_e32 v5, v6, v6
	ds_write2st64_b64 v183, v[172:173], v[174:175] offset0:60 offset1:65
	v_cvt_pk_bf16_f32 v172, v132, v133
	v_cvt_pk_bf16_f32 v173, v134, v135
	v_cvt_pk_bf16_f32 v174, v128, v129
	v_cvt_pk_bf16_f32 v175, v130, v131
	v_fmac_f32_e32 v5, v7, v7
	ds_write2st64_b64 v183, v[172:173], v[174:175] offset0:70 offset1:75
	ds_write_b128 v171, v[20:23] offset:40960
	ds_write_b128 v171, v[24:27] offset:46080
	ds_write_b128 v171, v[28:31] offset:51200
	ds_write_b128 v171, v[36:39] offset:56320
	v_add_f32_e32 v169, v169, v5
	v_add_u32_e32 v174, v162, v160
	s_setprio 1
	v_add_u32_e32 v160, v185, v160
	ds_read_b128 v[4:7], v160 offset:10240
	ds_read_b128 v[20:23], v160 offset:11520
	ds_read_b128 v[24:27], v174
	ds_read_b128 v[28:31], v174 offset:1280
	s_waitcnt lgkmcnt(1)
	v_mfma_f32_16x16x32_bf16 v[36:39], v[4:7], v[24:27], v[156:159]
	s_waitcnt lgkmcnt(0)
	v_mfma_f32_16x16x32_bf16 v[156:159], v[20:23], v[28:31], v[124:127]
	s_nop 2
	ds_read_b128 v[124:127], v174 offset:2560
	ds_read_b128 v[170:173], v174 offset:3840
	v_mfma_f32_16x16x32_bf16 v[152:155], v[20:23], v[24:27], v[152:155]
	v_mfma_f32_16x16x32_bf16 v[140:143], v[4:7], v[28:31], v[140:143]
	s_waitcnt lgkmcnt(1)
	v_mfma_f32_16x16x32_bf16 v[96:99], v[4:7], v[124:127], v[96:99]
	v_mfma_f32_16x16x32_bf16 v[88:91], v[20:23], v[124:127], v[88:91]
	s_waitcnt lgkmcnt(0)
	v_mfma_f32_16x16x32_bf16 v[4:7], v[4:7], v[170:173], v[64:67]
	s_nop 2
	ds_read_b128 v[64:67], v160 offset:12800
	v_mfma_f32_16x16x32_bf16 v[20:23], v[20:23], v[170:173], v[56:59]
	s_nop 2
	ds_read_b128 v[56:59], v160 offset:14080
	s_waitcnt lgkmcnt(1)
	v_mfma_f32_16x16x32_bf16 v[148:151], v[64:67], v[24:27], v[148:151]
	s_waitcnt lgkmcnt(0)
	v_mfma_f32_16x16x32_bf16 v[144:147], v[56:59], v[24:27], v[144:147]
	v_mfma_f32_16x16x32_bf16 v[184:187], v[64:67], v[28:31], v[112:115]
	v_mfma_f32_16x16x32_bf16 v[188:191], v[56:59], v[28:31], v[104:107]
	v_mfma_f32_16x16x32_bf16 v[80:83], v[64:67], v[124:127], v[80:83]
	v_mfma_f32_16x16x32_bf16 v[192:195], v[56:59], v[124:127], v[72:75]
	v_mfma_f32_16x16x32_bf16 v[48:51], v[64:67], v[170:173], v[48:51]
	ds_read_b128 v[64:67], v160 offset:15360
	v_mfma_f32_16x16x32_bf16 v[40:43], v[56:59], v[170:173], v[40:43]
	ds_read_b128 v[56:59], v160 offset:16640
	s_waitcnt lgkmcnt(0)
	v_mfma_f32_16x16x32_bf16 v[200:203], v[56:59], v[24:27], v[116:119]
	v_mfma_f32_16x16x32_bf16 v[212:215], v[56:59], v[28:31], v[84:87]
	v_mfma_f32_16x16x32_bf16 v[220:223], v[56:59], v[124:127], v[52:55]
	s_nop 2
	ds_read_b128 v[52:55], v160 offset:17920
	v_mfma_f32_16x16x32_bf16 v[56:59], v[56:59], v[170:173], v[12:15]
	s_nop 2
	ds_read_b128 v[12:15], v160 offset:19200
	v_mfma_f32_16x16x32_bf16 v[196:199], v[64:67], v[24:27], v[120:123]
	v_mfma_f32_16x16x32_bf16 v[16:19], v[64:67], v[170:173], v[16:19]
	s_waitcnt lgkmcnt(1)
	v_mfma_f32_16x16x32_bf16 v[224:227], v[52:55], v[24:27], v[108:111]
	s_waitcnt lgkmcnt(0)
	v_mfma_f32_16x16x32_bf16 v[24:27], v[12:15], v[24:27], v[100:103]
	v_mfma_f32_16x16x32_bf16 v[0:3], v[12:15], v[170:173], v[0:3]
	v_mfma_f32_16x16x32_bf16 v[204:207], v[64:67], v[28:31], v[92:95]
	v_mfma_f32_16x16x32_bf16 v[216:219], v[64:67], v[124:127], v[60:63]
	v_mfma_f32_16x16x32_bf16 v[228:231], v[52:55], v[28:31], v[76:79]
	v_mfma_f32_16x16x32_bf16 v[232:235], v[12:15], v[28:31], v[68:71]
	v_mfma_f32_16x16x32_bf16 v[236:239], v[52:55], v[124:127], v[44:47]
	v_mfma_f32_16x16x32_bf16 v[240:243], v[12:15], v[124:127], v[32:35]
	v_mfma_f32_16x16x32_bf16 v[244:247], v[52:55], v[170:173], v[8:11]
	s_setprio 0
	s_barrier
; #define G_LOAD(kt_) do { \
;     if constexpr (AF32) { _Pragma("unroll") for (int i = 0; i < 4; ++i) ld16_sc1(ra[i], Af + (size_t)i * 32 * lda + (kt_) * 32); } \
;     else { _Pragma("unroll") for (int i = 0; i < 2; ++i) ld16_sc1(rab[i], Ab + (size_t)i * 64 * lda + (kt_) * 32); } \
;     _Pragma("unroll") for (int i = 0; i < 4; ++i) ld16_sc1(rb[i], Bp + (size_t)(kt_) * bstep + i * 2048); } while (0)
; template <bool AF32, class Epi>
; __device__ __forceinline__ void gemm_tile(unsigned char* smem, const void* Ap, int lda, const bf16_t* WT, int N, int K, const Epi& epi, int m0, int n0,
;                                           GPre& pr, bool preloaded, const void* nAp, int nn0, bool has_next) {
;     ...
;     for (int m = 0; m < 4; ++m) af[m] = *(const bf16x8*)(a_s + m * 16 * GLD);
; #pragma unroll
;     for (int nh = 0; nh < 4; ++nh) {
;       bf16x8 bfr[2];
; #pragma unroll
;       for (int n2 = 0; n2 < 2; ++n2) bfr[n2] = *(const bf16x8*)(b_s + (nh * 2 + n2) * 16 * GLD);
; #pragma unroll
;       for (int m = 0; m < 4; ++m)
; #pragma unroll
;         for (int n2 = 0; n2 < 2; ++n2) acc[m][nh * 2 + n2] = __builtin_amdgcn_mfma_f32_16x16x32_bf16(bfr[n2], af[m], acc[m][nh * 2 + n2], 0, 0, 0);
;     }
;     __builtin_amdgcn_s_setprio(0);
;     __syncthreads();
;   }
;   if (has_next) {
;     const float* Af = (const float*)nAp + (size_t)(tid >> 3) * lda + (tid & 7) * 4;
;     const bf16_t* Ab = (const bf16_t*)nAp + (size_t)(tid >> 2) * lda + (tid & 3) * 8;
;     const bf16_t* Bp = WT + (size_t)nn0 * 32 + tid * 8;
;     G_LOAD(0);
;   }
;     ...
;   if constexpr (AF32) {
;     const float invK = 1.0f / (float)K;
; #pragma unroll
;     for (int i = 0; i < 4; ++i) {
;       float s = ss[i];
;       s += __shfl_xor(s, 1); s += __shfl_xor(s, 2); s += __shfl_xor(s, 4);
;       if ((tid & 7) == 0) sR[(tid >> 3) + 32 * i] = rsqrtf(s * invK + EPS);
;     }
;     __syncthreads();
	s_setprio 1
	ds_read_b128 v[8:11], v160 offset:40960
	ds_read_b128 v[12:15], v160 offset:42240
	ds_read_b128 v[32:35], v174 offset:30720
	ds_read_b128 v[170:173], v174 offset:32000
	s_waitcnt lgkmcnt(1)
	v_mfma_f32_16x16x32_bf16 v[116:119], v[12:15], v[32:35], v[152:155]
	s_waitcnt lgkmcnt(0)
	v_mfma_f32_16x16x32_bf16 v[108:111], v[8:11], v[170:173], v[140:143]
	s_nop 2
	ds_read_b128 v[140:143], v174 offset:33280
	ds_read_b128 v[152:155], v174 offset:34560
	s_waitcnt lgkmcnt(0)
	v_mfma_f32_16x16x32_bf16 v[76:79], v[8:11], v[152:155], v[4:7]
	s_nop 2
	ds_read_b128 v[4:7], v160 offset:43520
	v_mfma_f32_16x16x32_bf16 v[124:127], v[8:11], v[32:35], v[36:39]
	v_mfma_f32_16x16x32_bf16 v[92:95], v[8:11], v[140:143], v[96:99]
	ds_read_b128 v[8:11], v160 offset:44800
	v_mfma_f32_16x16x32_bf16 v[84:87], v[12:15], v[140:143], v[88:91]
	s_waitcnt lgkmcnt(1)
	v_mfma_f32_16x16x32_bf16 v[120:123], v[4:7], v[32:35], v[148:151]
	v_mfma_f32_16x16x32_bf16 v[104:107], v[4:7], v[170:173], v[184:187]
	v_mfma_f32_16x16x32_bf16 v[88:91], v[4:7], v[140:143], v[80:83]
	v_mfma_f32_16x16x32_bf16 v[68:71], v[4:7], v[152:155], v[48:51]
	ds_read_b128 v[4:7], v160 offset:46080
	v_mfma_f32_16x16x32_bf16 v[100:103], v[12:15], v[170:173], v[156:159]
	v_mfma_f32_16x16x32_bf16 v[72:75], v[12:15], v[152:155], v[20:23]
	s_waitcnt lgkmcnt(1)
	v_mfma_f32_16x16x32_bf16 v[112:115], v[8:11], v[32:35], v[144:147]
	v_mfma_f32_16x16x32_bf16 v[96:99], v[8:11], v[170:173], v[188:191]
	s_nop 1
	ds_read_b128 v[144:147], v160 offset:49920
	v_mfma_f32_16x16x32_bf16 v[80:83], v[8:11], v[140:143], v[192:195]
	v_mfma_f32_16x16x32_bf16 v[64:67], v[8:11], v[152:155], v[40:43]
	ds_read_b128 v[8:11], v160 offset:47360
	s_waitcnt lgkmcnt(2)
	v_mfma_f32_16x16x32_bf16 v[60:63], v[4:7], v[32:35], v[196:199]
	v_mfma_f32_16x16x32_bf16 v[44:47], v[4:7], v[170:173], v[204:207]
	v_mfma_f32_16x16x32_bf16 v[28:31], v[4:7], v[140:143], v[216:219]
	v_mfma_f32_16x16x32_bf16 v[12:15], v[4:7], v[152:155], v[16:19]
	ds_read_b128 v[4:7], v160 offset:48640
	s_waitcnt lgkmcnt(1)
	v_mfma_f32_16x16x32_bf16 v[52:55], v[8:11], v[32:35], v[200:203]
	v_mfma_f32_16x16x32_bf16 v[36:39], v[8:11], v[170:173], v[212:215]
	v_mfma_f32_16x16x32_bf16 v[20:23], v[8:11], v[140:143], v[220:223]
	v_mfma_f32_16x16x32_bf16 v[8:11], v[8:11], v[152:155], v[56:59]
	s_waitcnt lgkmcnt(0)
	v_mfma_f32_16x16x32_bf16 v[56:59], v[4:7], v[32:35], v[224:227]
	v_mfma_f32_16x16x32_bf16 v[48:51], v[144:147], v[32:35], v[24:27]
	v_mfma_f32_16x16x32_bf16 v[40:43], v[4:7], v[170:173], v[228:231]
	v_mfma_f32_16x16x32_bf16 v[32:35], v[144:147], v[170:173], v[232:235]
	v_mfma_f32_16x16x32_bf16 v[24:27], v[4:7], v[140:143], v[236:239]
	v_mfma_f32_16x16x32_bf16 v[16:19], v[144:147], v[140:143], v[240:243]
	v_mfma_f32_16x16x32_bf16 v[4:7], v[4:7], v[152:155], v[244:247]
	v_mfma_f32_16x16x32_bf16 v[0:3], v[144:147], v[152:155], v[0:3]
	s_setprio 0
	v_and_b32_e32 v141, 64, v177
	v_xor_b32_e32 v140, 1, v177
	v_add_u32_e32 v157, 64, v141
	v_cmp_lt_i32_e32 vcc, v140, v157
	v_xor_b32_e32 v142, 2, v177
	v_xor_b32_e32 v143, 4, v177
	v_cndmask_b32_e32 v140, v177, v140, vcc
	v_lshlrev_b32_e32 v140, 2, v140
	ds_bpermute_b32 v141, v140, v169
	v_cmp_lt_i32_e32 vcc, v142, v157
	s_waitcnt lgkmcnt(0)
	s_barrier
	v_cndmask_b32_e32 v142, v177, v142, vcc
	v_lshlrev_b32_e32 v142, 2, v142
	v_add_f32_e32 v141, v169, v141
	ds_bpermute_b32 v144, v142, v141
	v_cmp_lt_i32_e32 vcc, v143, v157
	s_waitcnt lgkmcnt(0)
	v_add_f32_e32 v144, v141, v144
	v_cndmask_b32_e32 v143, v177, v143, vcc
	v_lshlrev_b32_e32 v143, 2, v143
	ds_bpermute_b32 v145, v143, v144
	v_cmp_eq_u32_e32 vcc, 0, v165
	v_lshlrev_b32_e32 v141, 2, v164
	s_and_saveexec_b64 s[6:7], vcc
	s_cbranch_execz .LBB0_144
	s_waitcnt lgkmcnt(0)
	v_add_f32_e32 v144, v144, v145
	v_fmamk_f32 v144, v144, 0x3a800000, v176
	v_mul_f32_e32 v145, 0x4b800000, v144
	v_cmp_gt_f32_e64 s[4:5], s73, v144
	s_nop 1
	v_cndmask_b32_e64 v144, v144, v145, s[4:5]
	v_rsq_f32_e32 v144, v144
	s_nop 0
	v_mul_f32_e32 v145, 0x45800000, v144
	v_cndmask_b32_e64 v144, v144, v145, s[4:5]
	ds_write_b32 v141, v144 offset:61440

; #define G_LOAD(kt_) do { \
;     if constexpr (AF32) { _Pragma("unroll") for (int i = 0; i < 4; ++i) ld16_sc1(ra[i], Af + (size_t)i * 32 * lda + (kt_) * 32); } \
;     else { _Pragma("unroll") for (int i = 0; i < 2; ++i) ld16_sc1(rab[i], Ab + (size_t)i * 64 * lda + (kt_) * 32); } \
;     _Pragma("unroll") for (int i = 0; i < 4; ++i) ld16_sc1(rb[i], Bp + (size_t)(kt_) * bstep + i * 2048); } while (0)
; template <bool AF32, class Epi>
; __device__ __forceinline__ void gemm_tile(unsigned char* smem, const void* Ap, int lda, const bf16_t* WT, int N, int K, const Epi& epi, int m0, int n0,
;                                           GPre& pr, bool preloaded, const void* nAp, int nn0, bool has_next) {
;     ...
;   if (!preloaded) G_LOAD(0);
;   G_STORE(0);
;   if (nk > 1) G_LOAD(1);
;   __syncthreads();
;   for (int kt = 0; kt < nk; ++kt) {
;     const int cur = kt & 1;
;     if (kt + 1 < nk) G_STORE(cur ^ 1);
;     if (kt + 2 < nk) G_LOAD(kt + 2);
;     const bf16_t* a_s = sbase + cur * G_STAGE + (wr * 64 + l15) * GLD + quad * 8;
;     const bf16_t* b_s = sbase + cur * G_STAGE + 128 * GLD + (wc * 128 + l15) * GLD + quad * 8;
;     __builtin_amdgcn_s_setprio(1);
;     bf16x8 af[4];
; #pragma unroll
;     for (int m = 0; m < 4; ++m) af[m] = *(const bf16x8*)(a_s + m * 16 * GLD);
; #pragma unroll
;     for (int nh = 0; nh < 4; ++nh) {
;       bf16x8 bfr[2];
; #pragma unroll
;       for (int n2 = 0; n2 < 2; ++n2) bfr[n2] = *(const bf16x8*)(b_s + (nh * 2 + n2) * 16 * GLD);
; #pragma unroll
;       for (int m = 0; m < 4; ++m)
; #pragma unroll
;         for (int n2 = 0; n2 < 2; ++n2) acc[m][nh * 2 + n2] = __builtin_amdgcn_mfma_f32_16x16x32_bf16(bfr[n2], af[m], acc[m][nh * 2 + n2], 0, 0, 0);
;     }
;     __builtin_amdgcn_s_setprio(0);
;     __syncthreads();
;   }
.LBB0_265:
	s_and_b32 s3, s54, 1
	s_waitcnt vmcnt(0)
	s_xor_b32 s55, s3, 1
	s_mulk_i32 s55, 0x7800
	v_add_u32_e32 v176, s55, v155
	ds_write_b128 v176, v[0:3]
	ds_write_b128 v176, v[4:7] offset:5120
	ds_write_b128 v176, v[8:11] offset:10240
	ds_write_b128 v176, v[12:15] offset:15360
	ds_write_b128 v176, v[16:19] offset:20480
	ds_write_b128 v176, v[20:23] offset:25600
	s_setprio 2
	global_load_dwordx4 v[0:3], v[162:163], off sc1
	v_lshl_add_u64 v[168:169], v[162:163], 0, s[16:17]
	global_load_dwordx4 v[4:7], v[168:169], off sc1
	global_load_dwordx4 v[8:11], v[160:161], off sc1
	v_lshl_add_u64 v[170:171], v[160:161], 0, s[18:19]
	global_load_dwordx4 v[12:15], v[170:171], off sc1
	v_lshl_add_u64 v[172:173], v[160:161], 0, s[20:21]
	global_load_dwordx4 v[16:19], v[172:173], off sc1
	v_lshl_add_u64 v[174:175], v[160:161], 0, s[22:23]
	global_load_dwordx4 v[20:23], v[174:175], off sc1
	s_setprio 0
	s_add_i32 s54, s54, 1
	s_mulk_i32 s3, 0x7800
	v_add3_u32 v188, s3, v166, v167
	s_setprio 1
	v_add3_u32 v192, s3, v165, v167
	ds_read_b128 v[168:171], v192 offset:10240
	ds_read_b128 v[172:175], v192 offset:11520
	ds_read_b128 v[176:179], v188
	ds_read_b128 v[180:183], v188 offset:1280
	ds_read_b128 v[184:187], v188 offset:2560
	ds_read_b128 v[188:191], v188 offset:3840
	s_waitcnt lgkmcnt(3)
	v_mfma_f32_16x16x32_bf16 v[148:151], v[168:171], v[176:179], v[148:151]
	v_mfma_f32_16x16x32_bf16 v[144:147], v[172:175], v[176:179], v[144:147]
	s_waitcnt lgkmcnt(2)
	v_mfma_f32_16x16x32_bf16 v[132:135], v[168:171], v[180:183], v[132:135]
	v_mfma_f32_16x16x32_bf16 v[128:131], v[172:175], v[180:183], v[128:131]
	s_waitcnt lgkmcnt(1)
	v_mfma_f32_16x16x32_bf16 v[100:103], v[168:171], v[184:187], v[100:103]
	v_mfma_f32_16x16x32_bf16 v[92:95], v[172:175], v[184:187], v[92:95]
	s_waitcnt lgkmcnt(0)
	v_mfma_f32_16x16x32_bf16 v[68:71], v[168:171], v[188:191], v[68:71]
	ds_read_b128 v[168:171], v192 offset:12800
	v_mfma_f32_16x16x32_bf16 v[60:63], v[172:175], v[188:191], v[60:63]
	ds_read_b128 v[172:175], v192 offset:14080
	s_waitcnt lgkmcnt(1)
	v_mfma_f32_16x16x32_bf16 v[140:143], v[168:171], v[176:179], v[140:143]
	s_waitcnt lgkmcnt(0)
	v_mfma_f32_16x16x32_bf16 v[136:139], v[172:175], v[176:179], v[136:139]
	v_mfma_f32_16x16x32_bf16 v[116:119], v[168:171], v[180:183], v[116:119]
	v_mfma_f32_16x16x32_bf16 v[108:111], v[172:175], v[180:183], v[108:111]
	v_mfma_f32_16x16x32_bf16 v[84:87], v[168:171], v[184:187], v[84:87]
	v_mfma_f32_16x16x32_bf16 v[76:79], v[172:175], v[184:187], v[76:79]
	v_mfma_f32_16x16x32_bf16 v[52:55], v[168:171], v[188:191], v[52:55]
	ds_read_b128 v[168:171], v192 offset:15360
	v_mfma_f32_16x16x32_bf16 v[44:47], v[172:175], v[188:191], v[44:47]
	ds_read_b128 v[172:175], v192 offset:16640
	s_waitcnt lgkmcnt(1)
	v_mfma_f32_16x16x32_bf16 v[124:127], v[168:171], v[176:179], v[124:127]
	s_waitcnt lgkmcnt(0)
	v_mfma_f32_16x16x32_bf16 v[120:123], v[172:175], v[176:179], v[120:123]
	v_mfma_f32_16x16x32_bf16 v[96:99], v[168:171], v[180:183], v[96:99]
	v_mfma_f32_16x16x32_bf16 v[88:91], v[172:175], v[180:183], v[88:91]
	v_mfma_f32_16x16x32_bf16 v[64:67], v[168:171], v[184:187], v[64:67]
	v_mfma_f32_16x16x32_bf16 v[56:59], v[172:175], v[184:187], v[56:59]
	v_mfma_f32_16x16x32_bf16 v[36:39], v[168:171], v[188:191], v[36:39]
	ds_read_b128 v[168:171], v192 offset:17920
	v_mfma_f32_16x16x32_bf16 v[32:35], v[172:175], v[188:191], v[32:35]
	ds_read_b128 v[172:175], v192 offset:19200
	s_waitcnt lgkmcnt(1)
	v_mfma_f32_16x16x32_bf16 v[112:115], v[168:171], v[176:179], v[112:115]
	s_waitcnt lgkmcnt(0)
	v_mfma_f32_16x16x32_bf16 v[104:107], v[172:175], v[176:179], v[104:107]
	v_mfma_f32_16x16x32_bf16 v[80:83], v[168:171], v[180:183], v[80:83]
	v_mfma_f32_16x16x32_bf16 v[72:75], v[172:175], v[180:183], v[72:75]
	v_mfma_f32_16x16x32_bf16 v[48:51], v[168:171], v[184:187], v[48:51]
	v_mfma_f32_16x16x32_bf16 v[40:43], v[172:175], v[184:187], v[40:43]
	v_mfma_f32_16x16x32_bf16 v[28:31], v[168:171], v[188:191], v[28:31]
	v_mfma_f32_16x16x32_bf16 v[24:27], v[172:175], v[188:191], v[24:27]
	s_setprio 0
	v_lshl_add_u64 v[160:161], v[160:161], 0, s[26:27]
	s_cmp_eq_u32 s54, 22
	v_lshl_add_u64 v[162:163], v[162:163], 0, 64
	s_barrier
	s_cbranch_scc0 .LBB0_265
	s_waitcnt vmcnt(0)
	ds_write_b128 v155, v[0:3] offset:30720
	ds_write_b128 v155, v[4:7] offset:35840
	ds_write_b128 v155, v[8:11] offset:40960
	ds_write_b128 v155, v[12:15] offset:46080
	ds_write_b128 v155, v[16:19] offset:51200
	ds_write_b128 v155, v[20:23] offset:56320
	v_add_u32_e32 v155, v166, v167
	s_setprio 1
	v_add_u32_e32 v165, v165, v167
	ds_read_b128 v[160:163], v165 offset:10240
	ds_read_b128 v[166:169], v165 offset:11520
	ds_read_b128 v[170:173], v155
	ds_read_b128 v[174:177], v155 offset:1280
	ds_read_b128 v[178:181], v155 offset:2560
	ds_read_b128 v[182:185], v155 offset:3840
	s_waitcnt lgkmcnt(3)
	v_mfma_f32_16x16x32_bf16 v[148:151], v[160:163], v[170:173], v[148:151]
	v_mfma_f32_16x16x32_bf16 v[144:147], v[166:169], v[170:173], v[144:147]
	s_waitcnt lgkmcnt(2)
	v_mfma_f32_16x16x32_bf16 v[132:135], v[160:163], v[174:177], v[132:135]
	v_mfma_f32_16x16x32_bf16 v[128:131], v[166:169], v[174:177], v[128:131]
	s_waitcnt lgkmcnt(1)
	v_mfma_f32_16x16x32_bf16 v[100:103], v[160:163], v[178:181], v[100:103]
	v_mfma_f32_16x16x32_bf16 v[92:95], v[166:169], v[178:181], v[92:95]
	s_waitcnt lgkmcnt(0)
	v_mfma_f32_16x16x32_bf16 v[68:71], v[160:163], v[182:185], v[68:71]
	ds_read_b128 v[160:163], v165 offset:12800
	v_mfma_f32_16x16x32_bf16 v[60:63], v[166:169], v[182:185], v[60:63]
	ds_read_b128 v[166:169], v165 offset:14080
	s_waitcnt lgkmcnt(1)
	v_mfma_f32_16x16x32_bf16 v[186:189], v[160:163], v[170:173], v[140:143]
	s_waitcnt lgkmcnt(0)
; #define G_LOAD(kt_) do { \
;     if constexpr (AF32) { _Pragma("unroll") for (int i = 0; i < 4; ++i) ld16_sc1(ra[i], Af + (size_t)i * 32 * lda + (kt_) * 32); } \
;     else { _Pragma("unroll") for (int i = 0; i < 2; ++i) ld16_sc1(rab[i], Ab + (size_t)i * 64 * lda + (kt_) * 32); } \
;     _Pragma("unroll") for (int i = 0; i < 4; ++i) ld16_sc1(rb[i], Bp + (size_t)(kt_) * bstep + i * 2048); } while (0)
; template <bool AF32, class Epi>
; __device__ __forceinline__ void gemm_tile(unsigned char* smem, const void* Ap, int lda, const bf16_t* WT, int N, int K, const Epi& epi, int m0, int n0,
;                                           GPre& pr, bool preloaded, const void* nAp, int nn0, bool has_next) {
;     ...
;   for (int kt = 0; kt < nk; ++kt) {
;     const int cur = kt & 1;
;     if (kt + 1 < nk) G_STORE(cur ^ 1);
;     if (kt + 2 < nk) G_LOAD(kt + 2);
;     const bf16_t* a_s = sbase + cur * G_STAGE + (wr * 64 + l15) * GLD + quad * 8;
;     const bf16_t* b_s = sbase + cur * G_STAGE + 128 * GLD + (wc * 128 + l15) * GLD + quad * 8;
;     __builtin_amdgcn_s_setprio(1);
;     bf16x8 af[4];
; #pragma unroll
;     for (int m = 0; m < 4; ++m) af[m] = *(const bf16x8*)(a_s + m * 16 * GLD);
; #pragma unroll
;     for (int nh = 0; nh < 4; ++nh) {
;       bf16x8 bfr[2];
; #pragma unroll
;       for (int n2 = 0; n2 < 2; ++n2) bfr[n2] = *(const bf16x8*)(b_s + (nh * 2 + n2) * 16 * GLD);
; #pragma unroll
;       for (int m = 0; m < 4; ++m)
; #pragma unroll
;         for (int n2 = 0; n2 < 2; ++n2) acc[m][nh * 2 + n2] = __builtin_amdgcn_mfma_f32_16x16x32_bf16(bfr[n2], af[m], acc[m][nh * 2 + n2], 0, 0, 0);
;     }
;     __builtin_amdgcn_s_setprio(0);
;     __syncthreads();
;   }
;   if (has_next) {
;     const float* Af = (const float*)nAp + (size_t)(tid >> 3) * lda + (tid & 7) * 4;
;     const bf16_t* Ab = (const bf16_t*)nAp + (size_t)(tid >> 2) * lda + (tid & 3) * 8;
;     const bf16_t* Bp = WT + (size_t)nn0 * 32 + tid * 8;
;     G_LOAD(0);
;   }
	v_mfma_f32_16x16x32_bf16 v[136:139], v[166:169], v[170:173], v[136:139]
	v_mfma_f32_16x16x32_bf16 v[190:193], v[160:163], v[174:177], v[116:119]
	v_mfma_f32_16x16x32_bf16 v[194:197], v[166:169], v[174:177], v[108:111]
	v_mfma_f32_16x16x32_bf16 v[198:201], v[160:163], v[178:181], v[84:87]
	v_mfma_f32_16x16x32_bf16 v[202:205], v[166:169], v[178:181], v[76:79]
	v_mfma_f32_16x16x32_bf16 v[160:163], v[160:163], v[182:185], v[52:55]
	s_nop 2
	ds_read_b128 v[52:55], v165 offset:15360
	v_mfma_f32_16x16x32_bf16 v[166:169], v[166:169], v[182:185], v[44:47]
	s_nop 2
	ds_read_b128 v[44:47], v165 offset:16640
	s_waitcnt lgkmcnt(1)
	v_mfma_f32_16x16x32_bf16 v[124:127], v[52:55], v[170:173], v[124:127]
	s_waitcnt lgkmcnt(0)
	v_mfma_f32_16x16x32_bf16 v[120:123], v[44:47], v[170:173], v[120:123]
	v_mfma_f32_16x16x32_bf16 v[96:99], v[52:55], v[174:177], v[96:99]
	v_mfma_f32_16x16x32_bf16 v[88:91], v[44:47], v[174:177], v[88:91]
	v_mfma_f32_16x16x32_bf16 v[64:67], v[52:55], v[178:181], v[64:67]
	v_mfma_f32_16x16x32_bf16 v[56:59], v[44:47], v[178:181], v[56:59]
	v_mfma_f32_16x16x32_bf16 v[36:39], v[52:55], v[182:185], v[36:39]
	ds_read_b128 v[52:55], v165 offset:17920
	v_mfma_f32_16x16x32_bf16 v[32:35], v[44:47], v[182:185], v[32:35]
	ds_read_b128 v[44:47], v165 offset:19200
	s_waitcnt lgkmcnt(1)
	v_mfma_f32_16x16x32_bf16 v[28:31], v[52:55], v[182:185], v[28:31]
	s_waitcnt lgkmcnt(0)
	v_mfma_f32_16x16x32_bf16 v[24:27], v[44:47], v[182:185], v[24:27]
	v_mfma_f32_16x16x32_bf16 v[206:209], v[52:55], v[170:173], v[112:115]
	v_mfma_f32_16x16x32_bf16 v[170:173], v[44:47], v[170:173], v[104:107]
	v_mfma_f32_16x16x32_bf16 v[212:215], v[52:55], v[174:177], v[80:83]
	v_mfma_f32_16x16x32_bf16 v[174:177], v[44:47], v[174:177], v[72:75]
	v_mfma_f32_16x16x32_bf16 v[216:219], v[52:55], v[178:181], v[48:51]
	v_mfma_f32_16x16x32_bf16 v[178:181], v[44:47], v[178:181], v[40:43]
	s_setprio 0
	s_barrier
	s_setprio 1
	ds_read_b128 v[40:43], v165 offset:40960
	ds_read_b128 v[44:47], v165 offset:42240
	ds_read_b128 v[182:185], v155 offset:30720
	ds_read_b128 v[220:223], v155 offset:32000
	ds_read_b128 v[224:227], v155 offset:33280
	ds_read_b128 v[228:231], v155 offset:34560
	s_waitcnt lgkmcnt(3)
	v_mfma_f32_16x16x32_bf16 v[148:151], v[40:43], v[182:185], v[148:151]
	s_waitcnt lgkmcnt(2)
	v_mfma_f32_16x16x32_bf16 v[116:119], v[40:43], v[220:223], v[132:135]
	s_waitcnt lgkmcnt(1)
	v_mfma_f32_16x16x32_bf16 v[84:87], v[40:43], v[224:227], v[100:103]
	s_waitcnt lgkmcnt(0)
	v_mfma_f32_16x16x32_bf16 v[52:55], v[40:43], v[228:231], v[68:71]
	ds_read_b128 v[40:43], v165 offset:43520
	v_mfma_f32_16x16x32_bf16 v[48:51], v[44:47], v[228:231], v[60:63]
	s_nop 2
	ds_read_b128 v[60:63], v165 offset:44800
	v_mfma_f32_16x16x32_bf16 v[140:143], v[44:47], v[182:185], v[144:147]
	v_mfma_f32_16x16x32_bf16 v[108:111], v[44:47], v[220:223], v[128:131]
	v_mfma_f32_16x16x32_bf16 v[80:83], v[44:47], v[224:227], v[92:95]
	s_waitcnt lgkmcnt(1)
	v_mfma_f32_16x16x32_bf16 v[144:147], v[40:43], v[182:185], v[186:189]
	s_nop 0
	ds_read_b128 v[92:95], v165 offset:46080
	s_waitcnt lgkmcnt(1)
	v_mfma_f32_16x16x32_bf16 v[136:139], v[60:63], v[182:185], v[136:139]
	v_mfma_f32_16x16x32_bf16 v[112:115], v[40:43], v[220:223], v[190:193]
	v_mfma_f32_16x16x32_bf16 v[104:107], v[60:63], v[220:223], v[194:197]
	v_mfma_f32_16x16x32_bf16 v[76:79], v[40:43], v[224:227], v[198:201]
	v_mfma_f32_16x16x32_bf16 v[72:75], v[60:63], v[224:227], v[202:205]
	v_mfma_f32_16x16x32_bf16 v[44:47], v[40:43], v[228:231], v[160:163]
	v_mfma_f32_16x16x32_bf16 v[40:43], v[60:63], v[228:231], v[166:169]
	ds_read_b128 v[60:63], v165 offset:47360
	s_nop 0
	ds_read_b128 v[160:163], v165 offset:48640
	ds_read_b128 v[166:169], v165 offset:49920
	s_waitcnt lgkmcnt(3)
	v_mfma_f32_16x16x32_bf16 v[132:135], v[92:95], v[182:185], v[124:127]
	s_waitcnt lgkmcnt(2)
	v_mfma_f32_16x16x32_bf16 v[128:131], v[60:63], v[182:185], v[120:123]
	v_mfma_f32_16x16x32_bf16 v[100:103], v[92:95], v[220:223], v[96:99]
	v_mfma_f32_16x16x32_bf16 v[96:99], v[60:63], v[220:223], v[88:91]
	v_mfma_f32_16x16x32_bf16 v[68:71], v[92:95], v[224:227], v[64:67]
	v_mfma_f32_16x16x32_bf16 v[64:67], v[60:63], v[224:227], v[56:59]
	v_mfma_f32_16x16x32_bf16 v[36:39], v[92:95], v[228:231], v[36:39]
	v_mfma_f32_16x16x32_bf16 v[32:35], v[60:63], v[228:231], v[32:35]
	s_waitcnt lgkmcnt(1)
	v_mfma_f32_16x16x32_bf16 v[124:127], v[160:163], v[182:185], v[206:209]
	s_waitcnt lgkmcnt(0)
	v_mfma_f32_16x16x32_bf16 v[120:123], v[166:169], v[182:185], v[170:173]
	v_mfma_f32_16x16x32_bf16 v[92:95], v[160:163], v[220:223], v[212:215]
	v_mfma_f32_16x16x32_bf16 v[88:91], v[166:169], v[220:223], v[174:177]
	v_mfma_f32_16x16x32_bf16 v[60:63], v[160:163], v[224:227], v[216:219]
	v_mfma_f32_16x16x32_bf16 v[56:59], v[166:169], v[224:227], v[178:181]
	v_mfma_f32_16x16x32_bf16 v[28:31], v[160:163], v[228:231], v[28:31]
	v_mfma_f32_16x16x32_bf16 v[24:27], v[166:169], v[228:231], v[24:27]
	s_and_b64 vcc, exec, s[50:51]
	s_barrier
	s_cbranch_vccz .LBB0_253
	s_mul_i32 s50, s72, 0xc0000
	s_mul_hi_i32 s3, s72, 0xc0000
	s_add_u32 s50, s2, s50
	s_addc_u32 s51, s33, s3
	s_lshl_b32 s54, s71, 8
	s_ashr_i32 s55, s54, 31
	v_lshl_add_u64 v[0:1], v[158:159], 1, s[50:51]
	s_lshl_b64 s[50:51], s[54:55], 6
	v_lshl_add_u64 v[4:5], v[0:1], 0, v[152:153]
	s_add_u32 s50, s58, s50
	s_addc_u32 s51, s59, s51
	global_load_dwordx4 v[0:3], v[4:5], off sc1
	v_lshl_add_u64 v[4:5], v[4:5], 0, s[16:17]
	global_load_dwordx4 v[4:7], v[4:5], off sc1
	v_lshl_add_u64 v[20:21], v[156:157], 1, s[50:51]
	global_load_dwordx4 v[8:11], v[20:21], off sc1
	v_lshl_add_u64 v[12:13], v[20:21], 0, s[18:19]
	global_load_dwordx4 v[12:15], v[12:13], off sc1
	v_lshl_add_u64 v[16:17], v[20:21], 0, s[20:21]
	global_load_dwordx4 v[16:19], v[16:17], off sc1
	v_lshl_add_u64 v[20:21], v[20:21], 0, s[22:23]
	global_load_dwordx4 v[20:23], v[20:21], off sc1
	s_branch .LBB0_253

; #define G_LOAD(kt_) do { \
;     if constexpr (AF32) { _Pragma("unroll") for (int i = 0; i < 4; ++i) ld16_sc1(ra[i], Af + (size_t)i * 32 * lda + (kt_) * 32); } \
;     else { _Pragma("unroll") for (int i = 0; i < 2; ++i) ld16_sc1(rab[i], Ab + (size_t)i * 64 * lda + (kt_) * 32); } \
;     _Pragma("unroll") for (int i = 0; i < 4; ++i) ld16_sc1(rb[i], Bp + (size_t)(kt_) * bstep + i * 2048); } while (0)
; template <bool AF32, class Epi>
; __device__ __forceinline__ void gemm_tile(unsigned char* smem, const void* Ap, int lda, const bf16_t* WT, int N, int K, const Epi& epi, int m0, int n0,
;                                           GPre& pr, bool preloaded, const void* nAp, int nn0, bool has_next) {
;     ...
;   if (!preloaded) G_LOAD(0);
;   G_STORE(0);
;   if (nk > 1) G_LOAD(1);
;   __syncthreads();
;   for (int kt = 0; kt < nk; ++kt) {
;     const int cur = kt & 1;
;     if (kt + 1 < nk) G_STORE(cur ^ 1);
;     if (kt + 2 < nk) G_LOAD(kt + 2);
;     const bf16_t* a_s = sbase + cur * G_STAGE + (wr * 64 + l15) * GLD + quad * 8;
;     const bf16_t* b_s = sbase + cur * G_STAGE + 128 * GLD + (wc * 128 + l15) * GLD + quad * 8;
;     __builtin_amdgcn_s_setprio(1);
;     bf16x8 af[4];
; #pragma unroll
;     for (int m = 0; m < 4; ++m) af[m] = *(const bf16x8*)(a_s + m * 16 * GLD);
; #pragma unroll
;     for (int nh = 0; nh < 4; ++nh) {
;       bf16x8 bfr[2];
; #pragma unroll
;       for (int n2 = 0; n2 < 2; ++n2) bfr[n2] = *(const bf16x8*)(b_s + (nh * 2 + n2) * 16 * GLD);
; #pragma unroll
;       for (int m = 0; m < 4; ++m)
; #pragma unroll
;         for (int n2 = 0; n2 < 2; ++n2) acc[m][nh * 2 + n2] = __builtin_amdgcn_mfma_f32_16x16x32_bf16(bfr[n2], af[m], acc[m][nh * 2 + n2], 0, 0, 0);
;     }
;     __builtin_amdgcn_s_setprio(0);
;     __syncthreads();
;   }
.LBB0_296:
	s_and_b32 s3, s49, 1
	s_waitcnt vmcnt(0)
	s_xor_b32 s51, s3, 1
	s_mulk_i32 s51, 0x7800
	v_cvt_pk_bf16_f32 v202, v28, v29
	v_mov_b32_e32 v205, v28
	v_mov_b32_e32 v28, v25
	v_lshl_add_u32 v171, v160, 1, s51
	v_cvt_pk_bf16_f32 v203, v30, v31
	v_mov_b32_e32 v204, v24
	v_mov_b32_e32 v206, v26
	v_mov_b32_e32 v207, v30
	v_mov_b32_e32 v30, v27
	v_cvt_pk_bf16_f32 v24, v24, v25
	v_cvt_pk_bf16_f32 v25, v26, v27
	v_cvt_pk_bf16_f32 v26, v20, v21
	v_cvt_pk_bf16_f32 v27, v22, v23
	v_mov_b32_e32 v208, v16
	v_mov_b32_e32 v209, v20
	v_mov_b32_e32 v20, v17
	v_mov_b32_e32 v212, v18
	v_mov_b32_e32 v213, v22
	v_mov_b32_e32 v22, v19
	v_cvt_pk_bf16_f32 v16, v16, v17
	v_cvt_pk_bf16_f32 v17, v18, v19
	v_pk_mul_f32 v[18:19], v[28:29], v[28:29]
	v_lshl_add_u32 v176, v162, 1, s51
	ds_write2st64_b64 v171, v[202:203], v[24:25] offset1:5
	ds_write2st64_b64 v171, v[26:27], v[16:17] offset0:10 offset1:15
	ds_write_b128 v176, v[0:3] offset:10240
	ds_write_b128 v176, v[4:7] offset:15360
	ds_write_b128 v176, v[8:11] offset:20480
	ds_write_b128 v176, v[12:15] offset:25600
	v_pk_fma_f32 v[0:1], v[204:205], v[204:205], v[18:19]
	v_pk_mul_f32 v[20:21], v[20:21], v[20:21]
	v_pk_fma_f32 v[0:1], v[206:207], v[206:207], v[0:1]
	v_pk_fma_f32 v[2:3], v[208:209], v[208:209], v[20:21]
	v_pk_fma_f32 v[202:203], v[30:31], v[30:31], v[0:1]
	s_setprio 2
	global_load_dwordx4 v[28:31], v[166:167], off sc1
	v_lshl_add_u64 v[172:173], v[166:167], 0, s[14:15]
	v_pk_fma_f32 v[2:3], v[212:213], v[212:213], v[2:3]
	global_load_dwordx4 v[24:27], v[172:173], off sc1
	v_lshl_add_u64 v[174:175], v[166:167], 0, s[16:17]
	v_pk_fma_f32 v[204:205], v[22:23], v[22:23], v[2:3]
	global_load_dwordx4 v[20:23], v[174:175], off sc1
	v_lshl_add_u64 v[194:195], v[166:167], 0, s[18:19]
	global_load_dwordx4 v[16:19], v[194:195], off sc1
	global_load_dwordx4 v[0:3], v[164:165], off sc1
	v_lshl_add_u64 v[196:197], v[164:165], 0, s[20:21]
	global_load_dwordx4 v[4:7], v[196:197], off sc1
	v_lshl_add_u64 v[198:199], v[164:165], 0, s[22:23]
	global_load_dwordx4 v[8:11], v[198:199], off sc1
	v_lshl_add_u64 v[200:201], v[164:165], 0, s[24:25]
	global_load_dwordx4 v[12:15], v[200:201], off sc1
	s_setprio 0
	s_add_i32 s49, s49, 1
	s_mulk_i32 s3, 0x7800
	v_pk_add_f32 v[186:187], v[186:187], v[202:203]
	v_pk_add_f32 v[182:183], v[182:183], v[204:205]
	v_add3_u32 v171, s3, v169, v170
	s_setprio 1
	v_add3_u32 v176, s3, v168, v170
	ds_read_b128 v[172:175], v176 offset:10240
	ds_read_b128 v[194:197], v176 offset:11520
	ds_read_b128 v[198:201], v171
	ds_read_b128 v[202:205], v171 offset:1280
	ds_read_b128 v[206:209], v171 offset:2560
	ds_read_b128 v[212:215], v171 offset:3840
	s_waitcnt lgkmcnt(3)
	v_mfma_f32_16x16x32_bf16 v[156:159], v[172:175], v[198:201], v[156:159]
	v_mfma_f32_16x16x32_bf16 v[152:155], v[194:197], v[198:201], v[152:155]
	s_waitcnt lgkmcnt(2)
	v_mfma_f32_16x16x32_bf16 v[140:143], v[172:175], v[202:205], v[140:143]
	v_mfma_f32_16x16x32_bf16 v[136:139], v[194:197], v[202:205], v[136:139]
	s_waitcnt lgkmcnt(1)
	v_mfma_f32_16x16x32_bf16 v[108:111], v[172:175], v[206:209], v[108:111]
	v_mfma_f32_16x16x32_bf16 v[100:103], v[194:197], v[206:209], v[100:103]
	s_waitcnt lgkmcnt(0)
	v_mfma_f32_16x16x32_bf16 v[76:79], v[172:175], v[212:215], v[76:79]
	ds_read_b128 v[172:175], v176 offset:12800
	v_mfma_f32_16x16x32_bf16 v[68:71], v[194:197], v[212:215], v[68:71]
	ds_read_b128 v[194:197], v176 offset:14080
	s_waitcnt lgkmcnt(1)
	v_mfma_f32_16x16x32_bf16 v[148:151], v[172:175], v[198:201], v[148:151]
	s_waitcnt lgkmcnt(0)
	v_mfma_f32_16x16x32_bf16 v[144:147], v[194:197], v[198:201], v[144:147]
	v_mfma_f32_16x16x32_bf16 v[124:127], v[172:175], v[202:205], v[124:127]
	v_mfma_f32_16x16x32_bf16 v[116:119], v[194:197], v[202:205], v[116:119]
	v_mfma_f32_16x16x32_bf16 v[92:95], v[172:175], v[206:209], v[92:95]
	v_mfma_f32_16x16x32_bf16 v[84:87], v[194:197], v[206:209], v[84:87]
	v_mfma_f32_16x16x32_bf16 v[60:63], v[172:175], v[212:215], v[60:63]
	ds_read_b128 v[172:175], v176 offset:15360
	v_mfma_f32_16x16x32_bf16 v[52:55], v[194:197], v[212:215], v[52:55]
	ds_read_b128 v[194:197], v176 offset:16640
	s_waitcnt lgkmcnt(1)
	v_mfma_f32_16x16x32_bf16 v[132:135], v[172:175], v[198:201], v[132:135]
	s_waitcnt lgkmcnt(0)
	v_mfma_f32_16x16x32_bf16 v[128:131], v[194:197], v[198:201], v[128:131]
	v_mfma_f32_16x16x32_bf16 v[104:107], v[172:175], v[202:205], v[104:107]
	v_mfma_f32_16x16x32_bf16 v[96:99], v[194:197], v[202:205], v[96:99]
	v_mfma_f32_16x16x32_bf16 v[72:75], v[172:175], v[206:209], v[72:75]
	v_mfma_f32_16x16x32_bf16 v[64:67], v[194:197], v[206:209], v[64:67]
	v_mfma_f32_16x16x32_bf16 v[44:47], v[172:175], v[212:215], v[44:47]
	ds_read_b128 v[172:175], v176 offset:17920
	v_mfma_f32_16x16x32_bf16 v[40:43], v[194:197], v[212:215], v[40:43]
	ds_read_b128 v[194:197], v176 offset:19200
	s_waitcnt lgkmcnt(1)
	v_mfma_f32_16x16x32_bf16 v[120:123], v[172:175], v[198:201], v[120:123]
	s_waitcnt lgkmcnt(0)
	v_mfma_f32_16x16x32_bf16 v[112:115], v[194:197], v[198:201], v[112:115]
	v_mfma_f32_16x16x32_bf16 v[88:91], v[172:175], v[202:205], v[88:91]
	v_mfma_f32_16x16x32_bf16 v[80:83], v[194:197], v[202:205], v[80:83]
	v_mfma_f32_16x16x32_bf16 v[56:59], v[172:175], v[206:209], v[56:59]
	v_mfma_f32_16x16x32_bf16 v[48:51], v[194:197], v[206:209], v[48:51]
	v_mfma_f32_16x16x32_bf16 v[36:39], v[172:175], v[212:215], v[36:39]
	v_mfma_f32_16x16x32_bf16 v[32:35], v[194:197], v[212:215], v[32:35]
	s_setprio 0
	v_lshl_add_u64 v[164:165], v[164:165], 0, s[36:37]
	s_cmp_eq_u32 s49, 30
	v_lshl_add_u64 v[166:167], v[166:167], 0, s[26:27]
	s_barrier
	s_cbranch_scc0 .LBB0_296
; #define G_LOAD(kt_) do { \
;     if constexpr (AF32) { _Pragma("unroll") for (int i = 0; i < 4; ++i) ld16_sc1(ra[i], Af + (size_t)i * 32 * lda + (kt_) * 32); } \
;     else { _Pragma("unroll") for (int i = 0; i < 2; ++i) ld16_sc1(rab[i], Ab + (size_t)i * 64 * lda + (kt_) * 32); } \
;     _Pragma("unroll") for (int i = 0; i < 4; ++i) ld16_sc1(rb[i], Bp + (size_t)(kt_) * bstep + i * 2048); } while (0)
; template <bool AF32, class Epi>
; __device__ __forceinline__ void gemm_tile(unsigned char* smem, const void* Ap, int lda, const bf16_t* WT, int N, int K, const Epi& epi, int m0, int n0,
;                                           GPre& pr, bool preloaded, const void* nAp, int nn0, bool has_next) {
;     ...
;     if (kt + 1 < nk) G_STORE(cur ^ 1);
;     if (kt + 2 < nk) G_LOAD(kt + 2);
;     const bf16_t* a_s = sbase + cur * G_STAGE + (wr * 64 + l15) * GLD + quad * 8;
;     const bf16_t* b_s = sbase + cur * G_STAGE + 128 * GLD + (wc * 128 + l15) * GLD + quad * 8;
;     __builtin_amdgcn_s_setprio(1);
;     bf16x8 af[4];
; #pragma unroll
;     for (int m = 0; m < 4; ++m) af[m] = *(const bf16x8*)(a_s + m * 16 * GLD);
; #pragma unroll
;     for (int nh = 0; nh < 4; ++nh) {
;       bf16x8 bfr[2];
; #pragma unroll
;       for (int n2 = 0; n2 < 2; ++n2) bfr[n2] = *(const bf16x8*)(b_s + (nh * 2 + n2) * 16 * GLD);
; #pragma unroll
;       for (int m = 0; m < 4; ++m)
; #pragma unroll
;         for (int n2 = 0; n2 < 2; ++n2) acc[m][nh * 2 + n2] = __builtin_amdgcn_mfma_f32_16x16x32_bf16(bfr[n2], af[m], acc[m][nh * 2 + n2], 0, 0, 0);
	s_waitcnt vmcnt(0)
	v_add_u32_e32 v176, v169, v170
	v_cvt_pk_bf16_f32 v164, v28, v29
	v_cvt_pk_bf16_f32 v165, v30, v31
	v_cvt_pk_bf16_f32 v166, v24, v25
	v_cvt_pk_bf16_f32 v167, v26, v27
	ds_write2st64_b64 v161, v[164:165], v[166:167] offset0:60 offset1:65
	v_cvt_pk_bf16_f32 v164, v20, v21
	v_cvt_pk_bf16_f32 v165, v22, v23
	v_cvt_pk_bf16_f32 v166, v16, v17
	v_cvt_pk_bf16_f32 v167, v18, v19
	ds_write2st64_b64 v161, v[164:165], v[166:167] offset0:70 offset1:75
	ds_write_b128 v163, v[0:3] offset:40960
	ds_write_b128 v163, v[4:7] offset:46080
	ds_write_b128 v163, v[8:11] offset:51200
	ds_write_b128 v163, v[12:15] offset:56320
	s_setprio 1
	v_add_u32_e32 v193, v168, v170
	ds_read_b128 v[160:163], v193 offset:10240
	ds_read_b128 v[164:167], v193 offset:11520
	ds_read_b128 v[168:171], v176
	ds_read_b128 v[172:175], v176 offset:1280
	ds_read_b128 v[194:197], v176 offset:2560
	ds_read_b128 v[198:201], v176 offset:3840
	s_waitcnt lgkmcnt(3)
	v_mfma_f32_16x16x32_bf16 v[156:159], v[160:163], v[168:171], v[156:159]
	v_mfma_f32_16x16x32_bf16 v[152:155], v[164:167], v[168:171], v[152:155]
	s_waitcnt lgkmcnt(2)
	v_mfma_f32_16x16x32_bf16 v[140:143], v[160:163], v[172:175], v[140:143]
	v_mfma_f32_16x16x32_bf16 v[136:139], v[164:167], v[172:175], v[136:139]
	s_waitcnt lgkmcnt(1)
	v_mfma_f32_16x16x32_bf16 v[108:111], v[160:163], v[194:197], v[108:111]
	v_mfma_f32_16x16x32_bf16 v[100:103], v[164:167], v[194:197], v[100:103]
	s_waitcnt lgkmcnt(0)
	v_mfma_f32_16x16x32_bf16 v[76:79], v[160:163], v[198:201], v[76:79]
	ds_read_b128 v[160:163], v193 offset:12800
	v_mfma_f32_16x16x32_bf16 v[68:71], v[164:167], v[198:201], v[68:71]
	ds_read_b128 v[164:167], v193 offset:14080
	s_waitcnt lgkmcnt(1)
	v_mfma_f32_16x16x32_bf16 v[148:151], v[160:163], v[168:171], v[148:151]
	s_waitcnt lgkmcnt(0)
	v_mfma_f32_16x16x32_bf16 v[144:147], v[164:167], v[168:171], v[144:147]
	v_mfma_f32_16x16x32_bf16 v[124:127], v[160:163], v[172:175], v[124:127]
	v_mfma_f32_16x16x32_bf16 v[116:119], v[164:167], v[172:175], v[116:119]
	v_mfma_f32_16x16x32_bf16 v[92:95], v[160:163], v[194:197], v[92:95]
	v_mfma_f32_16x16x32_bf16 v[84:87], v[164:167], v[194:197], v[84:87]
	v_mfma_f32_16x16x32_bf16 v[60:63], v[160:163], v[198:201], v[60:63]
	ds_read_b128 v[160:163], v193 offset:15360
	v_mfma_f32_16x16x32_bf16 v[52:55], v[164:167], v[198:201], v[52:55]
	ds_read_b128 v[164:167], v193 offset:16640
	s_waitcnt lgkmcnt(1)
	v_mfma_f32_16x16x32_bf16 v[212:215], v[160:163], v[194:197], v[72:75]
	s_nop 2
	ds_read_b128 v[72:75], v193 offset:19200
	s_waitcnt lgkmcnt(1)
	v_mfma_f32_16x16x32_bf16 v[216:219], v[164:167], v[194:197], v[64:67]
	s_nop 2
	ds_read_b128 v[64:67], v193 offset:17920
	v_mfma_f32_16x16x32_bf16 v[128:131], v[164:167], v[168:171], v[128:131]
	v_mfma_f32_16x16x32_bf16 v[96:99], v[164:167], v[172:175], v[96:99]
	s_waitcnt lgkmcnt(0)
	v_mfma_f32_16x16x32_bf16 v[120:123], v[64:67], v[168:171], v[120:123]
	v_mfma_f32_16x16x32_bf16 v[112:115], v[72:75], v[168:171], v[112:115]
	v_mfma_f32_16x16x32_bf16 v[88:91], v[64:67], v[172:175], v[88:91]
	v_mfma_f32_16x16x32_bf16 v[80:83], v[72:75], v[172:175], v[80:83]
	v_mfma_f32_16x16x32_bf16 v[48:51], v[72:75], v[194:197], v[48:51]
	v_mfma_f32_16x16x32_bf16 v[202:205], v[160:163], v[168:171], v[132:135]
	v_mfma_f32_16x16x32_bf16 v[206:209], v[160:163], v[172:175], v[104:107]
	v_mfma_f32_16x16x32_bf16 v[44:47], v[160:163], v[198:201], v[44:47]
	v_mfma_f32_16x16x32_bf16 v[40:43], v[164:167], v[198:201], v[40:43]
	v_mfma_f32_16x16x32_bf16 v[220:223], v[64:67], v[194:197], v[56:59]
	v_mfma_f32_16x16x32_bf16 v[36:39], v[64:67], v[198:201], v[36:39]
	v_mfma_f32_16x16x32_bf16 v[32:35], v[72:75], v[198:201], v[32:35]
	s_setprio 0
	s_barrier
; #define G_LOAD(kt_) do { \
;     if constexpr (AF32) { _Pragma("unroll") for (int i = 0; i < 4; ++i) ld16_sc1(ra[i], Af + (size_t)i * 32 * lda + (kt_) * 32); } \
;     else { _Pragma("unroll") for (int i = 0; i < 2; ++i) ld16_sc1(rab[i], Ab + (size_t)i * 64 * lda + (kt_) * 32); } \
;     _Pragma("unroll") for (int i = 0; i < 4; ++i) ld16_sc1(rb[i], Bp + (size_t)(kt_) * bstep + i * 2048); } while (0)
; template <bool AF32, class Epi>
; __device__ __forceinline__ void gemm_tile(unsigned char* smem, const void* Ap, int lda, const bf16_t* WT, int N, int K, const Epi& epi, int m0, int n0,
;                                           GPre& pr, bool preloaded, const void* nAp, int nn0, bool has_next) {
;     ...
;   for (int kt = 0; kt < nk; ++kt) {
;     const int cur = kt & 1;
;     if (kt + 1 < nk) G_STORE(cur ^ 1);
;     if (kt + 2 < nk) G_LOAD(kt + 2);
;     const bf16_t* a_s = sbase + cur * G_STAGE + (wr * 64 + l15) * GLD + quad * 8;
;     const bf16_t* b_s = sbase + cur * G_STAGE + 128 * GLD + (wc * 128 + l15) * GLD + quad * 8;
;     __builtin_amdgcn_s_setprio(1);
;     bf16x8 af[4];
; #pragma unroll
;     for (int m = 0; m < 4; ++m) af[m] = *(const bf16x8*)(a_s + m * 16 * GLD);
; #pragma unroll
;     for (int nh = 0; nh < 4; ++nh) {
;       bf16x8 bfr[2];
; #pragma unroll
;       for (int n2 = 0; n2 < 2; ++n2) bfr[n2] = *(const bf16x8*)(b_s + (nh * 2 + n2) * 16 * GLD);
; #pragma unroll
;       for (int m = 0; m < 4; ++m)
; #pragma unroll
;         for (int n2 = 0; n2 < 2; ++n2) acc[m][nh * 2 + n2] = __builtin_amdgcn_mfma_f32_16x16x32_bf16(bfr[n2], af[m], acc[m][nh * 2 + n2], 0, 0, 0);
;     }
;     __builtin_amdgcn_s_setprio(0);
;     __syncthreads();
;   }
;   if (has_next) {
;     const float* Af = (const float*)nAp + (size_t)(tid >> 3) * lda + (tid & 7) * 4;
;     const bf16_t* Ab = (const bf16_t*)nAp + (size_t)(tid >> 2) * lda + (tid & 3) * 8;
;     const bf16_t* Bp = WT + (size_t)nn0 * 32 + tid * 8;
;     G_LOAD(0);
;   }
	s_setprio 1
	ds_read_b128 v[56:59], v193 offset:40960
	ds_read_b128 v[64:67], v193 offset:42240
	ds_read_b128 v[194:197], v176 offset:30720
	ds_read_b128 v[198:201], v176 offset:32000
	ds_read_b128 v[224:227], v176 offset:33280
	ds_read_b128 v[228:231], v176 offset:34560
	s_waitcnt lgkmcnt(3)
	v_mfma_f32_16x16x32_bf16 v[172:175], v[56:59], v[194:197], v[156:159]
	v_mfma_f32_16x16x32_bf16 v[164:167], v[64:67], v[194:197], v[152:155]
	s_waitcnt lgkmcnt(2)
	v_mfma_f32_16x16x32_bf16 v[140:143], v[56:59], v[198:201], v[140:143]
	v_mfma_f32_16x16x32_bf16 v[132:135], v[64:67], v[198:201], v[136:139]
	s_waitcnt lgkmcnt(1)
	v_mfma_f32_16x16x32_bf16 v[108:111], v[56:59], v[224:227], v[108:111]
	v_mfma_f32_16x16x32_bf16 v[100:103], v[64:67], v[224:227], v[100:103]
	s_waitcnt lgkmcnt(0)
	v_mfma_f32_16x16x32_bf16 v[76:79], v[56:59], v[228:231], v[76:79]
	ds_read_b128 v[56:59], v193 offset:43520
	v_mfma_f32_16x16x32_bf16 v[72:75], v[64:67], v[228:231], v[68:71]
	ds_read_b128 v[64:67], v193 offset:44800
	s_waitcnt lgkmcnt(1)
	v_mfma_f32_16x16x32_bf16 v[168:171], v[56:59], v[194:197], v[148:151]
	s_waitcnt lgkmcnt(0)
	v_mfma_f32_16x16x32_bf16 v[156:159], v[64:67], v[194:197], v[144:147]
	v_mfma_f32_16x16x32_bf16 v[136:139], v[56:59], v[198:201], v[124:127]
	v_mfma_f32_16x16x32_bf16 v[124:127], v[64:67], v[198:201], v[116:119]
	v_mfma_f32_16x16x32_bf16 v[104:107], v[56:59], v[224:227], v[92:95]
	v_mfma_f32_16x16x32_bf16 v[92:95], v[64:67], v[224:227], v[84:87]
	v_mfma_f32_16x16x32_bf16 v[68:71], v[56:59], v[228:231], v[60:63]
	ds_read_b128 v[56:59], v193 offset:46080
	v_mfma_f32_16x16x32_bf16 v[64:67], v[64:67], v[228:231], v[52:55]
	s_nop 2
	ds_read_b128 v[52:55], v193 offset:47360
	s_waitcnt lgkmcnt(1)
	v_mfma_f32_16x16x32_bf16 v[160:163], v[56:59], v[194:197], v[202:205]
	s_waitcnt lgkmcnt(0)
	v_mfma_f32_16x16x32_bf16 v[148:151], v[52:55], v[194:197], v[128:131]
	v_mfma_f32_16x16x32_bf16 v[128:131], v[56:59], v[198:201], v[206:209]
	v_mfma_f32_16x16x32_bf16 v[116:119], v[52:55], v[198:201], v[96:99]
	v_mfma_f32_16x16x32_bf16 v[96:99], v[56:59], v[224:227], v[212:215]
	v_mfma_f32_16x16x32_bf16 v[60:63], v[56:59], v[228:231], v[44:47]
	s_nop 2
	ds_read_b128 v[44:47], v193 offset:48640
	v_mfma_f32_16x16x32_bf16 v[56:59], v[52:55], v[228:231], v[40:43]
	s_nop 2
	ds_read_b128 v[40:43], v193 offset:49920
	v_mfma_f32_16x16x32_bf16 v[84:87], v[52:55], v[224:227], v[216:219]
	s_waitcnt lgkmcnt(1)
	v_mfma_f32_16x16x32_bf16 v[152:155], v[44:47], v[194:197], v[120:123]
	s_waitcnt lgkmcnt(0)
	v_mfma_f32_16x16x32_bf16 v[144:147], v[40:43], v[194:197], v[112:115]
	v_mfma_f32_16x16x32_bf16 v[120:123], v[44:47], v[198:201], v[88:91]
	v_mfma_f32_16x16x32_bf16 v[112:115], v[40:43], v[198:201], v[80:83]
	v_mfma_f32_16x16x32_bf16 v[88:91], v[44:47], v[224:227], v[220:223]
	v_mfma_f32_16x16x32_bf16 v[80:83], v[40:43], v[224:227], v[48:51]
	v_mfma_f32_16x16x32_bf16 v[52:55], v[44:47], v[228:231], v[36:39]
	v_mfma_f32_16x16x32_bf16 v[48:51], v[40:43], v[228:231], v[32:35]
	s_and_b64 vcc, exec, s[6:7]
	s_barrier
	s_cbranch_vccz .LBB0_299
	s_ashr_i32 s51, s50, 31
	s_lshl_b64 s[6:7], s[50:51], 19
	s_add_u32 s6, s10, s6
	s_addc_u32 s7, s11, s7
	s_lshl_b32 s50, s65, 8
	v_lshl_add_u64 v[0:1], v[188:189], 2, s[6:7]
	v_lshlrev_b32_e32 v176, 2, v190
	s_ashr_i32 s51, s50, 31
	v_lshl_add_u64 v[0:1], v[0:1], 0, v[176:177]
	s_lshl_b64 s[6:7], s[50:51], 6
	global_load_dwordx4 v[40:43], v[0:1], off sc1
	s_add_u32 s6, s2, s6
	v_lshl_add_u64 v[2:3], v[0:1], 0, s[14:15]
	global_load_dwordx4 v[44:47], v[2:3], off sc1
	s_addc_u32 s7, s33, s7
	v_lshl_add_u64 v[2:3], v[0:1], 0, s[16:17]
	global_load_dwordx4 v[32:35], v[2:3], off sc1
	v_lshl_add_u64 v[0:1], v[0:1], 0, s[18:19]
	global_load_dwordx4 v[36:39], v[0:1], off sc1
	v_lshl_add_u64 v[12:13], v[184:185], 1, s[6:7]
	global_load_dwordx4 v[0:3], v[12:13], off sc1
	v_lshl_add_u64 v[4:5], v[12:13], 0, s[20:21]
	global_load_dwordx4 v[4:7], v[4:5], off sc1
	v_lshl_add_u64 v[8:9], v[12:13], 0, s[22:23]
	global_load_dwordx4 v[8:11], v[8:9], off sc1
	v_lshl_add_u64 v[12:13], v[12:13], 0, s[24:25]
	global_load_dwordx4 v[12:15], v[12:13], off sc1
	s_branch .LBB0_300

; #define G_LOAD(kt_) do { \
;     if constexpr (AF32) { _Pragma("unroll") for (int i = 0; i < 4; ++i) ld16_sc1(ra[i], Af + (size_t)i * 32 * lda + (kt_) * 32); } \
;     else { _Pragma("unroll") for (int i = 0; i < 2; ++i) ld16_sc1(rab[i], Ab + (size_t)i * 64 * lda + (kt_) * 32); } \
;     _Pragma("unroll") for (int i = 0; i < 4; ++i) ld16_sc1(rb[i], Bp + (size_t)(kt_) * bstep + i * 2048); } while (0)
; template <bool AF32, class Epi>
; __device__ __forceinline__ void gemm_tile(unsigned char* smem, const void* Ap, int lda, const bf16_t* WT, int N, int K, const Epi& epi, int m0, int n0,
;                                           GPre& pr, bool preloaded, const void* nAp, int nn0, bool has_next) {
;     ...
;   if (!preloaded) G_LOAD(0);
;   G_STORE(0);
;   if (nk > 1) G_LOAD(1);
;   __syncthreads();
;   for (int kt = 0; kt < nk; ++kt) {
;     const int cur = kt & 1;
;     if (kt + 1 < nk) G_STORE(cur ^ 1);
;     if (kt + 2 < nk) G_LOAD(kt + 2);
;     const bf16_t* a_s = sbase + cur * G_STAGE + (wr * 64 + l15) * GLD + quad * 8;
;     const bf16_t* b_s = sbase + cur * G_STAGE + 128 * GLD + (wc * 128 + l15) * GLD + quad * 8;
;     __builtin_amdgcn_s_setprio(1);
;     bf16x8 af[4];
; #pragma unroll
;     for (int m = 0; m < 4; ++m) af[m] = *(const bf16x8*)(a_s + m * 16 * GLD);
; #pragma unroll
;     for (int nh = 0; nh < 4; ++nh) {
;       bf16x8 bfr[2];
; #pragma unroll
;       for (int n2 = 0; n2 < 2; ++n2) bfr[n2] = *(const bf16x8*)(b_s + (nh * 2 + n2) * 16 * GLD);
; #pragma unroll
;       for (int m = 0; m < 4; ++m)
; #pragma unroll
;         for (int n2 = 0; n2 < 2; ++n2) acc[m][nh * 2 + n2] = __builtin_amdgcn_mfma_f32_16x16x32_bf16(bfr[n2], af[m], acc[m][nh * 2 + n2], 0, 0, 0);
;     }
;     __builtin_amdgcn_s_setprio(0);
;     __syncthreads();
;   }
.LBB0_358:
	s_and_b32 s3, s53, 1
	s_waitcnt vmcnt(0)
	s_xor_b32 s54, s3, 1
	s_mulk_i32 s54, 0x7800
	v_add_u32_e32 v176, s54, v155
	ds_write_b128 v176, v[0:3]
	ds_write_b128 v176, v[4:7] offset:5120
	ds_write_b128 v176, v[8:11] offset:10240
	ds_write_b128 v176, v[12:15] offset:15360
	ds_write_b128 v176, v[16:19] offset:20480
	ds_write_b128 v176, v[20:23] offset:25600
	s_setprio 2
	global_load_dwordx4 v[0:3], v[162:163], off sc1
	v_lshl_add_u64 v[168:169], v[162:163], 0, s[12:13]
	global_load_dwordx4 v[4:7], v[168:169], off sc1
	global_load_dwordx4 v[8:11], v[160:161], off sc1
	v_lshl_add_u64 v[170:171], v[160:161], 0, s[14:15]
	global_load_dwordx4 v[12:15], v[170:171], off sc1
	v_lshl_add_u64 v[172:173], v[160:161], 0, s[16:17]
	global_load_dwordx4 v[16:19], v[172:173], off sc1
	v_lshl_add_u64 v[174:175], v[160:161], 0, s[18:19]
	global_load_dwordx4 v[20:23], v[174:175], off sc1
	s_setprio 0
	s_add_i32 s53, s53, 1
	s_mulk_i32 s3, 0x7800
	v_add3_u32 v188, s3, v166, v167
	s_setprio 1
	v_add3_u32 v192, s3, v165, v167
	ds_read_b128 v[168:171], v192 offset:10240
	ds_read_b128 v[172:175], v192 offset:11520
	ds_read_b128 v[176:179], v188
	ds_read_b128 v[180:183], v188 offset:1280
	ds_read_b128 v[184:187], v188 offset:2560
	ds_read_b128 v[188:191], v188 offset:3840
	s_waitcnt lgkmcnt(3)
	v_mfma_f32_16x16x32_bf16 v[148:151], v[168:171], v[176:179], v[148:151]
	v_mfma_f32_16x16x32_bf16 v[144:147], v[172:175], v[176:179], v[144:147]
	s_waitcnt lgkmcnt(2)
	v_mfma_f32_16x16x32_bf16 v[132:135], v[168:171], v[180:183], v[132:135]
	v_mfma_f32_16x16x32_bf16 v[128:131], v[172:175], v[180:183], v[128:131]
	s_waitcnt lgkmcnt(1)
	v_mfma_f32_16x16x32_bf16 v[100:103], v[168:171], v[184:187], v[100:103]
	v_mfma_f32_16x16x32_bf16 v[92:95], v[172:175], v[184:187], v[92:95]
	s_waitcnt lgkmcnt(0)
	v_mfma_f32_16x16x32_bf16 v[68:71], v[168:171], v[188:191], v[68:71]
	ds_read_b128 v[168:171], v192 offset:12800
	v_mfma_f32_16x16x32_bf16 v[60:63], v[172:175], v[188:191], v[60:63]
	ds_read_b128 v[172:175], v192 offset:14080
	s_waitcnt lgkmcnt(1)
	v_mfma_f32_16x16x32_bf16 v[140:143], v[168:171], v[176:179], v[140:143]
	s_waitcnt lgkmcnt(0)
	v_mfma_f32_16x16x32_bf16 v[136:139], v[172:175], v[176:179], v[136:139]
	v_mfma_f32_16x16x32_bf16 v[116:119], v[168:171], v[180:183], v[116:119]
	v_mfma_f32_16x16x32_bf16 v[108:111], v[172:175], v[180:183], v[108:111]
	v_mfma_f32_16x16x32_bf16 v[84:87], v[168:171], v[184:187], v[84:87]
	v_mfma_f32_16x16x32_bf16 v[76:79], v[172:175], v[184:187], v[76:79]
	v_mfma_f32_16x16x32_bf16 v[52:55], v[168:171], v[188:191], v[52:55]
	ds_read_b128 v[168:171], v192 offset:15360
	v_mfma_f32_16x16x32_bf16 v[44:47], v[172:175], v[188:191], v[44:47]
	ds_read_b128 v[172:175], v192 offset:16640
	s_waitcnt lgkmcnt(1)
	v_mfma_f32_16x16x32_bf16 v[124:127], v[168:171], v[176:179], v[124:127]
	s_waitcnt lgkmcnt(0)
	v_mfma_f32_16x16x32_bf16 v[120:123], v[172:175], v[176:179], v[120:123]
	v_mfma_f32_16x16x32_bf16 v[96:99], v[168:171], v[180:183], v[96:99]
	v_mfma_f32_16x16x32_bf16 v[88:91], v[172:175], v[180:183], v[88:91]
	v_mfma_f32_16x16x32_bf16 v[64:67], v[168:171], v[184:187], v[64:67]
	v_mfma_f32_16x16x32_bf16 v[56:59], v[172:175], v[184:187], v[56:59]
	v_mfma_f32_16x16x32_bf16 v[36:39], v[168:171], v[188:191], v[36:39]
	ds_read_b128 v[168:171], v192 offset:17920
	v_mfma_f32_16x16x32_bf16 v[32:35], v[172:175], v[188:191], v[32:35]
	ds_read_b128 v[172:175], v192 offset:19200
	s_waitcnt lgkmcnt(1)
	v_mfma_f32_16x16x32_bf16 v[112:115], v[168:171], v[176:179], v[112:115]
	s_waitcnt lgkmcnt(0)
	v_mfma_f32_16x16x32_bf16 v[104:107], v[172:175], v[176:179], v[104:107]
	v_mfma_f32_16x16x32_bf16 v[80:83], v[168:171], v[180:183], v[80:83]
	v_mfma_f32_16x16x32_bf16 v[72:75], v[172:175], v[180:183], v[72:75]
	v_mfma_f32_16x16x32_bf16 v[48:51], v[168:171], v[184:187], v[48:51]
	v_mfma_f32_16x16x32_bf16 v[40:43], v[172:175], v[184:187], v[40:43]
	v_mfma_f32_16x16x32_bf16 v[28:31], v[168:171], v[188:191], v[28:31]
	v_mfma_f32_16x16x32_bf16 v[24:27], v[172:175], v[188:191], v[24:27]
	s_setprio 0
	v_lshl_add_u64 v[160:161], v[160:161], 0, s[22:23]
	s_cmp_eq_u32 s53, 30
	v_lshl_add_u64 v[162:163], v[162:163], 0, 64
	s_barrier
	s_cbranch_scc0 .LBB0_358
	s_waitcnt vmcnt(0)
	ds_write_b128 v155, v[0:3] offset:30720
	ds_write_b128 v155, v[4:7] offset:35840
	ds_write_b128 v155, v[8:11] offset:40960
	ds_write_b128 v155, v[12:15] offset:46080
	ds_write_b128 v155, v[16:19] offset:51200
	ds_write_b128 v155, v[20:23] offset:56320
	v_add_u32_e32 v155, v166, v167
	s_setprio 1
	v_add_u32_e32 v165, v165, v167
	ds_read_b128 v[160:163], v165 offset:10240
	ds_read_b128 v[166:169], v165 offset:11520
	ds_read_b128 v[170:173], v155
	ds_read_b128 v[174:177], v155 offset:1280
	ds_read_b128 v[178:181], v155 offset:2560
	ds_read_b128 v[182:185], v155 offset:3840
	s_waitcnt lgkmcnt(3)
	v_mfma_f32_16x16x32_bf16 v[148:151], v[160:163], v[170:173], v[148:151]
	v_mfma_f32_16x16x32_bf16 v[144:147], v[166:169], v[170:173], v[144:147]
	s_waitcnt lgkmcnt(2)
	v_mfma_f32_16x16x32_bf16 v[132:135], v[160:163], v[174:177], v[132:135]
	v_mfma_f32_16x16x32_bf16 v[128:131], v[166:169], v[174:177], v[128:131]
	s_waitcnt lgkmcnt(1)
	v_mfma_f32_16x16x32_bf16 v[100:103], v[160:163], v[178:181], v[100:103]
	v_mfma_f32_16x16x32_bf16 v[92:95], v[166:169], v[178:181], v[92:95]
	s_waitcnt lgkmcnt(0)
	v_mfma_f32_16x16x32_bf16 v[68:71], v[160:163], v[182:185], v[68:71]
	ds_read_b128 v[160:163], v165 offset:12800
	v_mfma_f32_16x16x32_bf16 v[60:63], v[166:169], v[182:185], v[60:63]
	ds_read_b128 v[166:169], v165 offset:14080
	s_waitcnt lgkmcnt(1)
	v_mfma_f32_16x16x32_bf16 v[186:189], v[160:163], v[170:173], v[140:143]
	s_waitcnt lgkmcnt(0)
; #define G_LOAD(kt_) do { \
;     if constexpr (AF32) { _Pragma("unroll") for (int i = 0; i < 4; ++i) ld16_sc1(ra[i], Af + (size_t)i * 32 * lda + (kt_) * 32); } \
;     else { _Pragma("unroll") for (int i = 0; i < 2; ++i) ld16_sc1(rab[i], Ab + (size_t)i * 64 * lda + (kt_) * 32); } \
;     _Pragma("unroll") for (int i = 0; i < 4; ++i) ld16_sc1(rb[i], Bp + (size_t)(kt_) * bstep + i * 2048); } while (0)
; template <bool AF32, class Epi>
; __device__ __forceinline__ void gemm_tile(unsigned char* smem, const void* Ap, int lda, const bf16_t* WT, int N, int K, const Epi& epi, int m0, int n0,
;                                           GPre& pr, bool preloaded, const void* nAp, int nn0, bool has_next) {
;     ...
;   for (int kt = 0; kt < nk; ++kt) {
;     const int cur = kt & 1;
;     if (kt + 1 < nk) G_STORE(cur ^ 1);
;     if (kt + 2 < nk) G_LOAD(kt + 2);
;     const bf16_t* a_s = sbase + cur * G_STAGE + (wr * 64 + l15) * GLD + quad * 8;
;     const bf16_t* b_s = sbase + cur * G_STAGE + 128 * GLD + (wc * 128 + l15) * GLD + quad * 8;
;     __builtin_amdgcn_s_setprio(1);
;     bf16x8 af[4];
; #pragma unroll
;     for (int m = 0; m < 4; ++m) af[m] = *(const bf16x8*)(a_s + m * 16 * GLD);
; #pragma unroll
;     for (int nh = 0; nh < 4; ++nh) {
;       bf16x8 bfr[2];
; #pragma unroll
;       for (int n2 = 0; n2 < 2; ++n2) bfr[n2] = *(const bf16x8*)(b_s + (nh * 2 + n2) * 16 * GLD);
; #pragma unroll
;       for (int m = 0; m < 4; ++m)
; #pragma unroll
;         for (int n2 = 0; n2 < 2; ++n2) acc[m][nh * 2 + n2] = __builtin_amdgcn_mfma_f32_16x16x32_bf16(bfr[n2], af[m], acc[m][nh * 2 + n2], 0, 0, 0);
;     }
;     __builtin_amdgcn_s_setprio(0);
;     __syncthreads();
;   }
;   if (has_next) {
;     const float* Af = (const float*)nAp + (size_t)(tid >> 3) * lda + (tid & 7) * 4;
;     const bf16_t* Ab = (const bf16_t*)nAp + (size_t)(tid >> 2) * lda + (tid & 3) * 8;
;     const bf16_t* Bp = WT + (size_t)nn0 * 32 + tid * 8;
;     G_LOAD(0);
;   }
	v_mfma_f32_16x16x32_bf16 v[136:139], v[166:169], v[170:173], v[136:139]
	v_mfma_f32_16x16x32_bf16 v[190:193], v[160:163], v[174:177], v[116:119]
	v_mfma_f32_16x16x32_bf16 v[194:197], v[166:169], v[174:177], v[108:111]
	v_mfma_f32_16x16x32_bf16 v[198:201], v[160:163], v[178:181], v[84:87]
	v_mfma_f32_16x16x32_bf16 v[202:205], v[166:169], v[178:181], v[76:79]
	v_mfma_f32_16x16x32_bf16 v[160:163], v[160:163], v[182:185], v[52:55]
	s_nop 2
	ds_read_b128 v[52:55], v165 offset:15360
	v_mfma_f32_16x16x32_bf16 v[166:169], v[166:169], v[182:185], v[44:47]
	s_nop 2
	ds_read_b128 v[44:47], v165 offset:16640
	s_waitcnt lgkmcnt(1)
	v_mfma_f32_16x16x32_bf16 v[124:127], v[52:55], v[170:173], v[124:127]
	s_waitcnt lgkmcnt(0)
	v_mfma_f32_16x16x32_bf16 v[120:123], v[44:47], v[170:173], v[120:123]
	v_mfma_f32_16x16x32_bf16 v[96:99], v[52:55], v[174:177], v[96:99]
	v_mfma_f32_16x16x32_bf16 v[88:91], v[44:47], v[174:177], v[88:91]
	v_mfma_f32_16x16x32_bf16 v[64:67], v[52:55], v[178:181], v[64:67]
	v_mfma_f32_16x16x32_bf16 v[56:59], v[44:47], v[178:181], v[56:59]
	v_mfma_f32_16x16x32_bf16 v[36:39], v[52:55], v[182:185], v[36:39]
	ds_read_b128 v[52:55], v165 offset:17920
	v_mfma_f32_16x16x32_bf16 v[32:35], v[44:47], v[182:185], v[32:35]
	ds_read_b128 v[44:47], v165 offset:19200
	s_waitcnt lgkmcnt(1)
	v_mfma_f32_16x16x32_bf16 v[28:31], v[52:55], v[182:185], v[28:31]
	s_waitcnt lgkmcnt(0)
	v_mfma_f32_16x16x32_bf16 v[24:27], v[44:47], v[182:185], v[24:27]
	v_mfma_f32_16x16x32_bf16 v[206:209], v[52:55], v[170:173], v[112:115]
	v_mfma_f32_16x16x32_bf16 v[170:173], v[44:47], v[170:173], v[104:107]
	v_mfma_f32_16x16x32_bf16 v[212:215], v[52:55], v[174:177], v[80:83]
	v_mfma_f32_16x16x32_bf16 v[174:177], v[44:47], v[174:177], v[72:75]
	v_mfma_f32_16x16x32_bf16 v[216:219], v[52:55], v[178:181], v[48:51]
	v_mfma_f32_16x16x32_bf16 v[178:181], v[44:47], v[178:181], v[40:43]
	s_setprio 0
	s_barrier
	s_setprio 1
	ds_read_b128 v[40:43], v165 offset:40960
	ds_read_b128 v[44:47], v165 offset:42240
	ds_read_b128 v[182:185], v155 offset:30720
	ds_read_b128 v[220:223], v155 offset:32000
	ds_read_b128 v[224:227], v155 offset:33280
	ds_read_b128 v[228:231], v155 offset:34560
	s_waitcnt lgkmcnt(3)
	v_mfma_f32_16x16x32_bf16 v[148:151], v[40:43], v[182:185], v[148:151]
	s_waitcnt lgkmcnt(2)
	v_mfma_f32_16x16x32_bf16 v[116:119], v[40:43], v[220:223], v[132:135]
	s_waitcnt lgkmcnt(1)
	v_mfma_f32_16x16x32_bf16 v[84:87], v[40:43], v[224:227], v[100:103]
	s_waitcnt lgkmcnt(0)
	v_mfma_f32_16x16x32_bf16 v[52:55], v[40:43], v[228:231], v[68:71]
	ds_read_b128 v[40:43], v165 offset:43520
	v_mfma_f32_16x16x32_bf16 v[48:51], v[44:47], v[228:231], v[60:63]
	s_nop 2
	ds_read_b128 v[60:63], v165 offset:44800
	v_mfma_f32_16x16x32_bf16 v[140:143], v[44:47], v[182:185], v[144:147]
	v_mfma_f32_16x16x32_bf16 v[108:111], v[44:47], v[220:223], v[128:131]
	v_mfma_f32_16x16x32_bf16 v[80:83], v[44:47], v[224:227], v[92:95]
	s_waitcnt lgkmcnt(1)
	v_mfma_f32_16x16x32_bf16 v[144:147], v[40:43], v[182:185], v[186:189]
	s_nop 0
	ds_read_b128 v[92:95], v165 offset:46080
	s_waitcnt lgkmcnt(1)
	v_mfma_f32_16x16x32_bf16 v[136:139], v[60:63], v[182:185], v[136:139]
	v_mfma_f32_16x16x32_bf16 v[112:115], v[40:43], v[220:223], v[190:193]
	v_mfma_f32_16x16x32_bf16 v[104:107], v[60:63], v[220:223], v[194:197]
	v_mfma_f32_16x16x32_bf16 v[76:79], v[40:43], v[224:227], v[198:201]
	v_mfma_f32_16x16x32_bf16 v[72:75], v[60:63], v[224:227], v[202:205]
	v_mfma_f32_16x16x32_bf16 v[44:47], v[40:43], v[228:231], v[160:163]
	v_mfma_f32_16x16x32_bf16 v[40:43], v[60:63], v[228:231], v[166:169]
	ds_read_b128 v[60:63], v165 offset:47360
	s_nop 0
	ds_read_b128 v[160:163], v165 offset:48640
	ds_read_b128 v[166:169], v165 offset:49920
	s_waitcnt lgkmcnt(3)
	v_mfma_f32_16x16x32_bf16 v[132:135], v[92:95], v[182:185], v[124:127]
	s_waitcnt lgkmcnt(2)
	v_mfma_f32_16x16x32_bf16 v[128:131], v[60:63], v[182:185], v[120:123]
	v_mfma_f32_16x16x32_bf16 v[100:103], v[92:95], v[220:223], v[96:99]
	v_mfma_f32_16x16x32_bf16 v[96:99], v[60:63], v[220:223], v[88:91]
	v_mfma_f32_16x16x32_bf16 v[68:71], v[92:95], v[224:227], v[64:67]
	v_mfma_f32_16x16x32_bf16 v[64:67], v[60:63], v[224:227], v[56:59]
	v_mfma_f32_16x16x32_bf16 v[36:39], v[92:95], v[228:231], v[36:39]
	v_mfma_f32_16x16x32_bf16 v[32:35], v[60:63], v[228:231], v[32:35]
	s_waitcnt lgkmcnt(1)
	v_mfma_f32_16x16x32_bf16 v[124:127], v[160:163], v[182:185], v[206:209]
	s_waitcnt lgkmcnt(0)
	v_mfma_f32_16x16x32_bf16 v[120:123], v[166:169], v[182:185], v[170:173]
	v_mfma_f32_16x16x32_bf16 v[92:95], v[160:163], v[220:223], v[212:215]
	v_mfma_f32_16x16x32_bf16 v[88:91], v[166:169], v[220:223], v[174:177]
	v_mfma_f32_16x16x32_bf16 v[60:63], v[160:163], v[224:227], v[216:219]
	v_mfma_f32_16x16x32_bf16 v[56:59], v[166:169], v[224:227], v[178:181]
	v_mfma_f32_16x16x32_bf16 v[28:31], v[160:163], v[228:231], v[28:31]
	v_mfma_f32_16x16x32_bf16 v[24:27], v[166:169], v[228:231], v[24:27]
	s_and_b64 vcc, exec, s[48:49]
	s_barrier
	s_cbranch_vccz .LBB0_346
	s_ashr_i32 s53, s52, 31
	s_lshl_b64 s[48:49], s[52:53], 18
	s_add_u32 s48, s2, s48
	s_addc_u32 s49, s33, s49
	s_lshl_b32 s52, s68, 8
	s_ashr_i32 s53, s52, 31
	v_lshl_add_u64 v[0:1], v[158:159], 1, s[48:49]
	s_lshl_b64 s[48:49], s[52:53], 6
	v_lshl_add_u64 v[4:5], v[0:1], 0, v[152:153]
	s_add_u32 s48, s58, s48
	s_addc_u32 s49, s59, s49
	global_load_dwordx4 v[0:3], v[4:5], off sc1
	v_lshl_add_u64 v[4:5], v[4:5], 0, s[12:13]
	global_load_dwordx4 v[4:7], v[4:5], off sc1
	v_lshl_add_u64 v[20:21], v[156:157], 1, s[48:49]
	global_load_dwordx4 v[8:11], v[20:21], off sc1
	v_lshl_add_u64 v[12:13], v[20:21], 0, s[14:15]
	global_load_dwordx4 v[12:15], v[12:13], off sc1
	v_lshl_add_u64 v[16:17], v[20:21], 0, s[16:17]
	global_load_dwordx4 v[16:19], v[16:17], off sc1
	v_lshl_add_u64 v[20:21], v[20:21], 0, s[18:19]
	global_load_dwordx4 v[20:23], v[20:21], off sc1
	s_branch .LBB0_346

; #define G_LOAD(kt_) do { \
;     if constexpr (AF32) { _Pragma("unroll") for (int i = 0; i < 4; ++i) ld16_sc1(ra[i], Af + (size_t)i * 32 * lda + (kt_) * 32); } \
;     else { _Pragma("unroll") for (int i = 0; i < 2; ++i) ld16_sc1(rab[i], Ab + (size_t)i * 64 * lda + (kt_) * 32); } \
;     _Pragma("unroll") for (int i = 0; i < 4; ++i) ld16_sc1(rb[i], Bp + (size_t)(kt_) * bstep + i * 2048); } while (0)
; template <bool AF32, class Epi>
; __device__ __forceinline__ void gemm_tile(unsigned char* smem, const void* Ap, int lda, const bf16_t* WT, int N, int K, const Epi& epi, int m0, int n0,
;                                           GPre& pr, bool preloaded, const void* nAp, int nn0, bool has_next) {
;     ...
;   if (!preloaded) G_LOAD(0);
;   G_STORE(0);
;   if (nk > 1) G_LOAD(1);
;   __syncthreads();
;   for (int kt = 0; kt < nk; ++kt) {
;     const int cur = kt & 1;
;     if (kt + 1 < nk) G_STORE(cur ^ 1);
;     if (kt + 2 < nk) G_LOAD(kt + 2);
;     const bf16_t* a_s = sbase + cur * G_STAGE + (wr * 64 + l15) * GLD + quad * 8;
;     const bf16_t* b_s = sbase + cur * G_STAGE + 128 * GLD + (wc * 128 + l15) * GLD + quad * 8;
;     __builtin_amdgcn_s_setprio(1);
;     bf16x8 af[4];
; #pragma unroll
;     for (int m = 0; m < 4; ++m) af[m] = *(const bf16x8*)(a_s + m * 16 * GLD);
; #pragma unroll
;     for (int nh = 0; nh < 4; ++nh) {
;       bf16x8 bfr[2];
; #pragma unroll
;       for (int n2 = 0; n2 < 2; ++n2) bfr[n2] = *(const bf16x8*)(b_s + (nh * 2 + n2) * 16 * GLD);
; #pragma unroll
;       for (int m = 0; m < 4; ++m)
; #pragma unroll
;         for (int n2 = 0; n2 < 2; ++n2) acc[m][nh * 2 + n2] = __builtin_amdgcn_mfma_f32_16x16x32_bf16(bfr[n2], af[m], acc[m][nh * 2 + n2], 0, 0, 0);
;     }
;     __builtin_amdgcn_s_setprio(0);
;     __syncthreads();
;   }
.LBB0_389:
	s_and_b32 s3, s51, 1
	s_waitcnt vmcnt(0)
	s_xor_b32 s52, s3, 1
	s_mulk_i32 s52, 0x7800
	v_cvt_pk_bf16_f32 v202, v44, v45
	v_mov_b32_e32 v205, v44
	v_mov_b32_e32 v44, v41
	v_lshl_add_u32 v171, v160, 1, s52
	v_cvt_pk_bf16_f32 v203, v46, v47
	v_mov_b32_e32 v204, v40
	v_mov_b32_e32 v206, v42
	v_mov_b32_e32 v207, v46
	v_mov_b32_e32 v46, v43
	v_cvt_pk_bf16_f32 v40, v40, v41
	v_cvt_pk_bf16_f32 v41, v42, v43
	v_cvt_pk_bf16_f32 v42, v36, v37
	v_cvt_pk_bf16_f32 v43, v38, v39
	v_mov_b32_e32 v208, v32
	v_mov_b32_e32 v209, v36
	v_mov_b32_e32 v36, v33
	v_mov_b32_e32 v212, v34
	v_mov_b32_e32 v213, v38
	v_mov_b32_e32 v38, v35
	v_cvt_pk_bf16_f32 v32, v32, v33
	v_cvt_pk_bf16_f32 v33, v34, v35
	v_pk_mul_f32 v[34:35], v[44:45], v[44:45]
	v_lshl_add_u32 v176, v162, 1, s52
	ds_write2st64_b64 v171, v[202:203], v[40:41] offset1:5
	ds_write2st64_b64 v171, v[42:43], v[32:33] offset0:10 offset1:15
	ds_write_b128 v176, v[0:3] offset:10240
	ds_write_b128 v176, v[4:7] offset:15360
	ds_write_b128 v176, v[8:11] offset:20480
	ds_write_b128 v176, v[12:15] offset:25600
	v_pk_fma_f32 v[0:1], v[204:205], v[204:205], v[34:35]
	v_pk_mul_f32 v[36:37], v[36:37], v[36:37]
	v_pk_fma_f32 v[0:1], v[206:207], v[206:207], v[0:1]
	v_pk_fma_f32 v[2:3], v[208:209], v[208:209], v[36:37]
	v_pk_fma_f32 v[202:203], v[46:47], v[46:47], v[0:1]
	s_setprio 2
	global_load_dwordx4 v[44:47], v[166:167], off sc1
	v_lshl_add_u64 v[172:173], v[166:167], 0, s[16:17]
	v_pk_fma_f32 v[2:3], v[212:213], v[212:213], v[2:3]
	global_load_dwordx4 v[40:43], v[172:173], off sc1
	v_lshl_add_u64 v[174:175], v[166:167], 0, s[18:19]
	v_pk_fma_f32 v[204:205], v[38:39], v[38:39], v[2:3]
	global_load_dwordx4 v[36:39], v[174:175], off sc1
	v_lshl_add_u64 v[194:195], v[166:167], 0, s[20:21]
	global_load_dwordx4 v[32:35], v[194:195], off sc1
	global_load_dwordx4 v[0:3], v[164:165], off sc1
	v_lshl_add_u64 v[196:197], v[164:165], 0, s[22:23]
	global_load_dwordx4 v[4:7], v[196:197], off sc1
	v_lshl_add_u64 v[198:199], v[164:165], 0, s[24:25]
	global_load_dwordx4 v[8:11], v[198:199], off sc1
	v_lshl_add_u64 v[200:201], v[164:165], 0, s[26:27]
	global_load_dwordx4 v[12:15], v[200:201], off sc1
	s_setprio 0
	s_add_i32 s51, s51, 1
	s_mulk_i32 s3, 0x7800
	v_pk_add_f32 v[184:185], v[184:185], v[202:203]
	v_pk_add_f32 v[180:181], v[180:181], v[204:205]
	v_add3_u32 v171, s3, v169, v170
	s_setprio 1
	v_add3_u32 v176, s3, v168, v170
	ds_read_b128 v[172:175], v176 offset:10240
	ds_read_b128 v[194:197], v176 offset:11520
	ds_read_b128 v[198:201], v171
	ds_read_b128 v[202:205], v171 offset:1280
	ds_read_b128 v[206:209], v171 offset:2560
	ds_read_b128 v[212:215], v171 offset:3840
	s_waitcnt lgkmcnt(3)
	v_mfma_f32_16x16x32_bf16 v[156:159], v[172:175], v[198:201], v[156:159]
	v_mfma_f32_16x16x32_bf16 v[152:155], v[194:197], v[198:201], v[152:155]
	s_waitcnt lgkmcnt(2)
	v_mfma_f32_16x16x32_bf16 v[140:143], v[172:175], v[202:205], v[140:143]
	v_mfma_f32_16x16x32_bf16 v[136:139], v[194:197], v[202:205], v[136:139]
	s_waitcnt lgkmcnt(1)
	v_mfma_f32_16x16x32_bf16 v[108:111], v[172:175], v[206:209], v[108:111]
	v_mfma_f32_16x16x32_bf16 v[100:103], v[194:197], v[206:209], v[100:103]
	s_waitcnt lgkmcnt(0)
	v_mfma_f32_16x16x32_bf16 v[76:79], v[172:175], v[212:215], v[76:79]
	ds_read_b128 v[172:175], v176 offset:12800
	v_mfma_f32_16x16x32_bf16 v[68:71], v[194:197], v[212:215], v[68:71]
	ds_read_b128 v[194:197], v176 offset:14080
	s_waitcnt lgkmcnt(1)
	v_mfma_f32_16x16x32_bf16 v[148:151], v[172:175], v[198:201], v[148:151]
	s_waitcnt lgkmcnt(0)
	v_mfma_f32_16x16x32_bf16 v[144:147], v[194:197], v[198:201], v[144:147]
	v_mfma_f32_16x16x32_bf16 v[124:127], v[172:175], v[202:205], v[124:127]
	v_mfma_f32_16x16x32_bf16 v[116:119], v[194:197], v[202:205], v[116:119]
	v_mfma_f32_16x16x32_bf16 v[92:95], v[172:175], v[206:209], v[92:95]
	v_mfma_f32_16x16x32_bf16 v[84:87], v[194:197], v[206:209], v[84:87]
	v_mfma_f32_16x16x32_bf16 v[60:63], v[172:175], v[212:215], v[60:63]
	ds_read_b128 v[172:175], v176 offset:15360
	v_mfma_f32_16x16x32_bf16 v[52:55], v[194:197], v[212:215], v[52:55]
	ds_read_b128 v[194:197], v176 offset:16640
	s_waitcnt lgkmcnt(1)
	v_mfma_f32_16x16x32_bf16 v[132:135], v[172:175], v[198:201], v[132:135]
	s_waitcnt lgkmcnt(0)
	v_mfma_f32_16x16x32_bf16 v[128:131], v[194:197], v[198:201], v[128:131]
	v_mfma_f32_16x16x32_bf16 v[104:107], v[172:175], v[202:205], v[104:107]
	v_mfma_f32_16x16x32_bf16 v[96:99], v[194:197], v[202:205], v[96:99]
	v_mfma_f32_16x16x32_bf16 v[72:75], v[172:175], v[206:209], v[72:75]
	v_mfma_f32_16x16x32_bf16 v[64:67], v[194:197], v[206:209], v[64:67]
	v_mfma_f32_16x16x32_bf16 v[28:31], v[172:175], v[212:215], v[28:31]
	ds_read_b128 v[172:175], v176 offset:17920
	v_mfma_f32_16x16x32_bf16 v[24:27], v[194:197], v[212:215], v[24:27]
	ds_read_b128 v[194:197], v176 offset:19200
	s_waitcnt lgkmcnt(1)
	v_mfma_f32_16x16x32_bf16 v[120:123], v[172:175], v[198:201], v[120:123]
	s_waitcnt lgkmcnt(0)
	v_mfma_f32_16x16x32_bf16 v[112:115], v[194:197], v[198:201], v[112:115]
	v_mfma_f32_16x16x32_bf16 v[88:91], v[172:175], v[202:205], v[88:91]
	v_mfma_f32_16x16x32_bf16 v[80:83], v[194:197], v[202:205], v[80:83]
	v_mfma_f32_16x16x32_bf16 v[56:59], v[172:175], v[206:209], v[56:59]
	v_mfma_f32_16x16x32_bf16 v[48:51], v[194:197], v[206:209], v[48:51]
	v_mfma_f32_16x16x32_bf16 v[20:23], v[172:175], v[212:215], v[20:23]
	v_mfma_f32_16x16x32_bf16 v[16:19], v[194:197], v[212:215], v[16:19]
	s_setprio 0
	v_lshl_add_u64 v[164:165], v[164:165], 0, s[38:39]
	s_cmp_eq_u32 s51, 30
	v_lshl_add_u64 v[166:167], v[166:167], 0, s[28:29]
	s_barrier
	s_cbranch_scc0 .LBB0_389
; #define G_LOAD(kt_) do { \
;     if constexpr (AF32) { _Pragma("unroll") for (int i = 0; i < 4; ++i) ld16_sc1(ra[i], Af + (size_t)i * 32 * lda + (kt_) * 32); } \
;     else { _Pragma("unroll") for (int i = 0; i < 2; ++i) ld16_sc1(rab[i], Ab + (size_t)i * 64 * lda + (kt_) * 32); } \
;     _Pragma("unroll") for (int i = 0; i < 4; ++i) ld16_sc1(rb[i], Bp + (size_t)(kt_) * bstep + i * 2048); } while (0)
; template <bool AF32, class Epi>
; __device__ __forceinline__ void gemm_tile(unsigned char* smem, const void* Ap, int lda, const bf16_t* WT, int N, int K, const Epi& epi, int m0, int n0,
;                                           GPre& pr, bool preloaded, const void* nAp, int nn0, bool has_next) {
;     ...
;     if (kt + 1 < nk) G_STORE(cur ^ 1);
;     if (kt + 2 < nk) G_LOAD(kt + 2);
;     const bf16_t* a_s = sbase + cur * G_STAGE + (wr * 64 + l15) * GLD + quad * 8;
;     const bf16_t* b_s = sbase + cur * G_STAGE + 128 * GLD + (wc * 128 + l15) * GLD + quad * 8;
;     __builtin_amdgcn_s_setprio(1);
;     bf16x8 af[4];
; #pragma unroll
;     for (int m = 0; m < 4; ++m) af[m] = *(const bf16x8*)(a_s + m * 16 * GLD);
; #pragma unroll
;     for (int nh = 0; nh < 4; ++nh) {
;       bf16x8 bfr[2];
; #pragma unroll
;       for (int n2 = 0; n2 < 2; ++n2) bfr[n2] = *(const bf16x8*)(b_s + (nh * 2 + n2) * 16 * GLD);
; #pragma unroll
;       for (int m = 0; m < 4; ++m)
; #pragma unroll
;         for (int n2 = 0; n2 < 2; ++n2) acc[m][nh * 2 + n2] = __builtin_amdgcn_mfma_f32_16x16x32_bf16(bfr[n2], af[m], acc[m][nh * 2 + n2], 0, 0, 0);
	s_waitcnt vmcnt(0)
	v_add_u32_e32 v176, v169, v170
	v_cvt_pk_bf16_f32 v164, v44, v45
	v_cvt_pk_bf16_f32 v165, v46, v47
	v_cvt_pk_bf16_f32 v166, v40, v41
	v_cvt_pk_bf16_f32 v167, v42, v43
	ds_write2st64_b64 v161, v[164:165], v[166:167] offset0:60 offset1:65
	v_cvt_pk_bf16_f32 v164, v36, v37
	v_cvt_pk_bf16_f32 v165, v38, v39
	v_cvt_pk_bf16_f32 v166, v32, v33
	v_cvt_pk_bf16_f32 v167, v34, v35
	ds_write2st64_b64 v161, v[164:165], v[166:167] offset0:70 offset1:75
	ds_write_b128 v163, v[0:3] offset:40960
	ds_write_b128 v163, v[4:7] offset:46080
	ds_write_b128 v163, v[8:11] offset:51200
	ds_write_b128 v163, v[12:15] offset:56320
	s_setprio 1
	v_add_u32_e32 v193, v168, v170
	ds_read_b128 v[160:163], v193 offset:10240
	ds_read_b128 v[164:167], v193 offset:11520
	ds_read_b128 v[168:171], v176
	ds_read_b128 v[172:175], v176 offset:1280
	ds_read_b128 v[194:197], v176 offset:2560
	ds_read_b128 v[198:201], v176 offset:3840
	s_waitcnt lgkmcnt(3)
	v_mfma_f32_16x16x32_bf16 v[156:159], v[160:163], v[168:171], v[156:159]
	v_mfma_f32_16x16x32_bf16 v[152:155], v[164:167], v[168:171], v[152:155]
	s_waitcnt lgkmcnt(2)
	v_mfma_f32_16x16x32_bf16 v[140:143], v[160:163], v[172:175], v[140:143]
	v_mfma_f32_16x16x32_bf16 v[136:139], v[164:167], v[172:175], v[136:139]
	s_waitcnt lgkmcnt(1)
	v_mfma_f32_16x16x32_bf16 v[108:111], v[160:163], v[194:197], v[108:111]
	v_mfma_f32_16x16x32_bf16 v[100:103], v[164:167], v[194:197], v[100:103]
	s_waitcnt lgkmcnt(0)
	v_mfma_f32_16x16x32_bf16 v[76:79], v[160:163], v[198:201], v[76:79]
	ds_read_b128 v[160:163], v193 offset:12800
	v_mfma_f32_16x16x32_bf16 v[68:71], v[164:167], v[198:201], v[68:71]
	ds_read_b128 v[164:167], v193 offset:14080
	s_waitcnt lgkmcnt(1)
	v_mfma_f32_16x16x32_bf16 v[148:151], v[160:163], v[168:171], v[148:151]
	s_waitcnt lgkmcnt(0)
	v_mfma_f32_16x16x32_bf16 v[144:147], v[164:167], v[168:171], v[144:147]
	v_mfma_f32_16x16x32_bf16 v[124:127], v[160:163], v[172:175], v[124:127]
	v_mfma_f32_16x16x32_bf16 v[116:119], v[164:167], v[172:175], v[116:119]
	v_mfma_f32_16x16x32_bf16 v[92:95], v[160:163], v[194:197], v[92:95]
	v_mfma_f32_16x16x32_bf16 v[84:87], v[164:167], v[194:197], v[84:87]
	v_mfma_f32_16x16x32_bf16 v[60:63], v[160:163], v[198:201], v[60:63]
	ds_read_b128 v[160:163], v193 offset:15360
	v_mfma_f32_16x16x32_bf16 v[52:55], v[164:167], v[198:201], v[52:55]
	ds_read_b128 v[164:167], v193 offset:16640
	s_waitcnt lgkmcnt(1)
	v_mfma_f32_16x16x32_bf16 v[220:223], v[160:163], v[194:197], v[72:75]
	s_nop 2
	ds_read_b128 v[72:75], v193 offset:19200
	s_waitcnt lgkmcnt(1)
	v_mfma_f32_16x16x32_bf16 v[224:227], v[164:167], v[194:197], v[64:67]
	s_nop 2
	ds_read_b128 v[64:67], v193 offset:17920
	s_waitcnt lgkmcnt(1)
	v_mfma_f32_16x16x32_bf16 v[112:115], v[72:75], v[168:171], v[112:115]
	v_mfma_f32_16x16x32_bf16 v[80:83], v[72:75], v[172:175], v[80:83]
	v_mfma_f32_16x16x32_bf16 v[48:51], v[72:75], v[194:197], v[48:51]
	v_mfma_f32_16x16x32_bf16 v[202:205], v[160:163], v[168:171], v[132:135]
	v_mfma_f32_16x16x32_bf16 v[206:209], v[164:167], v[168:171], v[128:131]
	v_mfma_f32_16x16x32_bf16 v[212:215], v[160:163], v[172:175], v[104:107]
	v_mfma_f32_16x16x32_bf16 v[216:219], v[164:167], v[172:175], v[96:99]
	v_mfma_f32_16x16x32_bf16 v[28:31], v[160:163], v[198:201], v[28:31]
	v_mfma_f32_16x16x32_bf16 v[24:27], v[164:167], v[198:201], v[24:27]
	s_waitcnt lgkmcnt(0)
	v_mfma_f32_16x16x32_bf16 v[228:231], v[64:67], v[168:171], v[120:123]
	v_mfma_f32_16x16x32_bf16 v[232:235], v[64:67], v[172:175], v[88:91]
	v_mfma_f32_16x16x32_bf16 v[236:239], v[64:67], v[194:197], v[56:59]
	v_mfma_f32_16x16x32_bf16 v[20:23], v[64:67], v[198:201], v[20:23]
	v_mfma_f32_16x16x32_bf16 v[16:19], v[72:75], v[198:201], v[16:19]
	s_setprio 0
	s_barrier
; #define G_LOAD(kt_) do { \
;     if constexpr (AF32) { _Pragma("unroll") for (int i = 0; i < 4; ++i) ld16_sc1(ra[i], Af + (size_t)i * 32 * lda + (kt_) * 32); } \
;     else { _Pragma("unroll") for (int i = 0; i < 2; ++i) ld16_sc1(rab[i], Ab + (size_t)i * 64 * lda + (kt_) * 32); } \
;     _Pragma("unroll") for (int i = 0; i < 4; ++i) ld16_sc1(rb[i], Bp + (size_t)(kt_) * bstep + i * 2048); } while (0)
; template <bool AF32, class Epi>
; __device__ __forceinline__ void gemm_tile(unsigned char* smem, const void* Ap, int lda, const bf16_t* WT, int N, int K, const Epi& epi, int m0, int n0,
;                                           GPre& pr, bool preloaded, const void* nAp, int nn0, bool has_next) {
;     ...
;   for (int kt = 0; kt < nk; ++kt) {
;     const int cur = kt & 1;
;     if (kt + 1 < nk) G_STORE(cur ^ 1);
;     if (kt + 2 < nk) G_LOAD(kt + 2);
;     const bf16_t* a_s = sbase + cur * G_STAGE + (wr * 64 + l15) * GLD + quad * 8;
;     const bf16_t* b_s = sbase + cur * G_STAGE + 128 * GLD + (wc * 128 + l15) * GLD + quad * 8;
;     __builtin_amdgcn_s_setprio(1);
;     bf16x8 af[4];
; #pragma unroll
;     for (int m = 0; m < 4; ++m) af[m] = *(const bf16x8*)(a_s + m * 16 * GLD);
; #pragma unroll
;     for (int nh = 0; nh < 4; ++nh) {
;       bf16x8 bfr[2];
; #pragma unroll
;       for (int n2 = 0; n2 < 2; ++n2) bfr[n2] = *(const bf16x8*)(b_s + (nh * 2 + n2) * 16 * GLD);
; #pragma unroll
;       for (int m = 0; m < 4; ++m)
; #pragma unroll
;         for (int n2 = 0; n2 < 2; ++n2) acc[m][nh * 2 + n2] = __builtin_amdgcn_mfma_f32_16x16x32_bf16(bfr[n2], af[m], acc[m][nh * 2 + n2], 0, 0, 0);
;     }
;     __builtin_amdgcn_s_setprio(0);
;     __syncthreads();
;   }
;   if (has_next) {
;     const float* Af = (const float*)nAp + (size_t)(tid >> 3) * lda + (tid & 7) * 4;
;     const bf16_t* Ab = (const bf16_t*)nAp + (size_t)(tid >> 2) * lda + (tid & 3) * 8;
;     const bf16_t* Bp = WT + (size_t)nn0 * 32 + tid * 8;
;     G_LOAD(0);
;   }
	s_setprio 1
	ds_read_b128 v[56:59], v193 offset:40960
	ds_read_b128 v[64:67], v193 offset:42240
	ds_read_b128 v[194:197], v176 offset:30720
	ds_read_b128 v[198:201], v176 offset:32000
	ds_read_b128 v[240:243], v176 offset:33280
	ds_read_b128 v[244:247], v176 offset:34560
	s_waitcnt lgkmcnt(3)
	v_mfma_f32_16x16x32_bf16 v[172:175], v[56:59], v[194:197], v[156:159]
	v_mfma_f32_16x16x32_bf16 v[168:171], v[64:67], v[194:197], v[152:155]
	s_waitcnt lgkmcnt(2)
	v_mfma_f32_16x16x32_bf16 v[140:143], v[56:59], v[198:201], v[140:143]
	v_mfma_f32_16x16x32_bf16 v[136:139], v[64:67], v[198:201], v[136:139]
	s_waitcnt lgkmcnt(1)
	v_mfma_f32_16x16x32_bf16 v[108:111], v[56:59], v[240:243], v[108:111]
	v_mfma_f32_16x16x32_bf16 v[104:107], v[64:67], v[240:243], v[100:103]
	s_waitcnt lgkmcnt(0)
	v_mfma_f32_16x16x32_bf16 v[76:79], v[56:59], v[244:247], v[76:79]
	ds_read_b128 v[56:59], v193 offset:43520
	v_mfma_f32_16x16x32_bf16 v[72:75], v[64:67], v[244:247], v[68:71]
	ds_read_b128 v[64:67], v193 offset:44800
	s_waitcnt lgkmcnt(1)
	v_mfma_f32_16x16x32_bf16 v[164:167], v[56:59], v[194:197], v[148:151]
	s_waitcnt lgkmcnt(0)
	v_mfma_f32_16x16x32_bf16 v[160:163], v[64:67], v[194:197], v[144:147]
	v_mfma_f32_16x16x32_bf16 v[132:135], v[56:59], v[198:201], v[124:127]
	v_mfma_f32_16x16x32_bf16 v[128:131], v[64:67], v[198:201], v[116:119]
	v_mfma_f32_16x16x32_bf16 v[100:103], v[56:59], v[240:243], v[92:95]
	v_mfma_f32_16x16x32_bf16 v[96:99], v[64:67], v[240:243], v[84:87]
	v_mfma_f32_16x16x32_bf16 v[68:71], v[56:59], v[244:247], v[60:63]
	ds_read_b128 v[56:59], v193 offset:46080
	v_mfma_f32_16x16x32_bf16 v[64:67], v[64:67], v[244:247], v[52:55]
	s_nop 2
	ds_read_b128 v[52:55], v193 offset:47360
	s_waitcnt lgkmcnt(1)
	v_mfma_f32_16x16x32_bf16 v[156:159], v[56:59], v[194:197], v[202:205]
	v_mfma_f32_16x16x32_bf16 v[124:127], v[56:59], v[198:201], v[212:215]
	v_mfma_f32_16x16x32_bf16 v[92:95], v[56:59], v[240:243], v[220:223]
	v_mfma_f32_16x16x32_bf16 v[60:63], v[56:59], v[244:247], v[28:31]
	s_nop 2
	ds_read_b128 v[28:31], v193 offset:48640
	s_waitcnt lgkmcnt(1)
	v_mfma_f32_16x16x32_bf16 v[56:59], v[52:55], v[244:247], v[24:27]
	s_nop 2
	ds_read_b128 v[24:27], v193 offset:49920
	v_mfma_f32_16x16x32_bf16 v[152:155], v[52:55], v[194:197], v[206:209]
	v_mfma_f32_16x16x32_bf16 v[120:123], v[52:55], v[198:201], v[216:219]
	v_mfma_f32_16x16x32_bf16 v[88:91], v[52:55], v[240:243], v[224:227]
	s_waitcnt lgkmcnt(1)
	v_mfma_f32_16x16x32_bf16 v[148:151], v[28:31], v[194:197], v[228:231]
	s_waitcnt lgkmcnt(0)
	v_mfma_f32_16x16x32_bf16 v[144:147], v[24:27], v[194:197], v[112:115]
	v_mfma_f32_16x16x32_bf16 v[116:119], v[28:31], v[198:201], v[232:235]
	v_mfma_f32_16x16x32_bf16 v[112:115], v[24:27], v[198:201], v[80:83]
	v_mfma_f32_16x16x32_bf16 v[84:87], v[28:31], v[240:243], v[236:239]
	v_mfma_f32_16x16x32_bf16 v[80:83], v[24:27], v[240:243], v[48:51]
	v_mfma_f32_16x16x32_bf16 v[52:55], v[28:31], v[244:247], v[20:23]
	v_mfma_f32_16x16x32_bf16 v[48:51], v[24:27], v[244:247], v[16:19]
	s_and_b64 vcc, exec, s[6:7]
	s_barrier
	s_cbranch_vccz .LBB0_392
	s_ashr_i32 s51, s50, 31
	s_lshl_b64 s[6:7], s[50:51], 19
	s_add_u32 s6, s12, s6
	s_addc_u32 s7, s13, s7
	s_lshl_b32 s50, s67, 8
	v_lshl_add_u64 v[0:1], v[186:187], 2, s[6:7]
	v_lshlrev_b32_e32 v176, 2, v188
	s_ashr_i32 s51, s50, 31
	v_lshl_add_u64 v[0:1], v[0:1], 0, v[176:177]
	s_lshl_b64 s[6:7], s[50:51], 6
	global_load_dwordx4 v[24:27], v[0:1], off sc1
	s_add_u32 s6, s2, s6
	v_lshl_add_u64 v[2:3], v[0:1], 0, s[16:17]
	global_load_dwordx4 v[28:31], v[2:3], off sc1
	s_addc_u32 s7, s33, s7
	v_lshl_add_u64 v[2:3], v[0:1], 0, s[18:19]
	global_load_dwordx4 v[16:19], v[2:3], off sc1
	v_lshl_add_u64 v[0:1], v[0:1], 0, s[20:21]
	global_load_dwordx4 v[20:23], v[0:1], off sc1
	v_lshl_add_u64 v[12:13], v[182:183], 1, s[6:7]
	global_load_dwordx4 v[0:3], v[12:13], off sc1
	v_lshl_add_u64 v[4:5], v[12:13], 0, s[22:23]
	global_load_dwordx4 v[4:7], v[4:5], off sc1
	v_lshl_add_u64 v[8:9], v[12:13], 0, s[24:25]
	global_load_dwordx4 v[8:11], v[8:9], off sc1
	v_lshl_add_u64 v[12:13], v[12:13], 0, s[26:27]
	global_load_dwordx4 v[12:15], v[12:13], off sc1
	s_branch .LBB0_393

; #define G_LOAD(kt_) do { \
;     if constexpr (AF32) { _Pragma("unroll") for (int i = 0; i < 4; ++i) ld16_sc1(ra[i], Af + (size_t)i * 32 * lda + (kt_) * 32); } \
;     else { _Pragma("unroll") for (int i = 0; i < 2; ++i) ld16_sc1(rab[i], Ab + (size_t)i * 64 * lda + (kt_) * 32); } \
;     _Pragma("unroll") for (int i = 0; i < 4; ++i) ld16_sc1(rb[i], Bp + (size_t)(kt_) * bstep + i * 2048); } while (0)
; template <bool AF32, class Epi>
; __device__ __forceinline__ void gemm_tile(unsigned char* smem, const void* Ap, int lda, const bf16_t* WT, int N, int K, const Epi& epi, int m0, int n0,
;                                           GPre& pr, bool preloaded, const void* nAp, int nn0, bool has_next) {
;     ...
;   if (!preloaded) G_LOAD(0);
;   G_STORE(0);
;   if (nk > 1) G_LOAD(1);
;   __syncthreads();
;   for (int kt = 0; kt < nk; ++kt) {
;     const int cur = kt & 1;
;     if (kt + 1 < nk) G_STORE(cur ^ 1);
;     if (kt + 2 < nk) G_LOAD(kt + 2);
;     const bf16_t* a_s = sbase + cur * G_STAGE + (wr * 64 + l15) * GLD + quad * 8;
;     const bf16_t* b_s = sbase + cur * G_STAGE + 128 * GLD + (wc * 128 + l15) * GLD + quad * 8;
;     __builtin_amdgcn_s_setprio(1);
;     bf16x8 af[4];
; #pragma unroll
;     for (int m = 0; m < 4; ++m) af[m] = *(const bf16x8*)(a_s + m * 16 * GLD);
; #pragma unroll
;     for (int nh = 0; nh < 4; ++nh) {
;       bf16x8 bfr[2];
; #pragma unroll
;       for (int n2 = 0; n2 < 2; ++n2) bfr[n2] = *(const bf16x8*)(b_s + (nh * 2 + n2) * 16 * GLD);
; #pragma unroll
;       for (int m = 0; m < 4; ++m)
; #pragma unroll
;         for (int n2 = 0; n2 < 2; ++n2) acc[m][nh * 2 + n2] = __builtin_amdgcn_mfma_f32_16x16x32_bf16(bfr[n2], af[m], acc[m][nh * 2 + n2], 0, 0, 0);
;     }
;     __builtin_amdgcn_s_setprio(0);
;     __syncthreads();
;   }
.LBB0_429:
	s_and_b32 s3, s52, 1
	s_waitcnt vmcnt(0)
	s_xor_b32 s53, s3, 1
	s_mulk_i32 s53, 0x7800
	v_add_u32_e32 v176, s53, v155
	ds_write_b128 v176, v[0:3]
	ds_write_b128 v176, v[4:7] offset:5120
	ds_write_b128 v176, v[8:11] offset:10240
	ds_write_b128 v176, v[12:15] offset:15360
	ds_write_b128 v176, v[16:19] offset:20480
	ds_write_b128 v176, v[20:23] offset:25600
	s_setprio 2
	global_load_dwordx4 v[0:3], v[162:163], off sc1
	v_lshl_add_u64 v[168:169], v[162:163], 0, s[12:13]
	global_load_dwordx4 v[4:7], v[168:169], off sc1
	global_load_dwordx4 v[8:11], v[160:161], off sc1
	v_lshl_add_u64 v[170:171], v[160:161], 0, s[14:15]
	global_load_dwordx4 v[12:15], v[170:171], off sc1
	v_lshl_add_u64 v[172:173], v[160:161], 0, s[16:17]
	global_load_dwordx4 v[16:19], v[172:173], off sc1
	v_lshl_add_u64 v[174:175], v[160:161], 0, s[18:19]
	global_load_dwordx4 v[20:23], v[174:175], off sc1
	s_setprio 0
	s_add_i32 s52, s52, 1
	s_mulk_i32 s3, 0x7800
	v_add3_u32 v188, s3, v166, v167
	s_setprio 1
	v_add3_u32 v192, s3, v165, v167
	ds_read_b128 v[168:171], v192 offset:10240
	ds_read_b128 v[172:175], v192 offset:11520
	ds_read_b128 v[176:179], v188
	ds_read_b128 v[180:183], v188 offset:1280
	ds_read_b128 v[184:187], v188 offset:2560
	ds_read_b128 v[188:191], v188 offset:3840
	s_waitcnt lgkmcnt(3)
	v_mfma_f32_16x16x32_bf16 v[148:151], v[168:171], v[176:179], v[148:151]
	v_mfma_f32_16x16x32_bf16 v[144:147], v[172:175], v[176:179], v[144:147]
	s_waitcnt lgkmcnt(2)
	v_mfma_f32_16x16x32_bf16 v[132:135], v[168:171], v[180:183], v[132:135]
	v_mfma_f32_16x16x32_bf16 v[128:131], v[172:175], v[180:183], v[128:131]
	s_waitcnt lgkmcnt(1)
	v_mfma_f32_16x16x32_bf16 v[100:103], v[168:171], v[184:187], v[100:103]
	v_mfma_f32_16x16x32_bf16 v[92:95], v[172:175], v[184:187], v[92:95]
	s_waitcnt lgkmcnt(0)
	v_mfma_f32_16x16x32_bf16 v[68:71], v[168:171], v[188:191], v[68:71]
	ds_read_b128 v[168:171], v192 offset:12800
	v_mfma_f32_16x16x32_bf16 v[60:63], v[172:175], v[188:191], v[60:63]
	ds_read_b128 v[172:175], v192 offset:14080
	s_waitcnt lgkmcnt(1)
	v_mfma_f32_16x16x32_bf16 v[140:143], v[168:171], v[176:179], v[140:143]
	s_waitcnt lgkmcnt(0)
	v_mfma_f32_16x16x32_bf16 v[136:139], v[172:175], v[176:179], v[136:139]
	v_mfma_f32_16x16x32_bf16 v[116:119], v[168:171], v[180:183], v[116:119]
	v_mfma_f32_16x16x32_bf16 v[108:111], v[172:175], v[180:183], v[108:111]
	v_mfma_f32_16x16x32_bf16 v[84:87], v[168:171], v[184:187], v[84:87]
	v_mfma_f32_16x16x32_bf16 v[76:79], v[172:175], v[184:187], v[76:79]
	v_mfma_f32_16x16x32_bf16 v[52:55], v[168:171], v[188:191], v[52:55]
	ds_read_b128 v[168:171], v192 offset:15360
	v_mfma_f32_16x16x32_bf16 v[44:47], v[172:175], v[188:191], v[44:47]
	ds_read_b128 v[172:175], v192 offset:16640
	s_waitcnt lgkmcnt(1)
	v_mfma_f32_16x16x32_bf16 v[124:127], v[168:171], v[176:179], v[124:127]
	s_waitcnt lgkmcnt(0)
	v_mfma_f32_16x16x32_bf16 v[120:123], v[172:175], v[176:179], v[120:123]
	v_mfma_f32_16x16x32_bf16 v[96:99], v[168:171], v[180:183], v[96:99]
	v_mfma_f32_16x16x32_bf16 v[88:91], v[172:175], v[180:183], v[88:91]
	v_mfma_f32_16x16x32_bf16 v[64:67], v[168:171], v[184:187], v[64:67]
	v_mfma_f32_16x16x32_bf16 v[56:59], v[172:175], v[184:187], v[56:59]
	v_mfma_f32_16x16x32_bf16 v[36:39], v[168:171], v[188:191], v[36:39]
	ds_read_b128 v[168:171], v192 offset:17920
	v_mfma_f32_16x16x32_bf16 v[32:35], v[172:175], v[188:191], v[32:35]
	ds_read_b128 v[172:175], v192 offset:19200
	s_waitcnt lgkmcnt(1)
	v_mfma_f32_16x16x32_bf16 v[112:115], v[168:171], v[176:179], v[112:115]
	s_waitcnt lgkmcnt(0)
	v_mfma_f32_16x16x32_bf16 v[104:107], v[172:175], v[176:179], v[104:107]
	v_mfma_f32_16x16x32_bf16 v[80:83], v[168:171], v[180:183], v[80:83]
	v_mfma_f32_16x16x32_bf16 v[72:75], v[172:175], v[180:183], v[72:75]
	v_mfma_f32_16x16x32_bf16 v[48:51], v[168:171], v[184:187], v[48:51]
	v_mfma_f32_16x16x32_bf16 v[40:43], v[172:175], v[184:187], v[40:43]
	v_mfma_f32_16x16x32_bf16 v[28:31], v[168:171], v[188:191], v[28:31]
	v_mfma_f32_16x16x32_bf16 v[24:27], v[172:175], v[188:191], v[24:27]
	s_setprio 0
	v_lshl_add_u64 v[160:161], v[160:161], 0, s[22:23]
	s_cmpk_eq_i32 s52, 0x56
	v_lshl_add_u64 v[162:163], v[162:163], 0, 64
	s_barrier
	s_cbranch_scc0 .LBB0_429
	s_waitcnt vmcnt(0)
	ds_write_b128 v155, v[0:3] offset:30720
	ds_write_b128 v155, v[4:7] offset:35840
	ds_write_b128 v155, v[8:11] offset:40960
	ds_write_b128 v155, v[12:15] offset:46080
	ds_write_b128 v155, v[16:19] offset:51200
	ds_write_b128 v155, v[20:23] offset:56320
	v_add_u32_e32 v155, v166, v167
	s_setprio 1
	v_add_u32_e32 v165, v165, v167
	ds_read_b128 v[160:163], v165 offset:10240
	ds_read_b128 v[166:169], v165 offset:11520
	ds_read_b128 v[170:173], v155
	ds_read_b128 v[174:177], v155 offset:1280
	ds_read_b128 v[178:181], v155 offset:2560
	ds_read_b128 v[182:185], v155 offset:3840
	s_waitcnt lgkmcnt(3)
	v_mfma_f32_16x16x32_bf16 v[148:151], v[160:163], v[170:173], v[148:151]
	v_mfma_f32_16x16x32_bf16 v[144:147], v[166:169], v[170:173], v[144:147]
	s_waitcnt lgkmcnt(2)
	v_mfma_f32_16x16x32_bf16 v[132:135], v[160:163], v[174:177], v[132:135]
	v_mfma_f32_16x16x32_bf16 v[128:131], v[166:169], v[174:177], v[128:131]
	s_waitcnt lgkmcnt(1)
	v_mfma_f32_16x16x32_bf16 v[100:103], v[160:163], v[178:181], v[100:103]
	v_mfma_f32_16x16x32_bf16 v[92:95], v[166:169], v[178:181], v[92:95]
	s_waitcnt lgkmcnt(0)
	v_mfma_f32_16x16x32_bf16 v[68:71], v[160:163], v[182:185], v[68:71]
	ds_read_b128 v[160:163], v165 offset:12800
	v_mfma_f32_16x16x32_bf16 v[60:63], v[166:169], v[182:185], v[60:63]
	ds_read_b128 v[166:169], v165 offset:14080
	s_waitcnt lgkmcnt(1)
	v_mfma_f32_16x16x32_bf16 v[186:189], v[160:163], v[170:173], v[140:143]
	s_waitcnt lgkmcnt(0)
; #define G_LOAD(kt_) do { \
;     if constexpr (AF32) { _Pragma("unroll") for (int i = 0; i < 4; ++i) ld16_sc1(ra[i], Af + (size_t)i * 32 * lda + (kt_) * 32); } \
;     else { _Pragma("unroll") for (int i = 0; i < 2; ++i) ld16_sc1(rab[i], Ab + (size_t)i * 64 * lda + (kt_) * 32); } \
;     _Pragma("unroll") for (int i = 0; i < 4; ++i) ld16_sc1(rb[i], Bp + (size_t)(kt_) * bstep + i * 2048); } while (0)
; template <bool AF32, class Epi>
; __device__ __forceinline__ void gemm_tile(unsigned char* smem, const void* Ap, int lda, const bf16_t* WT, int N, int K, const Epi& epi, int m0, int n0,
;                                           GPre& pr, bool preloaded, const void* nAp, int nn0, bool has_next) {
;     ...
;   for (int kt = 0; kt < nk; ++kt) {
;     const int cur = kt & 1;
;     if (kt + 1 < nk) G_STORE(cur ^ 1);
;     if (kt + 2 < nk) G_LOAD(kt + 2);
;     const bf16_t* a_s = sbase + cur * G_STAGE + (wr * 64 + l15) * GLD + quad * 8;
;     const bf16_t* b_s = sbase + cur * G_STAGE + 128 * GLD + (wc * 128 + l15) * GLD + quad * 8;
;     __builtin_amdgcn_s_setprio(1);
;     bf16x8 af[4];
; #pragma unroll
;     for (int m = 0; m < 4; ++m) af[m] = *(const bf16x8*)(a_s + m * 16 * GLD);
; #pragma unroll
;     for (int nh = 0; nh < 4; ++nh) {
;       bf16x8 bfr[2];
; #pragma unroll
;       for (int n2 = 0; n2 < 2; ++n2) bfr[n2] = *(const bf16x8*)(b_s + (nh * 2 + n2) * 16 * GLD);
; #pragma unroll
;       for (int m = 0; m < 4; ++m)
; #pragma unroll
;         for (int n2 = 0; n2 < 2; ++n2) acc[m][nh * 2 + n2] = __builtin_amdgcn_mfma_f32_16x16x32_bf16(bfr[n2], af[m], acc[m][nh * 2 + n2], 0, 0, 0);
;     }
;     __builtin_amdgcn_s_setprio(0);
;     __syncthreads();
;   }
;   if (has_next) {
;     const float* Af = (const float*)nAp + (size_t)(tid >> 3) * lda + (tid & 7) * 4;
;     const bf16_t* Ab = (const bf16_t*)nAp + (size_t)(tid >> 2) * lda + (tid & 3) * 8;
;     const bf16_t* Bp = WT + (size_t)nn0 * 32 + tid * 8;
;     G_LOAD(0);
;   }
	v_mfma_f32_16x16x32_bf16 v[136:139], v[166:169], v[170:173], v[136:139]
	v_mfma_f32_16x16x32_bf16 v[190:193], v[160:163], v[174:177], v[116:119]
	v_mfma_f32_16x16x32_bf16 v[194:197], v[166:169], v[174:177], v[108:111]
	v_mfma_f32_16x16x32_bf16 v[198:201], v[160:163], v[178:181], v[84:87]
	v_mfma_f32_16x16x32_bf16 v[202:205], v[166:169], v[178:181], v[76:79]
	v_mfma_f32_16x16x32_bf16 v[160:163], v[160:163], v[182:185], v[52:55]
	s_nop 2
	ds_read_b128 v[52:55], v165 offset:15360
	v_mfma_f32_16x16x32_bf16 v[166:169], v[166:169], v[182:185], v[44:47]
	s_nop 2
	ds_read_b128 v[44:47], v165 offset:16640
	s_waitcnt lgkmcnt(1)
	v_mfma_f32_16x16x32_bf16 v[124:127], v[52:55], v[170:173], v[124:127]
	s_waitcnt lgkmcnt(0)
	v_mfma_f32_16x16x32_bf16 v[120:123], v[44:47], v[170:173], v[120:123]
	v_mfma_f32_16x16x32_bf16 v[96:99], v[52:55], v[174:177], v[96:99]
	v_mfma_f32_16x16x32_bf16 v[88:91], v[44:47], v[174:177], v[88:91]
	v_mfma_f32_16x16x32_bf16 v[64:67], v[52:55], v[178:181], v[64:67]
	v_mfma_f32_16x16x32_bf16 v[56:59], v[44:47], v[178:181], v[56:59]
	v_mfma_f32_16x16x32_bf16 v[36:39], v[52:55], v[182:185], v[36:39]
	ds_read_b128 v[52:55], v165 offset:17920
	v_mfma_f32_16x16x32_bf16 v[32:35], v[44:47], v[182:185], v[32:35]
	ds_read_b128 v[44:47], v165 offset:19200
	s_waitcnt lgkmcnt(1)
	v_mfma_f32_16x16x32_bf16 v[28:31], v[52:55], v[182:185], v[28:31]
	s_waitcnt lgkmcnt(0)
	v_mfma_f32_16x16x32_bf16 v[24:27], v[44:47], v[182:185], v[24:27]
	v_mfma_f32_16x16x32_bf16 v[206:209], v[52:55], v[170:173], v[112:115]
	v_mfma_f32_16x16x32_bf16 v[170:173], v[44:47], v[170:173], v[104:107]
	v_mfma_f32_16x16x32_bf16 v[212:215], v[52:55], v[174:177], v[80:83]
	v_mfma_f32_16x16x32_bf16 v[174:177], v[44:47], v[174:177], v[72:75]
	v_mfma_f32_16x16x32_bf16 v[216:219], v[52:55], v[178:181], v[48:51]
	v_mfma_f32_16x16x32_bf16 v[178:181], v[44:47], v[178:181], v[40:43]
	s_setprio 0
	s_barrier
	s_setprio 1
	ds_read_b128 v[40:43], v165 offset:40960
	ds_read_b128 v[44:47], v165 offset:42240
	ds_read_b128 v[182:185], v155 offset:30720
	ds_read_b128 v[220:223], v155 offset:32000
	ds_read_b128 v[224:227], v155 offset:33280
	ds_read_b128 v[228:231], v155 offset:34560
	s_waitcnt lgkmcnt(3)
	v_mfma_f32_16x16x32_bf16 v[148:151], v[40:43], v[182:185], v[148:151]
	s_waitcnt lgkmcnt(2)
	v_mfma_f32_16x16x32_bf16 v[116:119], v[40:43], v[220:223], v[132:135]
	s_waitcnt lgkmcnt(1)
	v_mfma_f32_16x16x32_bf16 v[84:87], v[40:43], v[224:227], v[100:103]
	s_waitcnt lgkmcnt(0)
	v_mfma_f32_16x16x32_bf16 v[52:55], v[40:43], v[228:231], v[68:71]
	ds_read_b128 v[40:43], v165 offset:43520
	v_mfma_f32_16x16x32_bf16 v[48:51], v[44:47], v[228:231], v[60:63]
	s_nop 2
	ds_read_b128 v[60:63], v165 offset:44800
	v_mfma_f32_16x16x32_bf16 v[140:143], v[44:47], v[182:185], v[144:147]
	v_mfma_f32_16x16x32_bf16 v[108:111], v[44:47], v[220:223], v[128:131]
	v_mfma_f32_16x16x32_bf16 v[80:83], v[44:47], v[224:227], v[92:95]
	s_waitcnt lgkmcnt(1)
	v_mfma_f32_16x16x32_bf16 v[144:147], v[40:43], v[182:185], v[186:189]
	s_nop 0
	ds_read_b128 v[92:95], v165 offset:46080
	s_waitcnt lgkmcnt(1)
	v_mfma_f32_16x16x32_bf16 v[136:139], v[60:63], v[182:185], v[136:139]
	v_mfma_f32_16x16x32_bf16 v[112:115], v[40:43], v[220:223], v[190:193]
	v_mfma_f32_16x16x32_bf16 v[104:107], v[60:63], v[220:223], v[194:197]
	v_mfma_f32_16x16x32_bf16 v[76:79], v[40:43], v[224:227], v[198:201]
	v_mfma_f32_16x16x32_bf16 v[72:75], v[60:63], v[224:227], v[202:205]
	v_mfma_f32_16x16x32_bf16 v[44:47], v[40:43], v[228:231], v[160:163]
	v_mfma_f32_16x16x32_bf16 v[40:43], v[60:63], v[228:231], v[166:169]
	ds_read_b128 v[60:63], v165 offset:47360
	s_nop 0
	ds_read_b128 v[160:163], v165 offset:48640
	ds_read_b128 v[166:169], v165 offset:49920
	s_waitcnt lgkmcnt(3)
	v_mfma_f32_16x16x32_bf16 v[132:135], v[92:95], v[182:185], v[124:127]
	s_waitcnt lgkmcnt(2)
	v_mfma_f32_16x16x32_bf16 v[128:131], v[60:63], v[182:185], v[120:123]
	v_mfma_f32_16x16x32_bf16 v[100:103], v[92:95], v[220:223], v[96:99]
	v_mfma_f32_16x16x32_bf16 v[96:99], v[60:63], v[220:223], v[88:91]
	v_mfma_f32_16x16x32_bf16 v[68:71], v[92:95], v[224:227], v[64:67]
	v_mfma_f32_16x16x32_bf16 v[64:67], v[60:63], v[224:227], v[56:59]
	v_mfma_f32_16x16x32_bf16 v[36:39], v[92:95], v[228:231], v[36:39]
	v_mfma_f32_16x16x32_bf16 v[32:35], v[60:63], v[228:231], v[32:35]
	s_waitcnt lgkmcnt(1)
	v_mfma_f32_16x16x32_bf16 v[124:127], v[160:163], v[182:185], v[206:209]
	s_waitcnt lgkmcnt(0)
	v_mfma_f32_16x16x32_bf16 v[120:123], v[166:169], v[182:185], v[170:173]
	v_mfma_f32_16x16x32_bf16 v[92:95], v[160:163], v[220:223], v[212:215]
	v_mfma_f32_16x16x32_bf16 v[88:91], v[166:169], v[220:223], v[174:177]
	v_mfma_f32_16x16x32_bf16 v[60:63], v[160:163], v[224:227], v[216:219]
	v_mfma_f32_16x16x32_bf16 v[56:59], v[166:169], v[224:227], v[178:181]
	v_mfma_f32_16x16x32_bf16 v[28:31], v[160:163], v[228:231], v[28:31]
	v_mfma_f32_16x16x32_bf16 v[24:27], v[166:169], v[228:231], v[24:27]
	s_and_b64 vcc, exec, s[48:49]
	s_barrier
	s_cbranch_vccz .LBB0_417
	s_mul_i32 s48, s69, 0xb0000
	s_mul_hi_i32 s3, s69, 0xb0000
	s_add_u32 s48, s2, s48
	s_addc_u32 s49, s33, s3
	s_lshl_b32 s52, s68, 8
	s_ashr_i32 s53, s52, 31
	v_lshl_add_u64 v[0:1], v[158:159], 1, s[48:49]
	s_lshl_b64 s[48:49], s[52:53], 6
	v_lshl_add_u64 v[4:5], v[0:1], 0, v[152:153]
	s_add_u32 s48, s56, s48
	s_addc_u32 s49, s57, s49
	global_load_dwordx4 v[0:3], v[4:5], off sc1
	v_lshl_add_u64 v[4:5], v[4:5], 0, s[12:13]
	global_load_dwordx4 v[4:7], v[4:5], off sc1
	v_lshl_add_u64 v[20:21], v[156:157], 1, s[48:49]
	global_load_dwordx4 v[8:11], v[20:21], off sc1
	v_lshl_add_u64 v[12:13], v[20:21], 0, s[14:15]
	global_load_dwordx4 v[12:15], v[12:13], off sc1
	v_lshl_add_u64 v[16:17], v[20:21], 0, s[16:17]
	global_load_dwordx4 v[16:19], v[16:17], off sc1
	v_lshl_add_u64 v[20:21], v[20:21], 0, s[18:19]
	global_load_dwordx4 v[20:23], v[20:21], off sc1
	s_branch .LBB0_417

; #define G_LOAD(kt_) do { \
;     if constexpr (AF32) { _Pragma("unroll") for (int i = 0; i < 4; ++i) ld16_sc1(ra[i], Af + (size_t)i * 32 * lda + (kt_) * 32); } \
;     else { _Pragma("unroll") for (int i = 0; i < 2; ++i) ld16_sc1(rab[i], Ab + (size_t)i * 64 * lda + (kt_) * 32); } \
;     _Pragma("unroll") for (int i = 0; i < 4; ++i) ld16_sc1(rb[i], Bp + (size_t)(kt_) * bstep + i * 2048); } while (0)
; template <bool AF32, class Epi>
; __device__ __forceinline__ void gemm_tile(unsigned char* smem, const void* Ap, int lda, const bf16_t* WT, int N, int K, const Epi& epi, int m0, int n0,
;                                           GPre& pr, bool preloaded, const void* nAp, int nn0, bool has_next) {
;     ...
;   if (!preloaded) G_LOAD(0);
;   G_STORE(0);
;   if (nk > 1) G_LOAD(1);
;   __syncthreads();
;   for (int kt = 0; kt < nk; ++kt) {
;     const int cur = kt & 1;
;     if (kt + 1 < nk) G_STORE(cur ^ 1);
;     if (kt + 2 < nk) G_LOAD(kt + 2);
;     const bf16_t* a_s = sbase + cur * G_STAGE + (wr * 64 + l15) * GLD + quad * 8;
;     const bf16_t* b_s = sbase + cur * G_STAGE + 128 * GLD + (wc * 128 + l15) * GLD + quad * 8;
;     __builtin_amdgcn_s_setprio(1);
;     bf16x8 af[4];
; #pragma unroll
;     for (int m = 0; m < 4; ++m) af[m] = *(const bf16x8*)(a_s + m * 16 * GLD);
; #pragma unroll
;     for (int nh = 0; nh < 4; ++nh) {
;       bf16x8 bfr[2];
; #pragma unroll
;       for (int n2 = 0; n2 < 2; ++n2) bfr[n2] = *(const bf16x8*)(b_s + (nh * 2 + n2) * 16 * GLD);
; #pragma unroll
;       for (int m = 0; m < 4; ++m)
; #pragma unroll
;         for (int n2 = 0; n2 < 2; ++n2) acc[m][nh * 2 + n2] = __builtin_amdgcn_mfma_f32_16x16x32_bf16(bfr[n2], af[m], acc[m][nh * 2 + n2], 0, 0, 0);
;     }
;     __builtin_amdgcn_s_setprio(0);
;     __syncthreads();
;   }
.LBB0_460:
	s_and_b32 s3, s51, 1
	s_waitcnt vmcnt(0)
	s_xor_b32 s53, s3, 1
	s_mulk_i32 s53, 0x7800
	v_cvt_pk_bf16_f32 v202, v28, v29
	v_mov_b32_e32 v205, v28
	v_mov_b32_e32 v28, v25
	v_lshl_add_u32 v171, v160, 1, s53
	v_cvt_pk_bf16_f32 v203, v30, v31
	v_mov_b32_e32 v204, v24
	v_mov_b32_e32 v206, v26
	v_mov_b32_e32 v207, v30
	v_mov_b32_e32 v30, v27
	v_cvt_pk_bf16_f32 v24, v24, v25
	v_cvt_pk_bf16_f32 v25, v26, v27
	v_cvt_pk_bf16_f32 v26, v20, v21
	v_cvt_pk_bf16_f32 v27, v22, v23
	v_mov_b32_e32 v208, v16
	v_mov_b32_e32 v209, v20
	v_mov_b32_e32 v20, v17
	v_mov_b32_e32 v212, v18
	v_mov_b32_e32 v213, v22
	v_mov_b32_e32 v22, v19
	v_cvt_pk_bf16_f32 v16, v16, v17
	v_cvt_pk_bf16_f32 v17, v18, v19
	v_pk_mul_f32 v[18:19], v[28:29], v[28:29]
	v_lshl_add_u32 v176, v162, 1, s53
	ds_write2st64_b64 v171, v[202:203], v[24:25] offset1:5
	ds_write2st64_b64 v171, v[26:27], v[16:17] offset0:10 offset1:15
	ds_write_b128 v176, v[0:3] offset:10240
	ds_write_b128 v176, v[4:7] offset:15360
	ds_write_b128 v176, v[8:11] offset:20480
	ds_write_b128 v176, v[12:15] offset:25600
	v_pk_fma_f32 v[0:1], v[204:205], v[204:205], v[18:19]
	v_pk_mul_f32 v[20:21], v[20:21], v[20:21]
	v_pk_fma_f32 v[0:1], v[206:207], v[206:207], v[0:1]
	v_pk_fma_f32 v[2:3], v[208:209], v[208:209], v[20:21]
	v_pk_fma_f32 v[202:203], v[30:31], v[30:31], v[0:1]
	s_setprio 2
	global_load_dwordx4 v[28:31], v[166:167], off sc1
	v_lshl_add_u64 v[172:173], v[166:167], 0, s[16:17]
	v_pk_fma_f32 v[2:3], v[212:213], v[212:213], v[2:3]
	global_load_dwordx4 v[24:27], v[172:173], off sc1
	v_lshl_add_u64 v[174:175], v[166:167], 0, s[18:19]
	v_pk_fma_f32 v[204:205], v[22:23], v[22:23], v[2:3]
	global_load_dwordx4 v[20:23], v[174:175], off sc1
	v_lshl_add_u64 v[194:195], v[166:167], 0, s[20:21]
	global_load_dwordx4 v[16:19], v[194:195], off sc1
	global_load_dwordx4 v[0:3], v[164:165], off sc1
	v_lshl_add_u64 v[196:197], v[164:165], 0, s[22:23]
	global_load_dwordx4 v[4:7], v[196:197], off sc1
	v_lshl_add_u64 v[198:199], v[164:165], 0, s[24:25]
	global_load_dwordx4 v[8:11], v[198:199], off sc1
	v_lshl_add_u64 v[200:201], v[164:165], 0, s[26:27]
	global_load_dwordx4 v[12:15], v[200:201], off sc1
	s_setprio 0
	s_add_i32 s51, s51, 1
	s_mulk_i32 s3, 0x7800
	v_pk_add_f32 v[186:187], v[186:187], v[202:203]
	v_pk_add_f32 v[182:183], v[182:183], v[204:205]
	v_add3_u32 v171, s3, v169, v170
	s_setprio 1
	v_add3_u32 v176, s3, v168, v170
	ds_read_b128 v[172:175], v176 offset:10240
	ds_read_b128 v[194:197], v176 offset:11520
	ds_read_b128 v[198:201], v171
	ds_read_b128 v[202:205], v171 offset:1280
	ds_read_b128 v[206:209], v171 offset:2560
	ds_read_b128 v[212:215], v171 offset:3840
	s_waitcnt lgkmcnt(3)
	v_mfma_f32_16x16x32_bf16 v[156:159], v[172:175], v[198:201], v[156:159]
	v_mfma_f32_16x16x32_bf16 v[152:155], v[194:197], v[198:201], v[152:155]
	s_waitcnt lgkmcnt(2)
	v_mfma_f32_16x16x32_bf16 v[140:143], v[172:175], v[202:205], v[140:143]
	v_mfma_f32_16x16x32_bf16 v[136:139], v[194:197], v[202:205], v[136:139]
	s_waitcnt lgkmcnt(1)
	v_mfma_f32_16x16x32_bf16 v[108:111], v[172:175], v[206:209], v[108:111]
	v_mfma_f32_16x16x32_bf16 v[100:103], v[194:197], v[206:209], v[100:103]
	s_waitcnt lgkmcnt(0)
	v_mfma_f32_16x16x32_bf16 v[76:79], v[172:175], v[212:215], v[76:79]
	ds_read_b128 v[172:175], v176 offset:12800
	v_mfma_f32_16x16x32_bf16 v[68:71], v[194:197], v[212:215], v[68:71]
	ds_read_b128 v[194:197], v176 offset:14080
	s_waitcnt lgkmcnt(1)
	v_mfma_f32_16x16x32_bf16 v[148:151], v[172:175], v[198:201], v[148:151]
	s_waitcnt lgkmcnt(0)
	v_mfma_f32_16x16x32_bf16 v[144:147], v[194:197], v[198:201], v[144:147]
	v_mfma_f32_16x16x32_bf16 v[124:127], v[172:175], v[202:205], v[124:127]
	v_mfma_f32_16x16x32_bf16 v[116:119], v[194:197], v[202:205], v[116:119]
	v_mfma_f32_16x16x32_bf16 v[92:95], v[172:175], v[206:209], v[92:95]
	v_mfma_f32_16x16x32_bf16 v[84:87], v[194:197], v[206:209], v[84:87]
	v_mfma_f32_16x16x32_bf16 v[60:63], v[172:175], v[212:215], v[60:63]
	ds_read_b128 v[172:175], v176 offset:15360
	v_mfma_f32_16x16x32_bf16 v[52:55], v[194:197], v[212:215], v[52:55]
	ds_read_b128 v[194:197], v176 offset:16640
	s_waitcnt lgkmcnt(1)
	v_mfma_f32_16x16x32_bf16 v[132:135], v[172:175], v[198:201], v[132:135]
	s_waitcnt lgkmcnt(0)
	v_mfma_f32_16x16x32_bf16 v[128:131], v[194:197], v[198:201], v[128:131]
	v_mfma_f32_16x16x32_bf16 v[104:107], v[172:175], v[202:205], v[104:107]
	v_mfma_f32_16x16x32_bf16 v[96:99], v[194:197], v[202:205], v[96:99]
	v_mfma_f32_16x16x32_bf16 v[72:75], v[172:175], v[206:209], v[72:75]
	v_mfma_f32_16x16x32_bf16 v[64:67], v[194:197], v[206:209], v[64:67]
	v_mfma_f32_16x16x32_bf16 v[44:47], v[172:175], v[212:215], v[44:47]
	ds_read_b128 v[172:175], v176 offset:17920
	v_mfma_f32_16x16x32_bf16 v[40:43], v[194:197], v[212:215], v[40:43]
	ds_read_b128 v[194:197], v176 offset:19200
	s_waitcnt lgkmcnt(1)
	v_mfma_f32_16x16x32_bf16 v[120:123], v[172:175], v[198:201], v[120:123]
	s_waitcnt lgkmcnt(0)
	v_mfma_f32_16x16x32_bf16 v[112:115], v[194:197], v[198:201], v[112:115]
	v_mfma_f32_16x16x32_bf16 v[88:91], v[172:175], v[202:205], v[88:91]
	v_mfma_f32_16x16x32_bf16 v[80:83], v[194:197], v[202:205], v[80:83]
	v_mfma_f32_16x16x32_bf16 v[56:59], v[172:175], v[206:209], v[56:59]
	v_mfma_f32_16x16x32_bf16 v[48:51], v[194:197], v[206:209], v[48:51]
	v_mfma_f32_16x16x32_bf16 v[36:39], v[172:175], v[212:215], v[36:39]
	v_mfma_f32_16x16x32_bf16 v[32:35], v[194:197], v[212:215], v[32:35]
	s_setprio 0
	v_lshl_add_u64 v[164:165], v[164:165], 0, s[38:39]
	s_cmp_eq_u32 s51, 30
	v_lshl_add_u64 v[166:167], v[166:167], 0, s[28:29]
	s_barrier
	s_cbranch_scc0 .LBB0_460
; #define G_LOAD(kt_) do { \
;     if constexpr (AF32) { _Pragma("unroll") for (int i = 0; i < 4; ++i) ld16_sc1(ra[i], Af + (size_t)i * 32 * lda + (kt_) * 32); } \
;     else { _Pragma("unroll") for (int i = 0; i < 2; ++i) ld16_sc1(rab[i], Ab + (size_t)i * 64 * lda + (kt_) * 32); } \
;     _Pragma("unroll") for (int i = 0; i < 4; ++i) ld16_sc1(rb[i], Bp + (size_t)(kt_) * bstep + i * 2048); } while (0)
; template <bool AF32, class Epi>
; __device__ __forceinline__ void gemm_tile(unsigned char* smem, const void* Ap, int lda, const bf16_t* WT, int N, int K, const Epi& epi, int m0, int n0,
;                                           GPre& pr, bool preloaded, const void* nAp, int nn0, bool has_next) {
;     ...
;   for (int kt = 0; kt < nk; ++kt) {
;     const int cur = kt & 1;
;     if (kt + 1 < nk) G_STORE(cur ^ 1);
;     if (kt + 2 < nk) G_LOAD(kt + 2);
;     const bf16_t* a_s = sbase + cur * G_STAGE + (wr * 64 + l15) * GLD + quad * 8;
;     const bf16_t* b_s = sbase + cur * G_STAGE + 128 * GLD + (wc * 128 + l15) * GLD + quad * 8;
;     __builtin_amdgcn_s_setprio(1);
;     bf16x8 af[4];
; #pragma unroll
;     for (int m = 0; m < 4; ++m) af[m] = *(const bf16x8*)(a_s + m * 16 * GLD);
; #pragma unroll
;     for (int nh = 0; nh < 4; ++nh) {
;       bf16x8 bfr[2];
; #pragma unroll
;       for (int n2 = 0; n2 < 2; ++n2) bfr[n2] = *(const bf16x8*)(b_s + (nh * 2 + n2) * 16 * GLD);
; #pragma unroll
;       for (int m = 0; m < 4; ++m)
; #pragma unroll
;         for (int n2 = 0; n2 < 2; ++n2) acc[m][nh * 2 + n2] = __builtin_amdgcn_mfma_f32_16x16x32_bf16(bfr[n2], af[m], acc[m][nh * 2 + n2], 0, 0, 0);
;     }
;     __builtin_amdgcn_s_setprio(0);
;     __syncthreads();
	s_waitcnt vmcnt(0)
	v_add_u32_e32 v176, v169, v170
	v_cvt_pk_bf16_f32 v164, v28, v29
	v_cvt_pk_bf16_f32 v165, v30, v31
	v_cvt_pk_bf16_f32 v166, v24, v25
	v_cvt_pk_bf16_f32 v167, v26, v27
	ds_write2st64_b64 v161, v[164:165], v[166:167] offset0:60 offset1:65
	v_cvt_pk_bf16_f32 v164, v20, v21
	v_cvt_pk_bf16_f32 v165, v22, v23
	v_cvt_pk_bf16_f32 v166, v16, v17
	v_cvt_pk_bf16_f32 v167, v18, v19
	ds_write2st64_b64 v161, v[164:165], v[166:167] offset0:70 offset1:75
	ds_write_b128 v163, v[0:3] offset:40960
	ds_write_b128 v163, v[4:7] offset:46080
	ds_write_b128 v163, v[8:11] offset:51200
	ds_write_b128 v163, v[12:15] offset:56320
	s_setprio 1
	v_add_u32_e32 v193, v168, v170
	ds_read_b128 v[160:163], v193 offset:10240
	ds_read_b128 v[164:167], v193 offset:11520
	ds_read_b128 v[168:171], v176
	ds_read_b128 v[172:175], v176 offset:1280
	ds_read_b128 v[194:197], v176 offset:2560
	ds_read_b128 v[198:201], v176 offset:3840
	s_waitcnt lgkmcnt(3)
	v_mfma_f32_16x16x32_bf16 v[156:159], v[160:163], v[168:171], v[156:159]
	v_mfma_f32_16x16x32_bf16 v[152:155], v[164:167], v[168:171], v[152:155]
	s_waitcnt lgkmcnt(2)
	v_mfma_f32_16x16x32_bf16 v[140:143], v[160:163], v[172:175], v[140:143]
	v_mfma_f32_16x16x32_bf16 v[136:139], v[164:167], v[172:175], v[136:139]
	s_waitcnt lgkmcnt(1)
	v_mfma_f32_16x16x32_bf16 v[108:111], v[160:163], v[194:197], v[108:111]
	v_mfma_f32_16x16x32_bf16 v[100:103], v[164:167], v[194:197], v[100:103]
	s_waitcnt lgkmcnt(0)
	v_mfma_f32_16x16x32_bf16 v[76:79], v[160:163], v[198:201], v[76:79]
	ds_read_b128 v[160:163], v193 offset:12800
	v_mfma_f32_16x16x32_bf16 v[68:71], v[164:167], v[198:201], v[68:71]
	ds_read_b128 v[164:167], v193 offset:14080
	s_waitcnt lgkmcnt(1)
	v_mfma_f32_16x16x32_bf16 v[148:151], v[160:163], v[168:171], v[148:151]
	s_waitcnt lgkmcnt(0)
	v_mfma_f32_16x16x32_bf16 v[144:147], v[164:167], v[168:171], v[144:147]
	v_mfma_f32_16x16x32_bf16 v[124:127], v[160:163], v[172:175], v[124:127]
	v_mfma_f32_16x16x32_bf16 v[116:119], v[164:167], v[172:175], v[116:119]
	v_mfma_f32_16x16x32_bf16 v[92:95], v[160:163], v[194:197], v[92:95]
	v_mfma_f32_16x16x32_bf16 v[84:87], v[164:167], v[194:197], v[84:87]
	v_mfma_f32_16x16x32_bf16 v[60:63], v[160:163], v[198:201], v[60:63]
	ds_read_b128 v[160:163], v193 offset:15360
	v_mfma_f32_16x16x32_bf16 v[52:55], v[164:167], v[198:201], v[52:55]
	ds_read_b128 v[164:167], v193 offset:16640
	s_waitcnt lgkmcnt(1)
	v_mfma_f32_16x16x32_bf16 v[212:215], v[160:163], v[194:197], v[72:75]
	s_nop 2
	ds_read_b128 v[72:75], v193 offset:19200
	s_waitcnt lgkmcnt(1)
	v_mfma_f32_16x16x32_bf16 v[216:219], v[164:167], v[194:197], v[64:67]
	s_nop 2
	ds_read_b128 v[64:67], v193 offset:17920
	v_mfma_f32_16x16x32_bf16 v[128:131], v[164:167], v[168:171], v[128:131]
	v_mfma_f32_16x16x32_bf16 v[96:99], v[164:167], v[172:175], v[96:99]
	s_waitcnt lgkmcnt(0)
	v_mfma_f32_16x16x32_bf16 v[120:123], v[64:67], v[168:171], v[120:123]
	v_mfma_f32_16x16x32_bf16 v[112:115], v[72:75], v[168:171], v[112:115]
	v_mfma_f32_16x16x32_bf16 v[88:91], v[64:67], v[172:175], v[88:91]
	v_mfma_f32_16x16x32_bf16 v[80:83], v[72:75], v[172:175], v[80:83]
	v_mfma_f32_16x16x32_bf16 v[48:51], v[72:75], v[194:197], v[48:51]
	v_mfma_f32_16x16x32_bf16 v[202:205], v[160:163], v[168:171], v[132:135]
	v_mfma_f32_16x16x32_bf16 v[206:209], v[160:163], v[172:175], v[104:107]
	v_mfma_f32_16x16x32_bf16 v[44:47], v[160:163], v[198:201], v[44:47]
	v_mfma_f32_16x16x32_bf16 v[40:43], v[164:167], v[198:201], v[40:43]
	v_mfma_f32_16x16x32_bf16 v[220:223], v[64:67], v[194:197], v[56:59]
	v_mfma_f32_16x16x32_bf16 v[36:39], v[64:67], v[198:201], v[36:39]
	v_mfma_f32_16x16x32_bf16 v[32:35], v[72:75], v[198:201], v[32:35]
	s_setprio 0
	s_barrier
; #define G_LOAD(kt_) do { \
;     if constexpr (AF32) { _Pragma("unroll") for (int i = 0; i < 4; ++i) ld16_sc1(ra[i], Af + (size_t)i * 32 * lda + (kt_) * 32); } \
;     else { _Pragma("unroll") for (int i = 0; i < 2; ++i) ld16_sc1(rab[i], Ab + (size_t)i * 64 * lda + (kt_) * 32); } \
;     _Pragma("unroll") for (int i = 0; i < 4; ++i) ld16_sc1(rb[i], Bp + (size_t)(kt_) * bstep + i * 2048); } while (0)
; template <bool AF32, class Epi>
; __device__ __forceinline__ void gemm_tile(unsigned char* smem, const void* Ap, int lda, const bf16_t* WT, int N, int K, const Epi& epi, int m0, int n0,
;                                           GPre& pr, bool preloaded, const void* nAp, int nn0, bool has_next) {
;     ...
;     for (int nh = 0; nh < 4; ++nh) {
;       bf16x8 bfr[2];
; #pragma unroll
;       for (int n2 = 0; n2 < 2; ++n2) bfr[n2] = *(const bf16x8*)(b_s + (nh * 2 + n2) * 16 * GLD);
; #pragma unroll
;       for (int m = 0; m < 4; ++m)
; #pragma unroll
;         for (int n2 = 0; n2 < 2; ++n2) acc[m][nh * 2 + n2] = __builtin_amdgcn_mfma_f32_16x16x32_bf16(bfr[n2], af[m], acc[m][nh * 2 + n2], 0, 0, 0);
;     }
;     __builtin_amdgcn_s_setprio(0);
;     __syncthreads();
;   }
;   if (has_next) {
;     const float* Af = (const float*)nAp + (size_t)(tid >> 3) * lda + (tid & 7) * 4;
;     const bf16_t* Ab = (const bf16_t*)nAp + (size_t)(tid >> 2) * lda + (tid & 3) * 8;
;     const bf16_t* Bp = WT + (size_t)nn0 * 32 + tid * 8;
;     G_LOAD(0);
;   }
	s_setprio 1
	ds_read_b128 v[56:59], v193 offset:40960
	ds_read_b128 v[64:67], v193 offset:42240
	ds_read_b128 v[194:197], v176 offset:30720
	ds_read_b128 v[198:201], v176 offset:32000
	ds_read_b128 v[224:227], v176 offset:33280
	ds_read_b128 v[228:231], v176 offset:34560
	s_waitcnt lgkmcnt(3)
	v_mfma_f32_16x16x32_bf16 v[172:175], v[56:59], v[194:197], v[156:159]
	v_mfma_f32_16x16x32_bf16 v[164:167], v[64:67], v[194:197], v[152:155]
	s_waitcnt lgkmcnt(2)
	v_mfma_f32_16x16x32_bf16 v[140:143], v[56:59], v[198:201], v[140:143]
	v_mfma_f32_16x16x32_bf16 v[132:135], v[64:67], v[198:201], v[136:139]
	s_waitcnt lgkmcnt(1)
	v_mfma_f32_16x16x32_bf16 v[108:111], v[56:59], v[224:227], v[108:111]
	v_mfma_f32_16x16x32_bf16 v[100:103], v[64:67], v[224:227], v[100:103]
	s_waitcnt lgkmcnt(0)
	v_mfma_f32_16x16x32_bf16 v[76:79], v[56:59], v[228:231], v[76:79]
	ds_read_b128 v[56:59], v193 offset:43520
	v_mfma_f32_16x16x32_bf16 v[72:75], v[64:67], v[228:231], v[68:71]
	ds_read_b128 v[64:67], v193 offset:44800
	s_waitcnt lgkmcnt(1)
	v_mfma_f32_16x16x32_bf16 v[168:171], v[56:59], v[194:197], v[148:151]
	s_waitcnt lgkmcnt(0)
	v_mfma_f32_16x16x32_bf16 v[156:159], v[64:67], v[194:197], v[144:147]
	v_mfma_f32_16x16x32_bf16 v[136:139], v[56:59], v[198:201], v[124:127]
	v_mfma_f32_16x16x32_bf16 v[124:127], v[64:67], v[198:201], v[116:119]
	v_mfma_f32_16x16x32_bf16 v[104:107], v[56:59], v[224:227], v[92:95]
	v_mfma_f32_16x16x32_bf16 v[92:95], v[64:67], v[224:227], v[84:87]
	v_mfma_f32_16x16x32_bf16 v[68:71], v[56:59], v[228:231], v[60:63]
	ds_read_b128 v[56:59], v193 offset:46080
	v_mfma_f32_16x16x32_bf16 v[64:67], v[64:67], v[228:231], v[52:55]
	s_nop 2
	ds_read_b128 v[52:55], v193 offset:47360
	s_waitcnt lgkmcnt(1)
	v_mfma_f32_16x16x32_bf16 v[160:163], v[56:59], v[194:197], v[202:205]
	s_waitcnt lgkmcnt(0)
	v_mfma_f32_16x16x32_bf16 v[148:151], v[52:55], v[194:197], v[128:131]
	v_mfma_f32_16x16x32_bf16 v[128:131], v[56:59], v[198:201], v[206:209]
	v_mfma_f32_16x16x32_bf16 v[116:119], v[52:55], v[198:201], v[96:99]
	v_mfma_f32_16x16x32_bf16 v[96:99], v[56:59], v[224:227], v[212:215]
	v_mfma_f32_16x16x32_bf16 v[60:63], v[56:59], v[228:231], v[44:47]
	s_nop 2
	ds_read_b128 v[44:47], v193 offset:48640
	v_mfma_f32_16x16x32_bf16 v[56:59], v[52:55], v[228:231], v[40:43]
	s_nop 2
	ds_read_b128 v[40:43], v193 offset:49920
	v_mfma_f32_16x16x32_bf16 v[84:87], v[52:55], v[224:227], v[216:219]
	s_waitcnt lgkmcnt(1)
	v_mfma_f32_16x16x32_bf16 v[152:155], v[44:47], v[194:197], v[120:123]
	s_waitcnt lgkmcnt(0)
	v_mfma_f32_16x16x32_bf16 v[144:147], v[40:43], v[194:197], v[112:115]
	v_mfma_f32_16x16x32_bf16 v[120:123], v[44:47], v[198:201], v[88:91]
	v_mfma_f32_16x16x32_bf16 v[112:115], v[40:43], v[198:201], v[80:83]
	v_mfma_f32_16x16x32_bf16 v[88:91], v[44:47], v[224:227], v[220:223]
	v_mfma_f32_16x16x32_bf16 v[80:83], v[40:43], v[224:227], v[48:51]
	v_mfma_f32_16x16x32_bf16 v[52:55], v[44:47], v[228:231], v[36:39]
	v_mfma_f32_16x16x32_bf16 v[48:51], v[40:43], v[228:231], v[32:35]
	s_and_b64 vcc, exec, s[6:7]
	s_barrier
	s_cbranch_vccz .LBB0_463
	s_ashr_i32 s53, s52, 31
	s_lshl_b64 s[6:7], s[52:53], 19
	s_add_u32 s6, s12, s6
	s_addc_u32 s7, s13, s7
	s_lshl_b32 s52, s68, 8
	v_lshl_add_u64 v[0:1], v[188:189], 2, s[6:7]
	v_lshlrev_b32_e32 v176, 2, v190
	s_ashr_i32 s53, s52, 31
	v_lshl_add_u64 v[0:1], v[0:1], 0, v[176:177]
	s_lshl_b64 s[6:7], s[52:53], 6
	global_load_dwordx4 v[40:43], v[0:1], off sc1
	s_add_u32 s6, s2, s6
	v_lshl_add_u64 v[2:3], v[0:1], 0, s[16:17]
	global_load_dwordx4 v[44:47], v[2:3], off sc1
	s_addc_u32 s7, s33, s7
	v_lshl_add_u64 v[2:3], v[0:1], 0, s[18:19]
	global_load_dwordx4 v[32:35], v[2:3], off sc1
	v_lshl_add_u64 v[0:1], v[0:1], 0, s[20:21]
	global_load_dwordx4 v[36:39], v[0:1], off sc1
	v_lshl_add_u64 v[12:13], v[184:185], 1, s[6:7]
	global_load_dwordx4 v[0:3], v[12:13], off sc1
	v_lshl_add_u64 v[4:5], v[12:13], 0, s[22:23]
	global_load_dwordx4 v[4:7], v[4:5], off sc1
	v_lshl_add_u64 v[8:9], v[12:13], 0, s[24:25]
	global_load_dwordx4 v[8:11], v[8:9], off sc1
	v_lshl_add_u64 v[12:13], v[12:13], 0, s[26:27]
	global_load_dwordx4 v[12:15], v[12:13], off sc1
	s_branch .LBB0_464

; #define G_LOAD(kt_) do { \
;     if constexpr (AF32) { _Pragma("unroll") for (int i = 0; i < 4; ++i) ld16_sc1(ra[i], Af + (size_t)i * 32 * lda + (kt_) * 32); } \
;     else { _Pragma("unroll") for (int i = 0; i < 2; ++i) ld16_sc1(rab[i], Ab + (size_t)i * 64 * lda + (kt_) * 32); } \
;     _Pragma("unroll") for (int i = 0; i < 4; ++i) ld16_sc1(rb[i], Bp + (size_t)(kt_) * bstep + i * 2048); } while (0)
; template <bool AF32, class Epi>
; __device__ __forceinline__ void gemm_tile(unsigned char* smem, const void* Ap, int lda, const bf16_t* WT, int N, int K, const Epi& epi, int m0, int n0,
;                                           GPre& pr, bool preloaded, const void* nAp, int nn0, bool has_next) {
;     ...
;   if (!preloaded) G_LOAD(0);
;   G_STORE(0);
;   if (nk > 1) G_LOAD(1);
;   __syncthreads();
;   for (int kt = 0; kt < nk; ++kt) {
;     const int cur = kt & 1;
;     if (kt + 1 < nk) G_STORE(cur ^ 1);
;     if (kt + 2 < nk) G_LOAD(kt + 2);
;     const bf16_t* a_s = sbase + cur * G_STAGE + (wr * 64 + l15) * GLD + quad * 8;
;     const bf16_t* b_s = sbase + cur * G_STAGE + 128 * GLD + (wc * 128 + l15) * GLD + quad * 8;
;     __builtin_amdgcn_s_setprio(1);
;     bf16x8 af[4];
; #pragma unroll
;     for (int m = 0; m < 4; ++m) af[m] = *(const bf16x8*)(a_s + m * 16 * GLD);
; #pragma unroll
;     for (int nh = 0; nh < 4; ++nh) {
;       bf16x8 bfr[2];
; #pragma unroll
;       for (int n2 = 0; n2 < 2; ++n2) bfr[n2] = *(const bf16x8*)(b_s + (nh * 2 + n2) * 16 * GLD);
; #pragma unroll
;       for (int m = 0; m < 4; ++m)
; #pragma unroll
;         for (int n2 = 0; n2 < 2; ++n2) acc[m][nh * 2 + n2] = __builtin_amdgcn_mfma_f32_16x16x32_bf16(bfr[n2], af[m], acc[m][nh * 2 + n2], 0, 0, 0);
;     }
;     __builtin_amdgcn_s_setprio(0);
;     __syncthreads();
;   }
.LBB0_555:
	s_and_b32 s3, s50, 1
	s_waitcnt vmcnt(0)
	s_xor_b32 s51, s3, 1
	s_mulk_i32 s51, 0x7800
	v_add_u32_e32 v176, s51, v155
	ds_write_b128 v176, v[0:3]
	ds_write_b128 v176, v[4:7] offset:5120
	ds_write_b128 v176, v[8:11] offset:10240
	ds_write_b128 v176, v[12:15] offset:15360
	ds_write_b128 v176, v[16:19] offset:20480
	ds_write_b128 v176, v[20:23] offset:25600
	s_setprio 2
	global_load_dwordx4 v[0:3], v[162:163], off sc1
	v_lshl_add_u64 v[168:169], v[162:163], 0, s[10:11]
	global_load_dwordx4 v[4:7], v[168:169], off sc1
	global_load_dwordx4 v[8:11], v[160:161], off sc1
	v_lshl_add_u64 v[170:171], v[160:161], 0, s[12:13]
	global_load_dwordx4 v[12:15], v[170:171], off sc1
	v_lshl_add_u64 v[172:173], v[160:161], 0, s[14:15]
	global_load_dwordx4 v[16:19], v[172:173], off sc1
	v_lshl_add_u64 v[174:175], v[160:161], 0, s[16:17]
	global_load_dwordx4 v[20:23], v[174:175], off sc1
	s_setprio 0
	s_add_i32 s50, s50, 1
	s_mulk_i32 s3, 0x7800
	v_add3_u32 v188, s3, v166, v167
	s_setprio 1
	v_add3_u32 v192, s3, v165, v167
	ds_read_b128 v[168:171], v192 offset:10240
	ds_read_b128 v[172:175], v192 offset:11520
	ds_read_b128 v[176:179], v188
	ds_read_b128 v[180:183], v188 offset:1280
	ds_read_b128 v[184:187], v188 offset:2560
	ds_read_b128 v[188:191], v188 offset:3840
	s_waitcnt lgkmcnt(3)
	v_mfma_f32_16x16x32_bf16 v[148:151], v[168:171], v[176:179], v[148:151]
	v_mfma_f32_16x16x32_bf16 v[144:147], v[172:175], v[176:179], v[144:147]
	s_waitcnt lgkmcnt(2)
	v_mfma_f32_16x16x32_bf16 v[132:135], v[168:171], v[180:183], v[132:135]
	v_mfma_f32_16x16x32_bf16 v[128:131], v[172:175], v[180:183], v[128:131]
	s_waitcnt lgkmcnt(1)
	v_mfma_f32_16x16x32_bf16 v[100:103], v[168:171], v[184:187], v[100:103]
	v_mfma_f32_16x16x32_bf16 v[92:95], v[172:175], v[184:187], v[92:95]
	s_waitcnt lgkmcnt(0)
	v_mfma_f32_16x16x32_bf16 v[68:71], v[168:171], v[188:191], v[68:71]
	ds_read_b128 v[168:171], v192 offset:12800
	v_mfma_f32_16x16x32_bf16 v[60:63], v[172:175], v[188:191], v[60:63]
	ds_read_b128 v[172:175], v192 offset:14080
	s_waitcnt lgkmcnt(1)
	v_mfma_f32_16x16x32_bf16 v[140:143], v[168:171], v[176:179], v[140:143]
	s_waitcnt lgkmcnt(0)
	v_mfma_f32_16x16x32_bf16 v[136:139], v[172:175], v[176:179], v[136:139]
	v_mfma_f32_16x16x32_bf16 v[116:119], v[168:171], v[180:183], v[116:119]
	v_mfma_f32_16x16x32_bf16 v[108:111], v[172:175], v[180:183], v[108:111]
	v_mfma_f32_16x16x32_bf16 v[84:87], v[168:171], v[184:187], v[84:87]
	v_mfma_f32_16x16x32_bf16 v[76:79], v[172:175], v[184:187], v[76:79]
	v_mfma_f32_16x16x32_bf16 v[52:55], v[168:171], v[188:191], v[52:55]
	ds_read_b128 v[168:171], v192 offset:15360
	v_mfma_f32_16x16x32_bf16 v[44:47], v[172:175], v[188:191], v[44:47]
	ds_read_b128 v[172:175], v192 offset:16640
	s_waitcnt lgkmcnt(1)
	v_mfma_f32_16x16x32_bf16 v[124:127], v[168:171], v[176:179], v[124:127]
	s_waitcnt lgkmcnt(0)
	v_mfma_f32_16x16x32_bf16 v[120:123], v[172:175], v[176:179], v[120:123]
	v_mfma_f32_16x16x32_bf16 v[96:99], v[168:171], v[180:183], v[96:99]
	v_mfma_f32_16x16x32_bf16 v[88:91], v[172:175], v[180:183], v[88:91]
	v_mfma_f32_16x16x32_bf16 v[64:67], v[168:171], v[184:187], v[64:67]
	v_mfma_f32_16x16x32_bf16 v[56:59], v[172:175], v[184:187], v[56:59]
	v_mfma_f32_16x16x32_bf16 v[36:39], v[168:171], v[188:191], v[36:39]
	ds_read_b128 v[168:171], v192 offset:17920
	v_mfma_f32_16x16x32_bf16 v[32:35], v[172:175], v[188:191], v[32:35]
	ds_read_b128 v[172:175], v192 offset:19200
	s_waitcnt lgkmcnt(1)
	v_mfma_f32_16x16x32_bf16 v[112:115], v[168:171], v[176:179], v[112:115]
	s_waitcnt lgkmcnt(0)
	v_mfma_f32_16x16x32_bf16 v[104:107], v[172:175], v[176:179], v[104:107]
	v_mfma_f32_16x16x32_bf16 v[80:83], v[168:171], v[180:183], v[80:83]
	v_mfma_f32_16x16x32_bf16 v[72:75], v[172:175], v[180:183], v[72:75]
	v_mfma_f32_16x16x32_bf16 v[48:51], v[168:171], v[184:187], v[48:51]
	v_mfma_f32_16x16x32_bf16 v[40:43], v[172:175], v[184:187], v[40:43]
	v_mfma_f32_16x16x32_bf16 v[28:31], v[168:171], v[188:191], v[28:31]
	v_mfma_f32_16x16x32_bf16 v[24:27], v[172:175], v[188:191], v[24:27]
	s_setprio 0
	v_lshl_add_u64 v[160:161], v[160:161], 0, s[20:21]
	s_cmp_eq_u32 s50, 30
	v_lshl_add_u64 v[162:163], v[162:163], 0, 64
	s_barrier
	s_cbranch_scc0 .LBB0_555
	s_waitcnt vmcnt(0)
	ds_write_b128 v155, v[0:3] offset:30720
	ds_write_b128 v155, v[4:7] offset:35840
	ds_write_b128 v155, v[8:11] offset:40960
	ds_write_b128 v155, v[12:15] offset:46080
	ds_write_b128 v155, v[16:19] offset:51200
	ds_write_b128 v155, v[20:23] offset:56320
	v_add_u32_e32 v155, v166, v167
	s_setprio 1
	v_add_u32_e32 v165, v165, v167
	ds_read_b128 v[160:163], v165 offset:10240
	ds_read_b128 v[166:169], v165 offset:11520
	ds_read_b128 v[170:173], v155
	ds_read_b128 v[174:177], v155 offset:1280
	ds_read_b128 v[178:181], v155 offset:2560
	ds_read_b128 v[182:185], v155 offset:3840
	s_waitcnt lgkmcnt(3)
	v_mfma_f32_16x16x32_bf16 v[148:151], v[160:163], v[170:173], v[148:151]
	v_mfma_f32_16x16x32_bf16 v[144:147], v[166:169], v[170:173], v[144:147]
	s_waitcnt lgkmcnt(2)
	v_mfma_f32_16x16x32_bf16 v[132:135], v[160:163], v[174:177], v[132:135]
	v_mfma_f32_16x16x32_bf16 v[128:131], v[166:169], v[174:177], v[128:131]
	s_waitcnt lgkmcnt(1)
	v_mfma_f32_16x16x32_bf16 v[100:103], v[160:163], v[178:181], v[100:103]
	v_mfma_f32_16x16x32_bf16 v[92:95], v[166:169], v[178:181], v[92:95]
	s_waitcnt lgkmcnt(0)
	v_mfma_f32_16x16x32_bf16 v[68:71], v[160:163], v[182:185], v[68:71]
	ds_read_b128 v[160:163], v165 offset:12800
	v_mfma_f32_16x16x32_bf16 v[60:63], v[166:169], v[182:185], v[60:63]
	ds_read_b128 v[166:169], v165 offset:14080
	s_waitcnt lgkmcnt(1)
	v_mfma_f32_16x16x32_bf16 v[186:189], v[160:163], v[170:173], v[140:143]
	s_waitcnt lgkmcnt(0)
; #define G_LOAD(kt_) do { \
;     if constexpr (AF32) { _Pragma("unroll") for (int i = 0; i < 4; ++i) ld16_sc1(ra[i], Af + (size_t)i * 32 * lda + (kt_) * 32); } \
;     else { _Pragma("unroll") for (int i = 0; i < 2; ++i) ld16_sc1(rab[i], Ab + (size_t)i * 64 * lda + (kt_) * 32); } \
;     _Pragma("unroll") for (int i = 0; i < 4; ++i) ld16_sc1(rb[i], Bp + (size_t)(kt_) * bstep + i * 2048); } while (0)
; template <bool AF32, class Epi>
; __device__ __forceinline__ void gemm_tile(unsigned char* smem, const void* Ap, int lda, const bf16_t* WT, int N, int K, const Epi& epi, int m0, int n0,
;                                           GPre& pr, bool preloaded, const void* nAp, int nn0, bool has_next) {
;     ...
;   for (int kt = 0; kt < nk; ++kt) {
;     const int cur = kt & 1;
;     if (kt + 1 < nk) G_STORE(cur ^ 1);
;     if (kt + 2 < nk) G_LOAD(kt + 2);
;     const bf16_t* a_s = sbase + cur * G_STAGE + (wr * 64 + l15) * GLD + quad * 8;
;     const bf16_t* b_s = sbase + cur * G_STAGE + 128 * GLD + (wc * 128 + l15) * GLD + quad * 8;
;     __builtin_amdgcn_s_setprio(1);
;     bf16x8 af[4];
; #pragma unroll
;     for (int m = 0; m < 4; ++m) af[m] = *(const bf16x8*)(a_s + m * 16 * GLD);
; #pragma unroll
;     for (int nh = 0; nh < 4; ++nh) {
;       bf16x8 bfr[2];
; #pragma unroll
;       for (int n2 = 0; n2 < 2; ++n2) bfr[n2] = *(const bf16x8*)(b_s + (nh * 2 + n2) * 16 * GLD);
; #pragma unroll
;       for (int m = 0; m < 4; ++m)
; #pragma unroll
;         for (int n2 = 0; n2 < 2; ++n2) acc[m][nh * 2 + n2] = __builtin_amdgcn_mfma_f32_16x16x32_bf16(bfr[n2], af[m], acc[m][nh * 2 + n2], 0, 0, 0);
;     }
;     __builtin_amdgcn_s_setprio(0);
;     __syncthreads();
;   }
;   if (has_next) {
;     const float* Af = (const float*)nAp + (size_t)(tid >> 3) * lda + (tid & 7) * 4;
;     const bf16_t* Ab = (const bf16_t*)nAp + (size_t)(tid >> 2) * lda + (tid & 3) * 8;
;     const bf16_t* Bp = WT + (size_t)nn0 * 32 + tid * 8;
;     G_LOAD(0);
;   }
	v_mfma_f32_16x16x32_bf16 v[136:139], v[166:169], v[170:173], v[136:139]
	v_mfma_f32_16x16x32_bf16 v[190:193], v[160:163], v[174:177], v[116:119]
	v_mfma_f32_16x16x32_bf16 v[194:197], v[166:169], v[174:177], v[108:111]
	v_mfma_f32_16x16x32_bf16 v[198:201], v[160:163], v[178:181], v[84:87]
	v_mfma_f32_16x16x32_bf16 v[202:205], v[166:169], v[178:181], v[76:79]
	v_mfma_f32_16x16x32_bf16 v[160:163], v[160:163], v[182:185], v[52:55]
	s_nop 2
	ds_read_b128 v[52:55], v165 offset:15360
	v_mfma_f32_16x16x32_bf16 v[166:169], v[166:169], v[182:185], v[44:47]
	s_nop 2
	ds_read_b128 v[44:47], v165 offset:16640
	s_waitcnt lgkmcnt(1)
	v_mfma_f32_16x16x32_bf16 v[124:127], v[52:55], v[170:173], v[124:127]
	s_waitcnt lgkmcnt(0)
	v_mfma_f32_16x16x32_bf16 v[120:123], v[44:47], v[170:173], v[120:123]
	v_mfma_f32_16x16x32_bf16 v[96:99], v[52:55], v[174:177], v[96:99]
	v_mfma_f32_16x16x32_bf16 v[88:91], v[44:47], v[174:177], v[88:91]
	v_mfma_f32_16x16x32_bf16 v[64:67], v[52:55], v[178:181], v[64:67]
	v_mfma_f32_16x16x32_bf16 v[56:59], v[44:47], v[178:181], v[56:59]
	v_mfma_f32_16x16x32_bf16 v[36:39], v[52:55], v[182:185], v[36:39]
	ds_read_b128 v[52:55], v165 offset:17920
	v_mfma_f32_16x16x32_bf16 v[32:35], v[44:47], v[182:185], v[32:35]
	ds_read_b128 v[44:47], v165 offset:19200
	s_waitcnt lgkmcnt(1)
	v_mfma_f32_16x16x32_bf16 v[28:31], v[52:55], v[182:185], v[28:31]
	s_waitcnt lgkmcnt(0)
	v_mfma_f32_16x16x32_bf16 v[24:27], v[44:47], v[182:185], v[24:27]
	v_mfma_f32_16x16x32_bf16 v[206:209], v[52:55], v[170:173], v[112:115]
	v_mfma_f32_16x16x32_bf16 v[170:173], v[44:47], v[170:173], v[104:107]
	v_mfma_f32_16x16x32_bf16 v[212:215], v[52:55], v[174:177], v[80:83]
	v_mfma_f32_16x16x32_bf16 v[174:177], v[44:47], v[174:177], v[72:75]
	v_mfma_f32_16x16x32_bf16 v[216:219], v[52:55], v[178:181], v[48:51]
	v_mfma_f32_16x16x32_bf16 v[178:181], v[44:47], v[178:181], v[40:43]
	s_setprio 0
	s_barrier
	s_setprio 1
	ds_read_b128 v[40:43], v165 offset:40960
	ds_read_b128 v[44:47], v165 offset:42240
	ds_read_b128 v[182:185], v155 offset:30720
	ds_read_b128 v[220:223], v155 offset:32000
	ds_read_b128 v[224:227], v155 offset:33280
	ds_read_b128 v[228:231], v155 offset:34560
	s_waitcnt lgkmcnt(3)
	v_mfma_f32_16x16x32_bf16 v[148:151], v[40:43], v[182:185], v[148:151]
	s_waitcnt lgkmcnt(2)
	v_mfma_f32_16x16x32_bf16 v[116:119], v[40:43], v[220:223], v[132:135]
	s_waitcnt lgkmcnt(1)
	v_mfma_f32_16x16x32_bf16 v[84:87], v[40:43], v[224:227], v[100:103]
	s_waitcnt lgkmcnt(0)
	v_mfma_f32_16x16x32_bf16 v[52:55], v[40:43], v[228:231], v[68:71]
	ds_read_b128 v[40:43], v165 offset:43520
	v_mfma_f32_16x16x32_bf16 v[48:51], v[44:47], v[228:231], v[60:63]
	s_nop 2
	ds_read_b128 v[60:63], v165 offset:44800
	v_mfma_f32_16x16x32_bf16 v[140:143], v[44:47], v[182:185], v[144:147]
	v_mfma_f32_16x16x32_bf16 v[108:111], v[44:47], v[220:223], v[128:131]
	v_mfma_f32_16x16x32_bf16 v[80:83], v[44:47], v[224:227], v[92:95]
	s_waitcnt lgkmcnt(1)
	v_mfma_f32_16x16x32_bf16 v[144:147], v[40:43], v[182:185], v[186:189]
	s_nop 0
	ds_read_b128 v[92:95], v165 offset:46080
	s_waitcnt lgkmcnt(1)
	v_mfma_f32_16x16x32_bf16 v[136:139], v[60:63], v[182:185], v[136:139]
	v_mfma_f32_16x16x32_bf16 v[112:115], v[40:43], v[220:223], v[190:193]
	v_mfma_f32_16x16x32_bf16 v[104:107], v[60:63], v[220:223], v[194:197]
	v_mfma_f32_16x16x32_bf16 v[76:79], v[40:43], v[224:227], v[198:201]
	v_mfma_f32_16x16x32_bf16 v[72:75], v[60:63], v[224:227], v[202:205]
	v_mfma_f32_16x16x32_bf16 v[44:47], v[40:43], v[228:231], v[160:163]
	v_mfma_f32_16x16x32_bf16 v[40:43], v[60:63], v[228:231], v[166:169]
	ds_read_b128 v[60:63], v165 offset:47360
	s_nop 0
	ds_read_b128 v[160:163], v165 offset:48640
	ds_read_b128 v[166:169], v165 offset:49920
	s_waitcnt lgkmcnt(3)
	v_mfma_f32_16x16x32_bf16 v[132:135], v[92:95], v[182:185], v[124:127]
	s_waitcnt lgkmcnt(2)
	v_mfma_f32_16x16x32_bf16 v[128:131], v[60:63], v[182:185], v[120:123]
	v_mfma_f32_16x16x32_bf16 v[100:103], v[92:95], v[220:223], v[96:99]
	v_mfma_f32_16x16x32_bf16 v[96:99], v[60:63], v[220:223], v[88:91]
	v_mfma_f32_16x16x32_bf16 v[68:71], v[92:95], v[224:227], v[64:67]
	v_mfma_f32_16x16x32_bf16 v[64:67], v[60:63], v[224:227], v[56:59]
	v_mfma_f32_16x16x32_bf16 v[36:39], v[92:95], v[228:231], v[36:39]
	v_mfma_f32_16x16x32_bf16 v[32:35], v[60:63], v[228:231], v[32:35]
	s_waitcnt lgkmcnt(1)
	v_mfma_f32_16x16x32_bf16 v[124:127], v[160:163], v[182:185], v[206:209]
	s_waitcnt lgkmcnt(0)
	v_mfma_f32_16x16x32_bf16 v[120:123], v[166:169], v[182:185], v[170:173]
	v_mfma_f32_16x16x32_bf16 v[92:95], v[160:163], v[220:223], v[212:215]
	v_mfma_f32_16x16x32_bf16 v[88:91], v[166:169], v[220:223], v[174:177]
	v_mfma_f32_16x16x32_bf16 v[60:63], v[160:163], v[224:227], v[216:219]
	v_mfma_f32_16x16x32_bf16 v[56:59], v[166:169], v[224:227], v[178:181]
	v_mfma_f32_16x16x32_bf16 v[28:31], v[160:163], v[228:231], v[28:31]
	v_mfma_f32_16x16x32_bf16 v[24:27], v[166:169], v[228:231], v[24:27]
	s_and_b64 vcc, exec, s[46:47]
	s_barrier
	s_cbranch_vccz .LBB0_543
	s_mul_i32 s46, s67, 0xc0000
	s_mul_hi_i32 s3, s67, 0xc0000
	s_add_u32 s46, s2, s46
	s_addc_u32 s47, s33, s3
	s_lshl_b32 s50, s66, 8
	s_ashr_i32 s51, s50, 31
	v_lshl_add_u64 v[0:1], v[158:159], 1, s[46:47]
	s_lshl_b64 s[46:47], s[50:51], 6
	v_lshl_add_u64 v[4:5], v[0:1], 0, v[152:153]
	s_add_u32 s46, s54, s46
	s_addc_u32 s47, s55, s47
	global_load_dwordx4 v[0:3], v[4:5], off sc1
	v_lshl_add_u64 v[4:5], v[4:5], 0, s[10:11]
	global_load_dwordx4 v[4:7], v[4:5], off sc1
	v_lshl_add_u64 v[20:21], v[156:157], 1, s[46:47]
	global_load_dwordx4 v[8:11], v[20:21], off sc1
	v_lshl_add_u64 v[12:13], v[20:21], 0, s[12:13]
	global_load_dwordx4 v[12:15], v[12:13], off sc1
	v_lshl_add_u64 v[16:17], v[20:21], 0, s[14:15]
	global_load_dwordx4 v[16:19], v[16:17], off sc1
	v_lshl_add_u64 v[20:21], v[20:21], 0, s[16:17]
	global_load_dwordx4 v[20:23], v[20:21], off sc1
	s_branch .LBB0_543

; #define G_LOAD(kt_) do { \
;     if constexpr (AF32) { _Pragma("unroll") for (int i = 0; i < 4; ++i) ld16_sc1(ra[i], Af + (size_t)i * 32 * lda + (kt_) * 32); } \
;     else { _Pragma("unroll") for (int i = 0; i < 2; ++i) ld16_sc1(rab[i], Ab + (size_t)i * 64 * lda + (kt_) * 32); } \
;     _Pragma("unroll") for (int i = 0; i < 4; ++i) ld16_sc1(rb[i], Bp + (size_t)(kt_) * bstep + i * 2048); } while (0)
; template <bool AF32, class Epi>
; __device__ __forceinline__ void gemm_tile(unsigned char* smem, const void* Ap, int lda, const bf16_t* WT, int N, int K, const Epi& epi, int m0, int n0,
;                                           GPre& pr, bool preloaded, const void* nAp, int nn0, bool has_next) {
;     ...
;   if (!preloaded) G_LOAD(0);
;   G_STORE(0);
;   if (nk > 1) G_LOAD(1);
;   __syncthreads();
;   for (int kt = 0; kt < nk; ++kt) {
;     const int cur = kt & 1;
;     if (kt + 1 < nk) G_STORE(cur ^ 1);
;     if (kt + 2 < nk) G_LOAD(kt + 2);
;     const bf16_t* a_s = sbase + cur * G_STAGE + (wr * 64 + l15) * GLD + quad * 8;
;     const bf16_t* b_s = sbase + cur * G_STAGE + 128 * GLD + (wc * 128 + l15) * GLD + quad * 8;
;     __builtin_amdgcn_s_setprio(1);
;     bf16x8 af[4];
; #pragma unroll
;     for (int m = 0; m < 4; ++m) af[m] = *(const bf16x8*)(a_s + m * 16 * GLD);
; #pragma unroll
;     for (int nh = 0; nh < 4; ++nh) {
;       bf16x8 bfr[2];
; #pragma unroll
;       for (int n2 = 0; n2 < 2; ++n2) bfr[n2] = *(const bf16x8*)(b_s + (nh * 2 + n2) * 16 * GLD);
; #pragma unroll
;       for (int m = 0; m < 4; ++m)
; #pragma unroll
;         for (int n2 = 0; n2 < 2; ++n2) acc[m][nh * 2 + n2] = __builtin_amdgcn_mfma_f32_16x16x32_bf16(bfr[n2], af[m], acc[m][nh * 2 + n2], 0, 0, 0);
;     }
;     __builtin_amdgcn_s_setprio(0);
;     __syncthreads();
;   }
.LBB0_647:
	s_and_b32 s3, s51, 1
	s_waitcnt vmcnt(0)
	s_xor_b32 s52, s3, 1
	s_mulk_i32 s52, 0x7800
	v_add_u32_e32 v176, s52, v155
	ds_write_b128 v176, v[0:3]
	ds_write_b128 v176, v[4:7] offset:5120
	ds_write_b128 v176, v[8:11] offset:10240
	ds_write_b128 v176, v[12:15] offset:15360
	ds_write_b128 v176, v[16:19] offset:20480
	ds_write_b128 v176, v[20:23] offset:25600
	s_setprio 2
	global_load_dwordx4 v[0:3], v[162:163], off sc1
	v_lshl_add_u64 v[168:169], v[162:163], 0, s[10:11]
	global_load_dwordx4 v[4:7], v[168:169], off sc1
	global_load_dwordx4 v[8:11], v[160:161], off sc1
	v_lshl_add_u64 v[170:171], v[160:161], 0, s[12:13]
	global_load_dwordx4 v[12:15], v[170:171], off sc1
	v_lshl_add_u64 v[172:173], v[160:161], 0, s[14:15]
	global_load_dwordx4 v[16:19], v[172:173], off sc1
	v_lshl_add_u64 v[174:175], v[160:161], 0, s[16:17]
	global_load_dwordx4 v[20:23], v[174:175], off sc1
	s_setprio 0
	s_add_i32 s51, s51, 1
	s_mulk_i32 s3, 0x7800
	v_add3_u32 v188, s3, v166, v167
	s_setprio 1
	v_add3_u32 v192, s3, v165, v167
	ds_read_b128 v[168:171], v192 offset:10240
	ds_read_b128 v[172:175], v192 offset:11520
	ds_read_b128 v[176:179], v188
	ds_read_b128 v[180:183], v188 offset:1280
	ds_read_b128 v[184:187], v188 offset:2560
	ds_read_b128 v[188:191], v188 offset:3840
	s_waitcnt lgkmcnt(3)
	v_mfma_f32_16x16x32_bf16 v[148:151], v[168:171], v[176:179], v[148:151]
	v_mfma_f32_16x16x32_bf16 v[144:147], v[172:175], v[176:179], v[144:147]
	s_waitcnt lgkmcnt(2)
	v_mfma_f32_16x16x32_bf16 v[132:135], v[168:171], v[180:183], v[132:135]
	v_mfma_f32_16x16x32_bf16 v[128:131], v[172:175], v[180:183], v[128:131]
	s_waitcnt lgkmcnt(1)
	v_mfma_f32_16x16x32_bf16 v[100:103], v[168:171], v[184:187], v[100:103]
	v_mfma_f32_16x16x32_bf16 v[92:95], v[172:175], v[184:187], v[92:95]
	s_waitcnt lgkmcnt(0)
	v_mfma_f32_16x16x32_bf16 v[68:71], v[168:171], v[188:191], v[68:71]
	ds_read_b128 v[168:171], v192 offset:12800
	v_mfma_f32_16x16x32_bf16 v[60:63], v[172:175], v[188:191], v[60:63]
	ds_read_b128 v[172:175], v192 offset:14080
	s_waitcnt lgkmcnt(1)
	v_mfma_f32_16x16x32_bf16 v[140:143], v[168:171], v[176:179], v[140:143]
	s_waitcnt lgkmcnt(0)
	v_mfma_f32_16x16x32_bf16 v[136:139], v[172:175], v[176:179], v[136:139]
	v_mfma_f32_16x16x32_bf16 v[116:119], v[168:171], v[180:183], v[116:119]
	v_mfma_f32_16x16x32_bf16 v[108:111], v[172:175], v[180:183], v[108:111]
	v_mfma_f32_16x16x32_bf16 v[84:87], v[168:171], v[184:187], v[84:87]
	v_mfma_f32_16x16x32_bf16 v[76:79], v[172:175], v[184:187], v[76:79]
	v_mfma_f32_16x16x32_bf16 v[52:55], v[168:171], v[188:191], v[52:55]
	ds_read_b128 v[168:171], v192 offset:15360
	v_mfma_f32_16x16x32_bf16 v[44:47], v[172:175], v[188:191], v[44:47]
	ds_read_b128 v[172:175], v192 offset:16640
	s_waitcnt lgkmcnt(1)
	v_mfma_f32_16x16x32_bf16 v[124:127], v[168:171], v[176:179], v[124:127]
	s_waitcnt lgkmcnt(0)
	v_mfma_f32_16x16x32_bf16 v[120:123], v[172:175], v[176:179], v[120:123]
	v_mfma_f32_16x16x32_bf16 v[96:99], v[168:171], v[180:183], v[96:99]
	v_mfma_f32_16x16x32_bf16 v[88:91], v[172:175], v[180:183], v[88:91]
	v_mfma_f32_16x16x32_bf16 v[64:67], v[168:171], v[184:187], v[64:67]
	v_mfma_f32_16x16x32_bf16 v[56:59], v[172:175], v[184:187], v[56:59]
	v_mfma_f32_16x16x32_bf16 v[36:39], v[168:171], v[188:191], v[36:39]
	ds_read_b128 v[168:171], v192 offset:17920
	v_mfma_f32_16x16x32_bf16 v[32:35], v[172:175], v[188:191], v[32:35]
	ds_read_b128 v[172:175], v192 offset:19200
	s_waitcnt lgkmcnt(1)
	v_mfma_f32_16x16x32_bf16 v[112:115], v[168:171], v[176:179], v[112:115]
	s_waitcnt lgkmcnt(0)
	v_mfma_f32_16x16x32_bf16 v[104:107], v[172:175], v[176:179], v[104:107]
	v_mfma_f32_16x16x32_bf16 v[80:83], v[168:171], v[180:183], v[80:83]
	v_mfma_f32_16x16x32_bf16 v[72:75], v[172:175], v[180:183], v[72:75]
	v_mfma_f32_16x16x32_bf16 v[48:51], v[168:171], v[184:187], v[48:51]
	v_mfma_f32_16x16x32_bf16 v[40:43], v[172:175], v[184:187], v[40:43]
	v_mfma_f32_16x16x32_bf16 v[28:31], v[168:171], v[188:191], v[28:31]
	v_mfma_f32_16x16x32_bf16 v[24:27], v[172:175], v[188:191], v[24:27]
	s_setprio 0
	v_lshl_add_u64 v[160:161], v[160:161], 0, s[20:21]
	s_cmp_eq_u32 s51, 30
	v_lshl_add_u64 v[162:163], v[162:163], 0, 64
	s_barrier
	s_cbranch_scc0 .LBB0_647
	s_waitcnt vmcnt(0)
	ds_write_b128 v155, v[0:3] offset:30720
	ds_write_b128 v155, v[4:7] offset:35840
	ds_write_b128 v155, v[8:11] offset:40960
	ds_write_b128 v155, v[12:15] offset:46080
	ds_write_b128 v155, v[16:19] offset:51200
	ds_write_b128 v155, v[20:23] offset:56320
	v_add_u32_e32 v155, v166, v167
	s_setprio 1
	v_add_u32_e32 v165, v165, v167
	ds_read_b128 v[160:163], v165 offset:10240
	ds_read_b128 v[166:169], v165 offset:11520
	ds_read_b128 v[170:173], v155
	ds_read_b128 v[174:177], v155 offset:1280
	ds_read_b128 v[178:181], v155 offset:2560
	ds_read_b128 v[182:185], v155 offset:3840
	s_waitcnt lgkmcnt(3)
	v_mfma_f32_16x16x32_bf16 v[148:151], v[160:163], v[170:173], v[148:151]
	v_mfma_f32_16x16x32_bf16 v[144:147], v[166:169], v[170:173], v[144:147]
	s_waitcnt lgkmcnt(2)
	v_mfma_f32_16x16x32_bf16 v[132:135], v[160:163], v[174:177], v[132:135]
	v_mfma_f32_16x16x32_bf16 v[128:131], v[166:169], v[174:177], v[128:131]
	s_waitcnt lgkmcnt(1)
	v_mfma_f32_16x16x32_bf16 v[100:103], v[160:163], v[178:181], v[100:103]
	v_mfma_f32_16x16x32_bf16 v[92:95], v[166:169], v[178:181], v[92:95]
	s_waitcnt lgkmcnt(0)
	v_mfma_f32_16x16x32_bf16 v[68:71], v[160:163], v[182:185], v[68:71]
	ds_read_b128 v[160:163], v165 offset:12800
	v_mfma_f32_16x16x32_bf16 v[60:63], v[166:169], v[182:185], v[60:63]
	ds_read_b128 v[166:169], v165 offset:14080
	s_waitcnt lgkmcnt(1)
	v_mfma_f32_16x16x32_bf16 v[186:189], v[160:163], v[170:173], v[140:143]
	s_waitcnt lgkmcnt(0)
; #define G_LOAD(kt_) do { \
;     if constexpr (AF32) { _Pragma("unroll") for (int i = 0; i < 4; ++i) ld16_sc1(ra[i], Af + (size_t)i * 32 * lda + (kt_) * 32); } \
;     else { _Pragma("unroll") for (int i = 0; i < 2; ++i) ld16_sc1(rab[i], Ab + (size_t)i * 64 * lda + (kt_) * 32); } \
;     _Pragma("unroll") for (int i = 0; i < 4; ++i) ld16_sc1(rb[i], Bp + (size_t)(kt_) * bstep + i * 2048); } while (0)
; template <bool AF32, class Epi>
; __device__ __forceinline__ void gemm_tile(unsigned char* smem, const void* Ap, int lda, const bf16_t* WT, int N, int K, const Epi& epi, int m0, int n0,
;                                           GPre& pr, bool preloaded, const void* nAp, int nn0, bool has_next) {
;     ...
;   for (int kt = 0; kt < nk; ++kt) {
;     const int cur = kt & 1;
;     if (kt + 1 < nk) G_STORE(cur ^ 1);
;     if (kt + 2 < nk) G_LOAD(kt + 2);
;     const bf16_t* a_s = sbase + cur * G_STAGE + (wr * 64 + l15) * GLD + quad * 8;
;     const bf16_t* b_s = sbase + cur * G_STAGE + 128 * GLD + (wc * 128 + l15) * GLD + quad * 8;
;     __builtin_amdgcn_s_setprio(1);
;     bf16x8 af[4];
; #pragma unroll
;     for (int m = 0; m < 4; ++m) af[m] = *(const bf16x8*)(a_s + m * 16 * GLD);
; #pragma unroll
;     for (int nh = 0; nh < 4; ++nh) {
;       bf16x8 bfr[2];
; #pragma unroll
;       for (int n2 = 0; n2 < 2; ++n2) bfr[n2] = *(const bf16x8*)(b_s + (nh * 2 + n2) * 16 * GLD);
; #pragma unroll
;       for (int m = 0; m < 4; ++m)
; #pragma unroll
;         for (int n2 = 0; n2 < 2; ++n2) acc[m][nh * 2 + n2] = __builtin_amdgcn_mfma_f32_16x16x32_bf16(bfr[n2], af[m], acc[m][nh * 2 + n2], 0, 0, 0);
;     }
;     __builtin_amdgcn_s_setprio(0);
;     __syncthreads();
;   }
;   if (has_next) {
;     const float* Af = (const float*)nAp + (size_t)(tid >> 3) * lda + (tid & 7) * 4;
;     const bf16_t* Ab = (const bf16_t*)nAp + (size_t)(tid >> 2) * lda + (tid & 3) * 8;
;     const bf16_t* Bp = WT + (size_t)nn0 * 32 + tid * 8;
;     G_LOAD(0);
;   }
	v_mfma_f32_16x16x32_bf16 v[136:139], v[166:169], v[170:173], v[136:139]
	v_mfma_f32_16x16x32_bf16 v[190:193], v[160:163], v[174:177], v[116:119]
	v_mfma_f32_16x16x32_bf16 v[194:197], v[166:169], v[174:177], v[108:111]
	v_mfma_f32_16x16x32_bf16 v[198:201], v[160:163], v[178:181], v[84:87]
	v_mfma_f32_16x16x32_bf16 v[202:205], v[166:169], v[178:181], v[76:79]
	v_mfma_f32_16x16x32_bf16 v[160:163], v[160:163], v[182:185], v[52:55]
	s_nop 2
	ds_read_b128 v[52:55], v165 offset:15360
	v_mfma_f32_16x16x32_bf16 v[166:169], v[166:169], v[182:185], v[44:47]
	s_nop 2
	ds_read_b128 v[44:47], v165 offset:16640
	s_waitcnt lgkmcnt(1)
	v_mfma_f32_16x16x32_bf16 v[124:127], v[52:55], v[170:173], v[124:127]
	s_waitcnt lgkmcnt(0)
	v_mfma_f32_16x16x32_bf16 v[120:123], v[44:47], v[170:173], v[120:123]
	v_mfma_f32_16x16x32_bf16 v[96:99], v[52:55], v[174:177], v[96:99]
	v_mfma_f32_16x16x32_bf16 v[88:91], v[44:47], v[174:177], v[88:91]
	v_mfma_f32_16x16x32_bf16 v[64:67], v[52:55], v[178:181], v[64:67]
	v_mfma_f32_16x16x32_bf16 v[56:59], v[44:47], v[178:181], v[56:59]
	v_mfma_f32_16x16x32_bf16 v[36:39], v[52:55], v[182:185], v[36:39]
	ds_read_b128 v[52:55], v165 offset:17920
	v_mfma_f32_16x16x32_bf16 v[32:35], v[44:47], v[182:185], v[32:35]
	ds_read_b128 v[44:47], v165 offset:19200
	s_waitcnt lgkmcnt(1)
	v_mfma_f32_16x16x32_bf16 v[28:31], v[52:55], v[182:185], v[28:31]
	s_waitcnt lgkmcnt(0)
	v_mfma_f32_16x16x32_bf16 v[24:27], v[44:47], v[182:185], v[24:27]
	v_mfma_f32_16x16x32_bf16 v[206:209], v[52:55], v[170:173], v[112:115]
	v_mfma_f32_16x16x32_bf16 v[170:173], v[44:47], v[170:173], v[104:107]
	v_mfma_f32_16x16x32_bf16 v[212:215], v[52:55], v[174:177], v[80:83]
	v_mfma_f32_16x16x32_bf16 v[174:177], v[44:47], v[174:177], v[72:75]
	v_mfma_f32_16x16x32_bf16 v[216:219], v[52:55], v[178:181], v[48:51]
	v_mfma_f32_16x16x32_bf16 v[178:181], v[44:47], v[178:181], v[40:43]
	s_setprio 0
	s_barrier
	s_setprio 1
	ds_read_b128 v[40:43], v165 offset:40960
	ds_read_b128 v[44:47], v165 offset:42240
	ds_read_b128 v[182:185], v155 offset:30720
	ds_read_b128 v[220:223], v155 offset:32000
	ds_read_b128 v[224:227], v155 offset:33280
	ds_read_b128 v[228:231], v155 offset:34560
	s_waitcnt lgkmcnt(3)
	v_mfma_f32_16x16x32_bf16 v[148:151], v[40:43], v[182:185], v[148:151]
	s_waitcnt lgkmcnt(2)
	v_mfma_f32_16x16x32_bf16 v[116:119], v[40:43], v[220:223], v[132:135]
	s_waitcnt lgkmcnt(1)
	v_mfma_f32_16x16x32_bf16 v[84:87], v[40:43], v[224:227], v[100:103]
	s_waitcnt lgkmcnt(0)
	v_mfma_f32_16x16x32_bf16 v[52:55], v[40:43], v[228:231], v[68:71]
	ds_read_b128 v[40:43], v165 offset:43520
	v_mfma_f32_16x16x32_bf16 v[48:51], v[44:47], v[228:231], v[60:63]
	s_nop 2
	ds_read_b128 v[60:63], v165 offset:44800
	v_mfma_f32_16x16x32_bf16 v[140:143], v[44:47], v[182:185], v[144:147]
	v_mfma_f32_16x16x32_bf16 v[108:111], v[44:47], v[220:223], v[128:131]
	v_mfma_f32_16x16x32_bf16 v[80:83], v[44:47], v[224:227], v[92:95]
	s_waitcnt lgkmcnt(1)
	v_mfma_f32_16x16x32_bf16 v[144:147], v[40:43], v[182:185], v[186:189]
	s_nop 0
	ds_read_b128 v[92:95], v165 offset:46080
	s_waitcnt lgkmcnt(1)
	v_mfma_f32_16x16x32_bf16 v[136:139], v[60:63], v[182:185], v[136:139]
	v_mfma_f32_16x16x32_bf16 v[112:115], v[40:43], v[220:223], v[190:193]
	v_mfma_f32_16x16x32_bf16 v[104:107], v[60:63], v[220:223], v[194:197]
	v_mfma_f32_16x16x32_bf16 v[76:79], v[40:43], v[224:227], v[198:201]
	v_mfma_f32_16x16x32_bf16 v[72:75], v[60:63], v[224:227], v[202:205]
	v_mfma_f32_16x16x32_bf16 v[44:47], v[40:43], v[228:231], v[160:163]
	v_mfma_f32_16x16x32_bf16 v[40:43], v[60:63], v[228:231], v[166:169]
	ds_read_b128 v[60:63], v165 offset:47360
	s_nop 0
	ds_read_b128 v[160:163], v165 offset:48640
	ds_read_b128 v[166:169], v165 offset:49920
	s_waitcnt lgkmcnt(3)
	v_mfma_f32_16x16x32_bf16 v[132:135], v[92:95], v[182:185], v[124:127]
	s_waitcnt lgkmcnt(2)
	v_mfma_f32_16x16x32_bf16 v[128:131], v[60:63], v[182:185], v[120:123]
	v_mfma_f32_16x16x32_bf16 v[100:103], v[92:95], v[220:223], v[96:99]
	v_mfma_f32_16x16x32_bf16 v[96:99], v[60:63], v[220:223], v[88:91]
	v_mfma_f32_16x16x32_bf16 v[68:71], v[92:95], v[224:227], v[64:67]
	v_mfma_f32_16x16x32_bf16 v[64:67], v[60:63], v[224:227], v[56:59]
	v_mfma_f32_16x16x32_bf16 v[36:39], v[92:95], v[228:231], v[36:39]
	v_mfma_f32_16x16x32_bf16 v[32:35], v[60:63], v[228:231], v[32:35]
	s_waitcnt lgkmcnt(1)
	v_mfma_f32_16x16x32_bf16 v[124:127], v[160:163], v[182:185], v[206:209]
	s_waitcnt lgkmcnt(0)
	v_mfma_f32_16x16x32_bf16 v[120:123], v[166:169], v[182:185], v[170:173]
	v_mfma_f32_16x16x32_bf16 v[92:95], v[160:163], v[220:223], v[212:215]
	v_mfma_f32_16x16x32_bf16 v[88:91], v[166:169], v[220:223], v[174:177]
	v_mfma_f32_16x16x32_bf16 v[60:63], v[160:163], v[224:227], v[216:219]
	v_mfma_f32_16x16x32_bf16 v[56:59], v[166:169], v[224:227], v[178:181]
	v_mfma_f32_16x16x32_bf16 v[28:31], v[160:163], v[228:231], v[28:31]
	v_mfma_f32_16x16x32_bf16 v[24:27], v[166:169], v[228:231], v[24:27]
	s_and_b64 vcc, exec, s[46:47]
	s_barrier
	s_cbranch_vccz .LBB0_635
	s_ashr_i32 s51, s50, 31
	s_lshl_b64 s[46:47], s[50:51], 18
	s_add_u32 s46, s2, s46
	s_addc_u32 s47, s33, s47
	s_lshl_b32 s50, s66, 8
	s_ashr_i32 s51, s50, 31
	v_lshl_add_u64 v[0:1], v[158:159], 1, s[46:47]
	s_lshl_b64 s[46:47], s[50:51], 6
	v_lshl_add_u64 v[4:5], v[0:1], 0, v[152:153]
	s_add_u32 s46, s56, s46
	s_addc_u32 s47, s57, s47
	global_load_dwordx4 v[0:3], v[4:5], off sc1
	v_lshl_add_u64 v[4:5], v[4:5], 0, s[10:11]
	global_load_dwordx4 v[4:7], v[4:5], off sc1
	v_lshl_add_u64 v[20:21], v[156:157], 1, s[46:47]
	global_load_dwordx4 v[8:11], v[20:21], off sc1
	v_lshl_add_u64 v[12:13], v[20:21], 0, s[12:13]
	global_load_dwordx4 v[12:15], v[12:13], off sc1
	v_lshl_add_u64 v[16:17], v[20:21], 0, s[14:15]
	global_load_dwordx4 v[16:19], v[16:17], off sc1
	v_lshl_add_u64 v[20:21], v[20:21], 0, s[16:17]
	global_load_dwordx4 v[20:23], v[20:21], off sc1
	s_branch .LBB0_635

; #define G_LOAD(kt_) do { \
;     if constexpr (AF32) { _Pragma("unroll") for (int i = 0; i < 4; ++i) ld16_sc1(ra[i], Af + (size_t)i * 32 * lda + (kt_) * 32); } \
;     else { _Pragma("unroll") for (int i = 0; i < 2; ++i) ld16_sc1(rab[i], Ab + (size_t)i * 64 * lda + (kt_) * 32); } \
;     _Pragma("unroll") for (int i = 0; i < 4; ++i) ld16_sc1(rb[i], Bp + (size_t)(kt_) * bstep + i * 2048); } while (0)
; template <bool AF32, class Epi>
; __device__ __forceinline__ void gemm_tile(unsigned char* smem, const void* Ap, int lda, const bf16_t* WT, int N, int K, const Epi& epi, int m0, int n0,
;                                           GPre& pr, bool preloaded, const void* nAp, int nn0, bool has_next) {
;     ...
;   if (!preloaded) G_LOAD(0);
;   G_STORE(0);
;   if (nk > 1) G_LOAD(1);
;   __syncthreads();
;   for (int kt = 0; kt < nk; ++kt) {
;     const int cur = kt & 1;
;     if (kt + 1 < nk) G_STORE(cur ^ 1);
;     if (kt + 2 < nk) G_LOAD(kt + 2);
;     const bf16_t* a_s = sbase + cur * G_STAGE + (wr * 64 + l15) * GLD + quad * 8;
;     const bf16_t* b_s = sbase + cur * G_STAGE + 128 * GLD + (wc * 128 + l15) * GLD + quad * 8;
;     __builtin_amdgcn_s_setprio(1);
;     bf16x8 af[4];
; #pragma unroll
;     for (int m = 0; m < 4; ++m) af[m] = *(const bf16x8*)(a_s + m * 16 * GLD);
; #pragma unroll
;     for (int nh = 0; nh < 4; ++nh) {
;       bf16x8 bfr[2];
; #pragma unroll
;       for (int n2 = 0; n2 < 2; ++n2) bfr[n2] = *(const bf16x8*)(b_s + (nh * 2 + n2) * 16 * GLD);
; #pragma unroll
;       for (int m = 0; m < 4; ++m)
; #pragma unroll
;         for (int n2 = 0; n2 < 2; ++n2) acc[m][nh * 2 + n2] = __builtin_amdgcn_mfma_f32_16x16x32_bf16(bfr[n2], af[m], acc[m][nh * 2 + n2], 0, 0, 0);
;     }
;     __builtin_amdgcn_s_setprio(0);
;     __syncthreads();
;   }
.LBB0_678:
	s_and_b32 s3, s49, 1
	s_waitcnt vmcnt(0)
	s_xor_b32 s50, s3, 1
	s_mulk_i32 s50, 0x7800
	v_cvt_pk_bf16_f32 v202, v44, v45
	v_mov_b32_e32 v205, v44
	v_mov_b32_e32 v44, v41
	v_lshl_add_u32 v171, v160, 1, s50
	v_cvt_pk_bf16_f32 v203, v46, v47
	v_mov_b32_e32 v204, v40
	v_mov_b32_e32 v206, v42
	v_mov_b32_e32 v207, v46
	v_mov_b32_e32 v46, v43
	v_cvt_pk_bf16_f32 v40, v40, v41
	v_cvt_pk_bf16_f32 v41, v42, v43
	v_cvt_pk_bf16_f32 v42, v36, v37
	v_cvt_pk_bf16_f32 v43, v38, v39
	v_mov_b32_e32 v208, v32
	v_mov_b32_e32 v209, v36
	v_mov_b32_e32 v36, v33
	v_mov_b32_e32 v212, v34
	v_mov_b32_e32 v213, v38
	v_mov_b32_e32 v38, v35
	v_cvt_pk_bf16_f32 v32, v32, v33
	v_cvt_pk_bf16_f32 v33, v34, v35
	v_pk_mul_f32 v[34:35], v[44:45], v[44:45]
	v_lshl_add_u32 v176, v162, 1, s50
	ds_write2st64_b64 v171, v[202:203], v[40:41] offset1:5
	ds_write2st64_b64 v171, v[42:43], v[32:33] offset0:10 offset1:15
	ds_write_b128 v176, v[0:3] offset:10240
	ds_write_b128 v176, v[4:7] offset:15360
	ds_write_b128 v176, v[8:11] offset:20480
	ds_write_b128 v176, v[12:15] offset:25600
	v_pk_fma_f32 v[0:1], v[204:205], v[204:205], v[34:35]
	v_pk_mul_f32 v[36:37], v[36:37], v[36:37]
	v_pk_fma_f32 v[0:1], v[206:207], v[206:207], v[0:1]
	v_pk_fma_f32 v[2:3], v[208:209], v[208:209], v[36:37]
	v_pk_fma_f32 v[202:203], v[46:47], v[46:47], v[0:1]
	s_setprio 2
	global_load_dwordx4 v[44:47], v[166:167], off sc1
	v_lshl_add_u64 v[172:173], v[166:167], 0, s[14:15]
	v_pk_fma_f32 v[2:3], v[212:213], v[212:213], v[2:3]
	global_load_dwordx4 v[40:43], v[172:173], off sc1
	v_lshl_add_u64 v[174:175], v[166:167], 0, s[16:17]
	v_pk_fma_f32 v[204:205], v[38:39], v[38:39], v[2:3]
	global_load_dwordx4 v[36:39], v[174:175], off sc1
	v_lshl_add_u64 v[194:195], v[166:167], 0, s[18:19]
	global_load_dwordx4 v[32:35], v[194:195], off sc1
	global_load_dwordx4 v[0:3], v[164:165], off sc1
	v_lshl_add_u64 v[196:197], v[164:165], 0, s[20:21]
	global_load_dwordx4 v[4:7], v[196:197], off sc1
	v_lshl_add_u64 v[198:199], v[164:165], 0, s[22:23]
	global_load_dwordx4 v[8:11], v[198:199], off sc1
	v_lshl_add_u64 v[200:201], v[164:165], 0, s[24:25]
	global_load_dwordx4 v[12:15], v[200:201], off sc1
	s_setprio 0
	s_add_i32 s49, s49, 1
	s_mulk_i32 s3, 0x7800
	v_pk_add_f32 v[184:185], v[184:185], v[202:203]
	v_pk_add_f32 v[180:181], v[180:181], v[204:205]
	v_add3_u32 v171, s3, v169, v170
	s_setprio 1
	v_add3_u32 v176, s3, v168, v170
	ds_read_b128 v[172:175], v176 offset:10240
	ds_read_b128 v[194:197], v176 offset:11520
	ds_read_b128 v[198:201], v171
	ds_read_b128 v[202:205], v171 offset:1280
	ds_read_b128 v[206:209], v171 offset:2560
	ds_read_b128 v[212:215], v171 offset:3840
	s_waitcnt lgkmcnt(3)
	v_mfma_f32_16x16x32_bf16 v[156:159], v[172:175], v[198:201], v[156:159]
	v_mfma_f32_16x16x32_bf16 v[152:155], v[194:197], v[198:201], v[152:155]
	s_waitcnt lgkmcnt(2)
	v_mfma_f32_16x16x32_bf16 v[140:143], v[172:175], v[202:205], v[140:143]
	v_mfma_f32_16x16x32_bf16 v[136:139], v[194:197], v[202:205], v[136:139]
	s_waitcnt lgkmcnt(1)
	v_mfma_f32_16x16x32_bf16 v[108:111], v[172:175], v[206:209], v[108:111]
	v_mfma_f32_16x16x32_bf16 v[100:103], v[194:197], v[206:209], v[100:103]
	s_waitcnt lgkmcnt(0)
	v_mfma_f32_16x16x32_bf16 v[76:79], v[172:175], v[212:215], v[76:79]
	ds_read_b128 v[172:175], v176 offset:12800
	v_mfma_f32_16x16x32_bf16 v[68:71], v[194:197], v[212:215], v[68:71]
	ds_read_b128 v[194:197], v176 offset:14080
	s_waitcnt lgkmcnt(1)
	v_mfma_f32_16x16x32_bf16 v[148:151], v[172:175], v[198:201], v[148:151]
	s_waitcnt lgkmcnt(0)
	v_mfma_f32_16x16x32_bf16 v[144:147], v[194:197], v[198:201], v[144:147]
	v_mfma_f32_16x16x32_bf16 v[124:127], v[172:175], v[202:205], v[124:127]
	v_mfma_f32_16x16x32_bf16 v[116:119], v[194:197], v[202:205], v[116:119]
	v_mfma_f32_16x16x32_bf16 v[92:95], v[172:175], v[206:209], v[92:95]
	v_mfma_f32_16x16x32_bf16 v[84:87], v[194:197], v[206:209], v[84:87]
	v_mfma_f32_16x16x32_bf16 v[60:63], v[172:175], v[212:215], v[60:63]
	ds_read_b128 v[172:175], v176 offset:15360
	v_mfma_f32_16x16x32_bf16 v[52:55], v[194:197], v[212:215], v[52:55]
	ds_read_b128 v[194:197], v176 offset:16640
	s_waitcnt lgkmcnt(1)
	v_mfma_f32_16x16x32_bf16 v[132:135], v[172:175], v[198:201], v[132:135]
	s_waitcnt lgkmcnt(0)
	v_mfma_f32_16x16x32_bf16 v[128:131], v[194:197], v[198:201], v[128:131]
	v_mfma_f32_16x16x32_bf16 v[104:107], v[172:175], v[202:205], v[104:107]
	v_mfma_f32_16x16x32_bf16 v[96:99], v[194:197], v[202:205], v[96:99]
	v_mfma_f32_16x16x32_bf16 v[72:75], v[172:175], v[206:209], v[72:75]
	v_mfma_f32_16x16x32_bf16 v[64:67], v[194:197], v[206:209], v[64:67]
	v_mfma_f32_16x16x32_bf16 v[28:31], v[172:175], v[212:215], v[28:31]
	ds_read_b128 v[172:175], v176 offset:17920
	v_mfma_f32_16x16x32_bf16 v[24:27], v[194:197], v[212:215], v[24:27]
	ds_read_b128 v[194:197], v176 offset:19200
	s_waitcnt lgkmcnt(1)
	v_mfma_f32_16x16x32_bf16 v[120:123], v[172:175], v[198:201], v[120:123]
	s_waitcnt lgkmcnt(0)
	v_mfma_f32_16x16x32_bf16 v[112:115], v[194:197], v[198:201], v[112:115]
	v_mfma_f32_16x16x32_bf16 v[88:91], v[172:175], v[202:205], v[88:91]
	v_mfma_f32_16x16x32_bf16 v[80:83], v[194:197], v[202:205], v[80:83]
	v_mfma_f32_16x16x32_bf16 v[56:59], v[172:175], v[206:209], v[56:59]
	v_mfma_f32_16x16x32_bf16 v[48:51], v[194:197], v[206:209], v[48:51]
	v_mfma_f32_16x16x32_bf16 v[20:23], v[172:175], v[212:215], v[20:23]
	v_mfma_f32_16x16x32_bf16 v[16:19], v[194:197], v[212:215], v[16:19]
	s_setprio 0
	v_lshl_add_u64 v[164:165], v[164:165], 0, s[36:37]
	s_cmp_eq_u32 s49, 30
	v_lshl_add_u64 v[166:167], v[166:167], 0, s[26:27]
	s_barrier
	s_cbranch_scc0 .LBB0_678
; #define G_LOAD(kt_) do { \
;     if constexpr (AF32) { _Pragma("unroll") for (int i = 0; i < 4; ++i) ld16_sc1(ra[i], Af + (size_t)i * 32 * lda + (kt_) * 32); } \
;     else { _Pragma("unroll") for (int i = 0; i < 2; ++i) ld16_sc1(rab[i], Ab + (size_t)i * 64 * lda + (kt_) * 32); } \
;     _Pragma("unroll") for (int i = 0; i < 4; ++i) ld16_sc1(rb[i], Bp + (size_t)(kt_) * bstep + i * 2048); } while (0)
; template <bool AF32, class Epi>
; __device__ __forceinline__ void gemm_tile(unsigned char* smem, const void* Ap, int lda, const bf16_t* WT, int N, int K, const Epi& epi, int m0, int n0,
;                                           GPre& pr, bool preloaded, const void* nAp, int nn0, bool has_next) {
;     ...
;   for (int kt = 0; kt < nk; ++kt) {
;     const int cur = kt & 1;
;     if (kt + 1 < nk) G_STORE(cur ^ 1);
;     if (kt + 2 < nk) G_LOAD(kt + 2);
;     const bf16_t* a_s = sbase + cur * G_STAGE + (wr * 64 + l15) * GLD + quad * 8;
;     const bf16_t* b_s = sbase + cur * G_STAGE + 128 * GLD + (wc * 128 + l15) * GLD + quad * 8;
;     __builtin_amdgcn_s_setprio(1);
;     bf16x8 af[4];
; #pragma unroll
;     for (int m = 0; m < 4; ++m) af[m] = *(const bf16x8*)(a_s + m * 16 * GLD);
; #pragma unroll
;     for (int nh = 0; nh < 4; ++nh) {
;       bf16x8 bfr[2];
; #pragma unroll
;       for (int n2 = 0; n2 < 2; ++n2) bfr[n2] = *(const bf16x8*)(b_s + (nh * 2 + n2) * 16 * GLD);
; #pragma unroll
;       for (int m = 0; m < 4; ++m)
; #pragma unroll
;         for (int n2 = 0; n2 < 2; ++n2) acc[m][nh * 2 + n2] = __builtin_amdgcn_mfma_f32_16x16x32_bf16(bfr[n2], af[m], acc[m][nh * 2 + n2], 0, 0, 0);
;     }
;     __builtin_amdgcn_s_setprio(0);
;     __syncthreads();
	s_waitcnt vmcnt(0)
	v_add_u32_e32 v176, v169, v170
	v_cvt_pk_bf16_f32 v164, v44, v45
	v_cvt_pk_bf16_f32 v165, v46, v47
	v_cvt_pk_bf16_f32 v166, v40, v41
	v_cvt_pk_bf16_f32 v167, v42, v43
	ds_write2st64_b64 v161, v[164:165], v[166:167] offset0:60 offset1:65
	v_cvt_pk_bf16_f32 v164, v36, v37
	v_cvt_pk_bf16_f32 v165, v38, v39
	v_cvt_pk_bf16_f32 v166, v32, v33
	v_cvt_pk_bf16_f32 v167, v34, v35
	ds_write2st64_b64 v161, v[164:165], v[166:167] offset0:70 offset1:75
	ds_write_b128 v163, v[0:3] offset:40960
	ds_write_b128 v163, v[4:7] offset:46080
	ds_write_b128 v163, v[8:11] offset:51200
	ds_write_b128 v163, v[12:15] offset:56320
	s_setprio 1
	v_add_u32_e32 v193, v168, v170
	ds_read_b128 v[160:163], v193 offset:10240
	ds_read_b128 v[164:167], v193 offset:11520
	ds_read_b128 v[168:171], v176
	ds_read_b128 v[172:175], v176 offset:1280
	ds_read_b128 v[194:197], v176 offset:2560
	ds_read_b128 v[198:201], v176 offset:3840
	s_waitcnt lgkmcnt(3)
	v_mfma_f32_16x16x32_bf16 v[156:159], v[160:163], v[168:171], v[156:159]
	v_mfma_f32_16x16x32_bf16 v[152:155], v[164:167], v[168:171], v[152:155]
	s_waitcnt lgkmcnt(2)
	v_mfma_f32_16x16x32_bf16 v[140:143], v[160:163], v[172:175], v[140:143]
	v_mfma_f32_16x16x32_bf16 v[136:139], v[164:167], v[172:175], v[136:139]
	s_waitcnt lgkmcnt(1)
	v_mfma_f32_16x16x32_bf16 v[108:111], v[160:163], v[194:197], v[108:111]
	v_mfma_f32_16x16x32_bf16 v[100:103], v[164:167], v[194:197], v[100:103]
	s_waitcnt lgkmcnt(0)
	v_mfma_f32_16x16x32_bf16 v[76:79], v[160:163], v[198:201], v[76:79]
	ds_read_b128 v[160:163], v193 offset:12800
	v_mfma_f32_16x16x32_bf16 v[68:71], v[164:167], v[198:201], v[68:71]
	ds_read_b128 v[164:167], v193 offset:14080
	s_waitcnt lgkmcnt(1)
	v_mfma_f32_16x16x32_bf16 v[148:151], v[160:163], v[168:171], v[148:151]
	s_waitcnt lgkmcnt(0)
	v_mfma_f32_16x16x32_bf16 v[144:147], v[164:167], v[168:171], v[144:147]
	v_mfma_f32_16x16x32_bf16 v[124:127], v[160:163], v[172:175], v[124:127]
	v_mfma_f32_16x16x32_bf16 v[116:119], v[164:167], v[172:175], v[116:119]
	v_mfma_f32_16x16x32_bf16 v[92:95], v[160:163], v[194:197], v[92:95]
	v_mfma_f32_16x16x32_bf16 v[84:87], v[164:167], v[194:197], v[84:87]
	v_mfma_f32_16x16x32_bf16 v[60:63], v[160:163], v[198:201], v[60:63]
	ds_read_b128 v[160:163], v193 offset:15360
	v_mfma_f32_16x16x32_bf16 v[52:55], v[164:167], v[198:201], v[52:55]
	ds_read_b128 v[164:167], v193 offset:16640
	s_waitcnt lgkmcnt(1)
	v_mfma_f32_16x16x32_bf16 v[220:223], v[160:163], v[194:197], v[72:75]
	s_nop 2
	ds_read_b128 v[72:75], v193 offset:19200
	s_waitcnt lgkmcnt(1)
	v_mfma_f32_16x16x32_bf16 v[224:227], v[164:167], v[194:197], v[64:67]
	s_nop 2
	ds_read_b128 v[64:67], v193 offset:17920
	s_waitcnt lgkmcnt(1)
	v_mfma_f32_16x16x32_bf16 v[112:115], v[72:75], v[168:171], v[112:115]
	v_mfma_f32_16x16x32_bf16 v[80:83], v[72:75], v[172:175], v[80:83]
	v_mfma_f32_16x16x32_bf16 v[48:51], v[72:75], v[194:197], v[48:51]
	v_mfma_f32_16x16x32_bf16 v[202:205], v[160:163], v[168:171], v[132:135]
	v_mfma_f32_16x16x32_bf16 v[206:209], v[164:167], v[168:171], v[128:131]
	v_mfma_f32_16x16x32_bf16 v[212:215], v[160:163], v[172:175], v[104:107]
	v_mfma_f32_16x16x32_bf16 v[216:219], v[164:167], v[172:175], v[96:99]
	v_mfma_f32_16x16x32_bf16 v[28:31], v[160:163], v[198:201], v[28:31]
	v_mfma_f32_16x16x32_bf16 v[24:27], v[164:167], v[198:201], v[24:27]
	s_waitcnt lgkmcnt(0)
	v_mfma_f32_16x16x32_bf16 v[228:231], v[64:67], v[168:171], v[120:123]
	v_mfma_f32_16x16x32_bf16 v[232:235], v[64:67], v[172:175], v[88:91]
	v_mfma_f32_16x16x32_bf16 v[236:239], v[64:67], v[194:197], v[56:59]
	v_mfma_f32_16x16x32_bf16 v[20:23], v[64:67], v[198:201], v[20:23]
	v_mfma_f32_16x16x32_bf16 v[16:19], v[72:75], v[198:201], v[16:19]
	s_setprio 0
	s_barrier
; #define G_LOAD(kt_) do { \
;     if constexpr (AF32) { _Pragma("unroll") for (int i = 0; i < 4; ++i) ld16_sc1(ra[i], Af + (size_t)i * 32 * lda + (kt_) * 32); } \
;     else { _Pragma("unroll") for (int i = 0; i < 2; ++i) ld16_sc1(rab[i], Ab + (size_t)i * 64 * lda + (kt_) * 32); } \
;     _Pragma("unroll") for (int i = 0; i < 4; ++i) ld16_sc1(rb[i], Bp + (size_t)(kt_) * bstep + i * 2048); } while (0)
; template <bool AF32, class Epi>
; __device__ __forceinline__ void gemm_tile(unsigned char* smem, const void* Ap, int lda, const bf16_t* WT, int N, int K, const Epi& epi, int m0, int n0,
;                                           GPre& pr, bool preloaded, const void* nAp, int nn0, bool has_next) {
;     ...
;     for (int nh = 0; nh < 4; ++nh) {
;       bf16x8 bfr[2];
; #pragma unroll
;       for (int n2 = 0; n2 < 2; ++n2) bfr[n2] = *(const bf16x8*)(b_s + (nh * 2 + n2) * 16 * GLD);
; #pragma unroll
;       for (int m = 0; m < 4; ++m)
; #pragma unroll
;         for (int n2 = 0; n2 < 2; ++n2) acc[m][nh * 2 + n2] = __builtin_amdgcn_mfma_f32_16x16x32_bf16(bfr[n2], af[m], acc[m][nh * 2 + n2], 0, 0, 0);
;     }
;     __builtin_amdgcn_s_setprio(0);
;     __syncthreads();
;   }
;   if (has_next) {
;     const float* Af = (const float*)nAp + (size_t)(tid >> 3) * lda + (tid & 7) * 4;
;     const bf16_t* Ab = (const bf16_t*)nAp + (size_t)(tid >> 2) * lda + (tid & 3) * 8;
;     const bf16_t* Bp = WT + (size_t)nn0 * 32 + tid * 8;
;     G_LOAD(0);
;   }
	s_setprio 1
	ds_read_b128 v[56:59], v193 offset:40960
	ds_read_b128 v[64:67], v193 offset:42240
	ds_read_b128 v[194:197], v176 offset:30720
	ds_read_b128 v[198:201], v176 offset:32000
	ds_read_b128 v[240:243], v176 offset:33280
	ds_read_b128 v[244:247], v176 offset:34560
	s_waitcnt lgkmcnt(3)
	v_mfma_f32_16x16x32_bf16 v[172:175], v[56:59], v[194:197], v[156:159]
	v_mfma_f32_16x16x32_bf16 v[168:171], v[64:67], v[194:197], v[152:155]
	s_waitcnt lgkmcnt(2)
	v_mfma_f32_16x16x32_bf16 v[140:143], v[56:59], v[198:201], v[140:143]
	v_mfma_f32_16x16x32_bf16 v[136:139], v[64:67], v[198:201], v[136:139]
	s_waitcnt lgkmcnt(1)
	v_mfma_f32_16x16x32_bf16 v[108:111], v[56:59], v[240:243], v[108:111]
	v_mfma_f32_16x16x32_bf16 v[104:107], v[64:67], v[240:243], v[100:103]
	s_waitcnt lgkmcnt(0)
	v_mfma_f32_16x16x32_bf16 v[76:79], v[56:59], v[244:247], v[76:79]
	ds_read_b128 v[56:59], v193 offset:43520
	v_mfma_f32_16x16x32_bf16 v[72:75], v[64:67], v[244:247], v[68:71]
	ds_read_b128 v[64:67], v193 offset:44800
	s_waitcnt lgkmcnt(1)
	v_mfma_f32_16x16x32_bf16 v[164:167], v[56:59], v[194:197], v[148:151]
	s_waitcnt lgkmcnt(0)
	v_mfma_f32_16x16x32_bf16 v[160:163], v[64:67], v[194:197], v[144:147]
	v_mfma_f32_16x16x32_bf16 v[132:135], v[56:59], v[198:201], v[124:127]
	v_mfma_f32_16x16x32_bf16 v[128:131], v[64:67], v[198:201], v[116:119]
	v_mfma_f32_16x16x32_bf16 v[100:103], v[56:59], v[240:243], v[92:95]
	v_mfma_f32_16x16x32_bf16 v[96:99], v[64:67], v[240:243], v[84:87]
	v_mfma_f32_16x16x32_bf16 v[68:71], v[56:59], v[244:247], v[60:63]
	ds_read_b128 v[56:59], v193 offset:46080
	v_mfma_f32_16x16x32_bf16 v[64:67], v[64:67], v[244:247], v[52:55]
	s_nop 2
	ds_read_b128 v[52:55], v193 offset:47360
	s_waitcnt lgkmcnt(1)
	v_mfma_f32_16x16x32_bf16 v[156:159], v[56:59], v[194:197], v[202:205]
	v_mfma_f32_16x16x32_bf16 v[124:127], v[56:59], v[198:201], v[212:215]
	v_mfma_f32_16x16x32_bf16 v[92:95], v[56:59], v[240:243], v[220:223]
	v_mfma_f32_16x16x32_bf16 v[60:63], v[56:59], v[244:247], v[28:31]
	s_nop 2
	ds_read_b128 v[28:31], v193 offset:48640
	s_waitcnt lgkmcnt(1)
	v_mfma_f32_16x16x32_bf16 v[56:59], v[52:55], v[244:247], v[24:27]
	s_nop 2
	ds_read_b128 v[24:27], v193 offset:49920
	v_mfma_f32_16x16x32_bf16 v[152:155], v[52:55], v[194:197], v[206:209]
	v_mfma_f32_16x16x32_bf16 v[120:123], v[52:55], v[198:201], v[216:219]
	v_mfma_f32_16x16x32_bf16 v[88:91], v[52:55], v[240:243], v[224:227]
	s_waitcnt lgkmcnt(1)
	v_mfma_f32_16x16x32_bf16 v[148:151], v[28:31], v[194:197], v[228:231]
	s_waitcnt lgkmcnt(0)
	v_mfma_f32_16x16x32_bf16 v[144:147], v[24:27], v[194:197], v[112:115]
	v_mfma_f32_16x16x32_bf16 v[116:119], v[28:31], v[198:201], v[232:235]
	v_mfma_f32_16x16x32_bf16 v[112:115], v[24:27], v[198:201], v[80:83]
	v_mfma_f32_16x16x32_bf16 v[84:87], v[28:31], v[240:243], v[236:239]
	v_mfma_f32_16x16x32_bf16 v[80:83], v[24:27], v[240:243], v[48:51]
	v_mfma_f32_16x16x32_bf16 v[52:55], v[28:31], v[244:247], v[20:23]
	v_mfma_f32_16x16x32_bf16 v[48:51], v[24:27], v[244:247], v[16:19]
	s_and_b64 vcc, exec, s[6:7]
	s_barrier
	s_cbranch_vccz .LBB0_681
	s_ashr_i32 s49, s48, 31
	s_lshl_b64 s[6:7], s[48:49], 19
	s_add_u32 s6, s10, s6
	s_addc_u32 s7, s11, s7
	s_lshl_b32 s48, s65, 8
	v_lshl_add_u64 v[0:1], v[186:187], 2, s[6:7]
	v_lshlrev_b32_e32 v176, 2, v188
	s_ashr_i32 s49, s48, 31
	v_lshl_add_u64 v[0:1], v[0:1], 0, v[176:177]
	s_lshl_b64 s[6:7], s[48:49], 6
	global_load_dwordx4 v[24:27], v[0:1], off sc1
	s_add_u32 s6, s2, s6
	v_lshl_add_u64 v[2:3], v[0:1], 0, s[14:15]
	global_load_dwordx4 v[28:31], v[2:3], off sc1
	s_addc_u32 s7, s33, s7
	v_lshl_add_u64 v[2:3], v[0:1], 0, s[16:17]
	global_load_dwordx4 v[16:19], v[2:3], off sc1
	v_lshl_add_u64 v[0:1], v[0:1], 0, s[18:19]
	global_load_dwordx4 v[20:23], v[0:1], off sc1
	v_lshl_add_u64 v[12:13], v[182:183], 1, s[6:7]
	global_load_dwordx4 v[0:3], v[12:13], off sc1
	v_lshl_add_u64 v[4:5], v[12:13], 0, s[20:21]
	global_load_dwordx4 v[4:7], v[4:5], off sc1
	v_lshl_add_u64 v[8:9], v[12:13], 0, s[22:23]
	global_load_dwordx4 v[8:11], v[8:9], off sc1
	v_lshl_add_u64 v[12:13], v[12:13], 0, s[24:25]
	global_load_dwordx4 v[12:15], v[12:13], off sc1
	s_branch .LBB0_682

; #define G_LOAD(kt_) do { \
;     if constexpr (AF32) { _Pragma("unroll") for (int i = 0; i < 4; ++i) ld16_sc1(ra[i], Af + (size_t)i * 32 * lda + (kt_) * 32); } \
;     else { _Pragma("unroll") for (int i = 0; i < 2; ++i) ld16_sc1(rab[i], Ab + (size_t)i * 64 * lda + (kt_) * 32); } \
;     _Pragma("unroll") for (int i = 0; i < 4; ++i) ld16_sc1(rb[i], Bp + (size_t)(kt_) * bstep + i * 2048); } while (0)
; template <bool AF32, class Epi>
; __device__ __forceinline__ void gemm_tile(unsigned char* smem, const void* Ap, int lda, const bf16_t* WT, int N, int K, const Epi& epi, int m0, int n0,
;                                           GPre& pr, bool preloaded, const void* nAp, int nn0, bool has_next) {
;     ...
;   if (!preloaded) G_LOAD(0);
;   G_STORE(0);
;   if (nk > 1) G_LOAD(1);
;   __syncthreads();
;   for (int kt = 0; kt < nk; ++kt) {
;     const int cur = kt & 1;
;     if (kt + 1 < nk) G_STORE(cur ^ 1);
;     if (kt + 2 < nk) G_LOAD(kt + 2);
;     const bf16_t* a_s = sbase + cur * G_STAGE + (wr * 64 + l15) * GLD + quad * 8;
;     const bf16_t* b_s = sbase + cur * G_STAGE + 128 * GLD + (wc * 128 + l15) * GLD + quad * 8;
;     __builtin_amdgcn_s_setprio(1);
;     bf16x8 af[4];
; #pragma unroll
;     for (int m = 0; m < 4; ++m) af[m] = *(const bf16x8*)(a_s + m * 16 * GLD);
; #pragma unroll
;     for (int nh = 0; nh < 4; ++nh) {
;       bf16x8 bfr[2];
; #pragma unroll
;       for (int n2 = 0; n2 < 2; ++n2) bfr[n2] = *(const bf16x8*)(b_s + (nh * 2 + n2) * 16 * GLD);
; #pragma unroll
;       for (int m = 0; m < 4; ++m)
; #pragma unroll
;         for (int n2 = 0; n2 < 2; ++n2) acc[m][nh * 2 + n2] = __builtin_amdgcn_mfma_f32_16x16x32_bf16(bfr[n2], af[m], acc[m][nh * 2 + n2], 0, 0, 0);
;     }
;     __builtin_amdgcn_s_setprio(0);
;     __syncthreads();
;   }
.LBB0_718:
	s_and_b32 s3, s50, 1
	s_waitcnt vmcnt(0)
	s_xor_b32 s51, s3, 1
	s_mulk_i32 s51, 0x7800
	v_add_u32_e32 v176, s51, v155
	ds_write_b128 v176, v[0:3]
	ds_write_b128 v176, v[4:7] offset:5120
	ds_write_b128 v176, v[8:11] offset:10240
	ds_write_b128 v176, v[12:15] offset:15360
	ds_write_b128 v176, v[16:19] offset:20480
	ds_write_b128 v176, v[20:23] offset:25600
	s_setprio 2
	global_load_dwordx4 v[0:3], v[162:163], off sc1
	v_lshl_add_u64 v[168:169], v[162:163], 0, s[10:11]
	global_load_dwordx4 v[4:7], v[168:169], off sc1
	global_load_dwordx4 v[8:11], v[160:161], off sc1
	v_lshl_add_u64 v[170:171], v[160:161], 0, s[12:13]
	global_load_dwordx4 v[12:15], v[170:171], off sc1
	v_lshl_add_u64 v[172:173], v[160:161], 0, s[14:15]
	global_load_dwordx4 v[16:19], v[172:173], off sc1
	v_lshl_add_u64 v[174:175], v[160:161], 0, s[16:17]
	global_load_dwordx4 v[20:23], v[174:175], off sc1
	s_setprio 0
	s_add_i32 s50, s50, 1
	s_mulk_i32 s3, 0x7800
	v_add3_u32 v188, s3, v166, v167
	s_setprio 1
	v_add3_u32 v192, s3, v165, v167
	ds_read_b128 v[168:171], v192 offset:10240
	ds_read_b128 v[172:175], v192 offset:11520
	ds_read_b128 v[176:179], v188
	ds_read_b128 v[180:183], v188 offset:1280
	ds_read_b128 v[184:187], v188 offset:2560
	ds_read_b128 v[188:191], v188 offset:3840
	s_waitcnt lgkmcnt(3)
	v_mfma_f32_16x16x32_bf16 v[148:151], v[168:171], v[176:179], v[148:151]
	v_mfma_f32_16x16x32_bf16 v[144:147], v[172:175], v[176:179], v[144:147]
	s_waitcnt lgkmcnt(2)
	v_mfma_f32_16x16x32_bf16 v[132:135], v[168:171], v[180:183], v[132:135]
	v_mfma_f32_16x16x32_bf16 v[128:131], v[172:175], v[180:183], v[128:131]
	s_waitcnt lgkmcnt(1)
	v_mfma_f32_16x16x32_bf16 v[100:103], v[168:171], v[184:187], v[100:103]
	v_mfma_f32_16x16x32_bf16 v[92:95], v[172:175], v[184:187], v[92:95]
	s_waitcnt lgkmcnt(0)
	v_mfma_f32_16x16x32_bf16 v[68:71], v[168:171], v[188:191], v[68:71]
	ds_read_b128 v[168:171], v192 offset:12800
	v_mfma_f32_16x16x32_bf16 v[60:63], v[172:175], v[188:191], v[60:63]
	ds_read_b128 v[172:175], v192 offset:14080
	s_waitcnt lgkmcnt(1)
	v_mfma_f32_16x16x32_bf16 v[140:143], v[168:171], v[176:179], v[140:143]
	s_waitcnt lgkmcnt(0)
	v_mfma_f32_16x16x32_bf16 v[136:139], v[172:175], v[176:179], v[136:139]
	v_mfma_f32_16x16x32_bf16 v[116:119], v[168:171], v[180:183], v[116:119]
	v_mfma_f32_16x16x32_bf16 v[108:111], v[172:175], v[180:183], v[108:111]
	v_mfma_f32_16x16x32_bf16 v[84:87], v[168:171], v[184:187], v[84:87]
	v_mfma_f32_16x16x32_bf16 v[76:79], v[172:175], v[184:187], v[76:79]
	v_mfma_f32_16x16x32_bf16 v[52:55], v[168:171], v[188:191], v[52:55]
	ds_read_b128 v[168:171], v192 offset:15360
	v_mfma_f32_16x16x32_bf16 v[44:47], v[172:175], v[188:191], v[44:47]
	ds_read_b128 v[172:175], v192 offset:16640
	s_waitcnt lgkmcnt(1)
	v_mfma_f32_16x16x32_bf16 v[124:127], v[168:171], v[176:179], v[124:127]
	s_waitcnt lgkmcnt(0)
	v_mfma_f32_16x16x32_bf16 v[120:123], v[172:175], v[176:179], v[120:123]
	v_mfma_f32_16x16x32_bf16 v[96:99], v[168:171], v[180:183], v[96:99]
	v_mfma_f32_16x16x32_bf16 v[88:91], v[172:175], v[180:183], v[88:91]
	v_mfma_f32_16x16x32_bf16 v[64:67], v[168:171], v[184:187], v[64:67]
	v_mfma_f32_16x16x32_bf16 v[56:59], v[172:175], v[184:187], v[56:59]
	v_mfma_f32_16x16x32_bf16 v[36:39], v[168:171], v[188:191], v[36:39]
	ds_read_b128 v[168:171], v192 offset:17920
	v_mfma_f32_16x16x32_bf16 v[32:35], v[172:175], v[188:191], v[32:35]
	ds_read_b128 v[172:175], v192 offset:19200
	s_waitcnt lgkmcnt(1)
	v_mfma_f32_16x16x32_bf16 v[112:115], v[168:171], v[176:179], v[112:115]
	s_waitcnt lgkmcnt(0)
	v_mfma_f32_16x16x32_bf16 v[104:107], v[172:175], v[176:179], v[104:107]
	v_mfma_f32_16x16x32_bf16 v[80:83], v[168:171], v[180:183], v[80:83]
	v_mfma_f32_16x16x32_bf16 v[72:75], v[172:175], v[180:183], v[72:75]
	v_mfma_f32_16x16x32_bf16 v[48:51], v[168:171], v[184:187], v[48:51]
	v_mfma_f32_16x16x32_bf16 v[40:43], v[172:175], v[184:187], v[40:43]
	v_mfma_f32_16x16x32_bf16 v[28:31], v[168:171], v[188:191], v[28:31]
	v_mfma_f32_16x16x32_bf16 v[24:27], v[172:175], v[188:191], v[24:27]
	s_setprio 0
	v_lshl_add_u64 v[160:161], v[160:161], 0, s[20:21]
	s_cmpk_eq_i32 s50, 0x56
	v_lshl_add_u64 v[162:163], v[162:163], 0, 64
	s_barrier
	s_cbranch_scc0 .LBB0_718
	s_waitcnt vmcnt(0)
	ds_write_b128 v155, v[0:3] offset:30720
	ds_write_b128 v155, v[4:7] offset:35840
	ds_write_b128 v155, v[8:11] offset:40960
	ds_write_b128 v155, v[12:15] offset:46080
	ds_write_b128 v155, v[16:19] offset:51200
	ds_write_b128 v155, v[20:23] offset:56320
	v_add_u32_e32 v155, v166, v167
	s_setprio 1
	v_add_u32_e32 v165, v165, v167
	ds_read_b128 v[160:163], v165 offset:10240
	ds_read_b128 v[166:169], v165 offset:11520
	ds_read_b128 v[170:173], v155
	ds_read_b128 v[174:177], v155 offset:1280
	ds_read_b128 v[178:181], v155 offset:2560
	ds_read_b128 v[182:185], v155 offset:3840
	s_waitcnt lgkmcnt(3)
	v_mfma_f32_16x16x32_bf16 v[148:151], v[160:163], v[170:173], v[148:151]
	v_mfma_f32_16x16x32_bf16 v[144:147], v[166:169], v[170:173], v[144:147]
	s_waitcnt lgkmcnt(2)
	v_mfma_f32_16x16x32_bf16 v[132:135], v[160:163], v[174:177], v[132:135]
	v_mfma_f32_16x16x32_bf16 v[128:131], v[166:169], v[174:177], v[128:131]
	s_waitcnt lgkmcnt(1)
	v_mfma_f32_16x16x32_bf16 v[100:103], v[160:163], v[178:181], v[100:103]
	v_mfma_f32_16x16x32_bf16 v[92:95], v[166:169], v[178:181], v[92:95]
	s_waitcnt lgkmcnt(0)
	v_mfma_f32_16x16x32_bf16 v[68:71], v[160:163], v[182:185], v[68:71]
	ds_read_b128 v[160:163], v165 offset:12800
	v_mfma_f32_16x16x32_bf16 v[60:63], v[166:169], v[182:185], v[60:63]
	ds_read_b128 v[166:169], v165 offset:14080
	s_waitcnt lgkmcnt(1)
	v_mfma_f32_16x16x32_bf16 v[186:189], v[160:163], v[170:173], v[140:143]
	s_waitcnt lgkmcnt(0)
; #define G_LOAD(kt_) do { \
;     if constexpr (AF32) { _Pragma("unroll") for (int i = 0; i < 4; ++i) ld16_sc1(ra[i], Af + (size_t)i * 32 * lda + (kt_) * 32); } \
;     else { _Pragma("unroll") for (int i = 0; i < 2; ++i) ld16_sc1(rab[i], Ab + (size_t)i * 64 * lda + (kt_) * 32); } \
;     _Pragma("unroll") for (int i = 0; i < 4; ++i) ld16_sc1(rb[i], Bp + (size_t)(kt_) * bstep + i * 2048); } while (0)
; template <bool AF32, class Epi>
; __device__ __forceinline__ void gemm_tile(unsigned char* smem, const void* Ap, int lda, const bf16_t* WT, int N, int K, const Epi& epi, int m0, int n0,
;                                           GPre& pr, bool preloaded, const void* nAp, int nn0, bool has_next) {
;     ...
;   for (int kt = 0; kt < nk; ++kt) {
;     const int cur = kt & 1;
;     if (kt + 1 < nk) G_STORE(cur ^ 1);
;     if (kt + 2 < nk) G_LOAD(kt + 2);
;     const bf16_t* a_s = sbase + cur * G_STAGE + (wr * 64 + l15) * GLD + quad * 8;
;     const bf16_t* b_s = sbase + cur * G_STAGE + 128 * GLD + (wc * 128 + l15) * GLD + quad * 8;
;     __builtin_amdgcn_s_setprio(1);
;     bf16x8 af[4];
; #pragma unroll
;     for (int m = 0; m < 4; ++m) af[m] = *(const bf16x8*)(a_s + m * 16 * GLD);
; #pragma unroll
;     for (int nh = 0; nh < 4; ++nh) {
;       bf16x8 bfr[2];
; #pragma unroll
;       for (int n2 = 0; n2 < 2; ++n2) bfr[n2] = *(const bf16x8*)(b_s + (nh * 2 + n2) * 16 * GLD);
; #pragma unroll
;       for (int m = 0; m < 4; ++m)
; #pragma unroll
;         for (int n2 = 0; n2 < 2; ++n2) acc[m][nh * 2 + n2] = __builtin_amdgcn_mfma_f32_16x16x32_bf16(bfr[n2], af[m], acc[m][nh * 2 + n2], 0, 0, 0);
;     }
;     __builtin_amdgcn_s_setprio(0);
;     __syncthreads();
;   }
;   if (has_next) {
;     const float* Af = (const float*)nAp + (size_t)(tid >> 3) * lda + (tid & 7) * 4;
;     const bf16_t* Ab = (const bf16_t*)nAp + (size_t)(tid >> 2) * lda + (tid & 3) * 8;
;     const bf16_t* Bp = WT + (size_t)nn0 * 32 + tid * 8;
;     G_LOAD(0);
;   }
	v_mfma_f32_16x16x32_bf16 v[136:139], v[166:169], v[170:173], v[136:139]
	v_mfma_f32_16x16x32_bf16 v[190:193], v[160:163], v[174:177], v[116:119]
	v_mfma_f32_16x16x32_bf16 v[194:197], v[166:169], v[174:177], v[108:111]
	v_mfma_f32_16x16x32_bf16 v[198:201], v[160:163], v[178:181], v[84:87]
	v_mfma_f32_16x16x32_bf16 v[202:205], v[166:169], v[178:181], v[76:79]
	v_mfma_f32_16x16x32_bf16 v[160:163], v[160:163], v[182:185], v[52:55]
	s_nop 2
	ds_read_b128 v[52:55], v165 offset:15360
	v_mfma_f32_16x16x32_bf16 v[166:169], v[166:169], v[182:185], v[44:47]
	s_nop 2
	ds_read_b128 v[44:47], v165 offset:16640
	s_waitcnt lgkmcnt(1)
	v_mfma_f32_16x16x32_bf16 v[124:127], v[52:55], v[170:173], v[124:127]
	s_waitcnt lgkmcnt(0)
	v_mfma_f32_16x16x32_bf16 v[120:123], v[44:47], v[170:173], v[120:123]
	v_mfma_f32_16x16x32_bf16 v[96:99], v[52:55], v[174:177], v[96:99]
	v_mfma_f32_16x16x32_bf16 v[88:91], v[44:47], v[174:177], v[88:91]
	v_mfma_f32_16x16x32_bf16 v[64:67], v[52:55], v[178:181], v[64:67]
	v_mfma_f32_16x16x32_bf16 v[56:59], v[44:47], v[178:181], v[56:59]
	v_mfma_f32_16x16x32_bf16 v[36:39], v[52:55], v[182:185], v[36:39]
	ds_read_b128 v[52:55], v165 offset:17920
	v_mfma_f32_16x16x32_bf16 v[32:35], v[44:47], v[182:185], v[32:35]
	ds_read_b128 v[44:47], v165 offset:19200
	s_waitcnt lgkmcnt(1)
	v_mfma_f32_16x16x32_bf16 v[28:31], v[52:55], v[182:185], v[28:31]
	s_waitcnt lgkmcnt(0)
	v_mfma_f32_16x16x32_bf16 v[24:27], v[44:47], v[182:185], v[24:27]
	v_mfma_f32_16x16x32_bf16 v[206:209], v[52:55], v[170:173], v[112:115]
	v_mfma_f32_16x16x32_bf16 v[170:173], v[44:47], v[170:173], v[104:107]
	v_mfma_f32_16x16x32_bf16 v[212:215], v[52:55], v[174:177], v[80:83]
	v_mfma_f32_16x16x32_bf16 v[174:177], v[44:47], v[174:177], v[72:75]
	v_mfma_f32_16x16x32_bf16 v[216:219], v[52:55], v[178:181], v[48:51]
	v_mfma_f32_16x16x32_bf16 v[178:181], v[44:47], v[178:181], v[40:43]
	s_setprio 0
	s_barrier
	s_setprio 1
	ds_read_b128 v[40:43], v165 offset:40960
	ds_read_b128 v[44:47], v165 offset:42240
	ds_read_b128 v[182:185], v155 offset:30720
	ds_read_b128 v[220:223], v155 offset:32000
	ds_read_b128 v[224:227], v155 offset:33280
	ds_read_b128 v[228:231], v155 offset:34560
	s_waitcnt lgkmcnt(3)
	v_mfma_f32_16x16x32_bf16 v[148:151], v[40:43], v[182:185], v[148:151]
	s_waitcnt lgkmcnt(2)
	v_mfma_f32_16x16x32_bf16 v[116:119], v[40:43], v[220:223], v[132:135]
	s_waitcnt lgkmcnt(1)
	v_mfma_f32_16x16x32_bf16 v[84:87], v[40:43], v[224:227], v[100:103]
	s_waitcnt lgkmcnt(0)
	v_mfma_f32_16x16x32_bf16 v[52:55], v[40:43], v[228:231], v[68:71]
	ds_read_b128 v[40:43], v165 offset:43520
	v_mfma_f32_16x16x32_bf16 v[48:51], v[44:47], v[228:231], v[60:63]
	s_nop 2
	ds_read_b128 v[60:63], v165 offset:44800
	v_mfma_f32_16x16x32_bf16 v[140:143], v[44:47], v[182:185], v[144:147]
	v_mfma_f32_16x16x32_bf16 v[108:111], v[44:47], v[220:223], v[128:131]
	v_mfma_f32_16x16x32_bf16 v[80:83], v[44:47], v[224:227], v[92:95]
	s_waitcnt lgkmcnt(1)
	v_mfma_f32_16x16x32_bf16 v[144:147], v[40:43], v[182:185], v[186:189]
	s_nop 0
	ds_read_b128 v[92:95], v165 offset:46080
	s_waitcnt lgkmcnt(1)
	v_mfma_f32_16x16x32_bf16 v[136:139], v[60:63], v[182:185], v[136:139]
	v_mfma_f32_16x16x32_bf16 v[112:115], v[40:43], v[220:223], v[190:193]
	v_mfma_f32_16x16x32_bf16 v[104:107], v[60:63], v[220:223], v[194:197]
	v_mfma_f32_16x16x32_bf16 v[76:79], v[40:43], v[224:227], v[198:201]
	v_mfma_f32_16x16x32_bf16 v[72:75], v[60:63], v[224:227], v[202:205]
	v_mfma_f32_16x16x32_bf16 v[44:47], v[40:43], v[228:231], v[160:163]
	v_mfma_f32_16x16x32_bf16 v[40:43], v[60:63], v[228:231], v[166:169]
	ds_read_b128 v[60:63], v165 offset:47360
	s_nop 0
	ds_read_b128 v[160:163], v165 offset:48640
	ds_read_b128 v[166:169], v165 offset:49920
	s_waitcnt lgkmcnt(3)
	v_mfma_f32_16x16x32_bf16 v[132:135], v[92:95], v[182:185], v[124:127]
	s_waitcnt lgkmcnt(2)
	v_mfma_f32_16x16x32_bf16 v[128:131], v[60:63], v[182:185], v[120:123]
	v_mfma_f32_16x16x32_bf16 v[100:103], v[92:95], v[220:223], v[96:99]
	v_mfma_f32_16x16x32_bf16 v[96:99], v[60:63], v[220:223], v[88:91]
	v_mfma_f32_16x16x32_bf16 v[68:71], v[92:95], v[224:227], v[64:67]
	v_mfma_f32_16x16x32_bf16 v[64:67], v[60:63], v[224:227], v[56:59]
	v_mfma_f32_16x16x32_bf16 v[36:39], v[92:95], v[228:231], v[36:39]
	v_mfma_f32_16x16x32_bf16 v[32:35], v[60:63], v[228:231], v[32:35]
	s_waitcnt lgkmcnt(1)
	v_mfma_f32_16x16x32_bf16 v[124:127], v[160:163], v[182:185], v[206:209]
	s_waitcnt lgkmcnt(0)
	v_mfma_f32_16x16x32_bf16 v[120:123], v[166:169], v[182:185], v[170:173]
	v_mfma_f32_16x16x32_bf16 v[92:95], v[160:163], v[220:223], v[212:215]
	v_mfma_f32_16x16x32_bf16 v[88:91], v[166:169], v[220:223], v[174:177]
	v_mfma_f32_16x16x32_bf16 v[60:63], v[160:163], v[224:227], v[216:219]
	v_mfma_f32_16x16x32_bf16 v[56:59], v[166:169], v[224:227], v[178:181]
	v_mfma_f32_16x16x32_bf16 v[28:31], v[160:163], v[228:231], v[28:31]
	v_mfma_f32_16x16x32_bf16 v[24:27], v[166:169], v[228:231], v[24:27]
	s_and_b64 vcc, exec, s[46:47]
	s_barrier
	s_cbranch_vccz .LBB0_706
	s_mul_i32 s46, s67, 0xb0000
	s_mul_hi_i32 s3, s67, 0xb0000
	s_add_u32 s46, s2, s46
	s_addc_u32 s47, s33, s3
	s_lshl_b32 s50, s66, 8
	s_ashr_i32 s51, s50, 31
	v_lshl_add_u64 v[0:1], v[158:159], 1, s[46:47]
	s_lshl_b64 s[46:47], s[50:51], 6
	v_lshl_add_u64 v[4:5], v[0:1], 0, v[152:153]
	s_add_u32 s46, s54, s46
	s_addc_u32 s47, s55, s47
	global_load_dwordx4 v[0:3], v[4:5], off sc1
	v_lshl_add_u64 v[4:5], v[4:5], 0, s[10:11]
	global_load_dwordx4 v[4:7], v[4:5], off sc1
	v_lshl_add_u64 v[20:21], v[156:157], 1, s[46:47]
	global_load_dwordx4 v[8:11], v[20:21], off sc1
	v_lshl_add_u64 v[12:13], v[20:21], 0, s[12:13]
	global_load_dwordx4 v[12:15], v[12:13], off sc1
	v_lshl_add_u64 v[16:17], v[20:21], 0, s[14:15]
	global_load_dwordx4 v[16:19], v[16:17], off sc1
	v_lshl_add_u64 v[20:21], v[20:21], 0, s[16:17]
	global_load_dwordx4 v[20:23], v[20:21], off sc1
	s_branch .LBB0_706
